# GEMM K-loops: loop-carried counter/pointer adds and exit compare moved above the loop-back barrier (strategy 7.11 back-edge rotation, light form)
# baseline (speedup 1.0000x reference)
; #define STAGE(bufoff, gbase) STAGE_(bufoff, gbase, voffA)
; #define STAGEB(bufoff, gbase) STAGE_(bufoff, gbase, voffB)
; #define LDA(dst, b, h) do { _Pragma("unroll") for (int m = 0; m < 4; ++m) _Pragma("unroll") for (int k = 0; k < 2; ++k) dst[m][k] = *LDSP(const bf16x8, lds + SA(b, h) + aoff + m * 2048 + k * 1024); } while (0)
; #define LDB(dst, b, h) do { _Pragma("unroll") for (int n = 0; n < 2; ++n) _Pragma("unroll") for (int k = 0; k < 2; ++k) dst[n][k] = *LDSP(const bf16x8, lds + SB(b, h) + boff + n * 2048 + k * 1024); } while (0)
; #define MMA(ai, bj, AT, BT) do { __builtin_amdgcn_s_setprio(1); \
;     _Pragma("unroll") for (int m = 0; m < 4; ++m) _Pragma("unroll") for (int n = 0; n < 2; ++n) _Pragma("unroll") for (int k = 0; k < 2; ++k) \
;       acc[ai][bj][m][n] = __builtin_amdgcn_mfma_f32_16x16x32_bf16(BT[n][k], AT[m][k], acc[ai][bj][m][n], 0, 0, 0); \
;     __builtin_amdgcn_s_setprio(0); } while (0)
; #define WAIT_V(n) asm volatile("s_waitcnt vmcnt(" #n ")" ::: "memory")
; #define WAIT_L(n) asm volatile("s_waitcnt lgkmcnt(" #n ")" ::: "memory")
; #define BAR __builtin_amdgcn_s_barrier()
; #define SCHED __builtin_amdgcn_sched_barrier(0)
; #define WAIT_V(n) asm volatile("s_waitcnt vmcnt(" #n ")" ::: "memory")
; #define BAR do { __builtin_amdgcn_sched_barrier(0); __builtin_amdgcn_s_barrier(); asm volatile("" ::: "memory"); __builtin_amdgcn_sched_barrier(0); } while (0)
; template <bool SP2, bool ALIGN_EPI, bool DUAL, class Epi> DI void gemm_phase2(const bf16_t* A, const bf16_t* Bt, const bf16_t* A2, const bf16_t* Bt2, int M, int N, int K, const Epi& E, lds_t* lds) {
;     ...
;     for (int t = 0; t < nt; t += 2) {
;       const bool last = (t == nt - 2);
;       const char* a1 = cA + (size_t)(t + 1) * kstep;
;       const char* a2 = last ? nA : cA + (size_t)(t + 2) * kstep; const char* b2 = last ? nB : cB + (size_t)(t + 2) * kstep;
;       const char* a3 = a2 + kstep; const char* b3 = b2 + kstep;
;       if constexpr (SP2) {
;         LDB(B0, 0, 0); LDB(B1, 0, 1); SCHED; LDA(At, 0, 0); STAGE(SA(1, 1), a1 + hstep);
;         WAIT_V(8); WAIT_L(0); BAR; MMA(0, 0, At, B0); MMA(0, 1, At, B1); BAR; SCHED;
;         LDA(At, 0, 1); STAGEB(SB(0, 0), b2); STAGEB(SB(0, 1), b2 + bstep); STAGE(SA(0, 0), a2);
.LBB0_157:
	ds_read_b128 v[144:147], v161
	ds_read_b128 v[148:151], v161 offset:1024
	ds_read_b128 v[166:169], v161 offset:2048
	ds_read_b128 v[170:173], v161 offset:3072
	ds_read_b128 v[174:177], v162
	ds_read_b128 v[178:181], v162 offset:1024
	ds_read_b128 v[182:185], v162 offset:2048
	ds_read_b128 v[186:189], v162 offset:3072
	s_add_u32 s22, s8, 0xfffc0080
	s_addc_u32 s23, s9, -1
	s_cmp_eq_u32 s21, 12
	s_cselect_b32 s91, s0, s23
	s_cselect_b32 s90, s1, s22
	s_cselect_b32 s89, s11, s20
	s_cselect_b32 s88, s18, s19
	v_lshl_add_u64 v[152:153], s[8:9], 0, v[140:141]
	s_add_i32 m0, s3, 0xc000
	ds_read_b128 v[190:193], v163
	ds_read_b128 v[194:197], v163 offset:1024
	ds_read_b128 v[198:201], v163 offset:2048
	ds_read_b128 v[202:205], v163 offset:3072
	ds_read_b128 v[206:209], v163 offset:4096
	ds_read_b128 v[214:217], v163 offset:5120
	ds_read_b128 v[218:221], v163 offset:6144
	ds_read_b128 v[222:225], v163 offset:7168
	global_load_lds_dwordx4 v[152:153], off
	v_lshl_add_u64 v[152:153], s[8:9], 0, v[142:143]
	s_add_i32 m0, s3, 0xe000
	s_nop 0
	global_load_lds_dwordx4 v[152:153], off
	s_waitcnt vmcnt(8)
	s_waitcnt lgkmcnt(0)
	s_barrier
	s_setprio 1
	s_waitcnt lgkmcnt(0)
	v_mfma_f32_16x16x32_bf16 v[124:127], v[144:147], v[190:193], v[124:127]
	v_mfma_f32_16x16x32_bf16 v[120:123], v[166:169], v[190:193], v[120:123]
	v_mfma_f32_16x16x32_bf16 v[108:111], v[144:147], v[198:201], v[108:111]
	v_mfma_f32_16x16x32_bf16 v[104:107], v[166:169], v[198:201], v[104:107]
	v_mfma_f32_16x16x32_bf16 v[92:95], v[144:147], v[206:209], v[92:95]
	v_mfma_f32_16x16x32_bf16 v[88:91], v[166:169], v[206:209], v[88:91]
	v_mfma_f32_16x16x32_bf16 v[76:79], v[144:147], v[218:221], v[76:79]
	v_mfma_f32_16x16x32_bf16 v[72:75], v[166:169], v[218:221], v[72:75]
	v_mfma_f32_16x16x32_bf16 v[124:127], v[148:151], v[194:197], v[124:127]
	v_mfma_f32_16x16x32_bf16 v[120:123], v[170:173], v[194:197], v[120:123]
	v_mfma_f32_16x16x32_bf16 v[108:111], v[148:151], v[202:205], v[108:111]
	v_mfma_f32_16x16x32_bf16 v[104:107], v[170:173], v[202:205], v[104:107]
	v_mfma_f32_16x16x32_bf16 v[92:95], v[148:151], v[214:217], v[92:95]
	v_mfma_f32_16x16x32_bf16 v[88:91], v[170:173], v[214:217], v[88:91]
	v_mfma_f32_16x16x32_bf16 v[76:79], v[148:151], v[222:225], v[76:79]
	v_mfma_f32_16x16x32_bf16 v[72:75], v[170:173], v[222:225], v[72:75]
	s_setprio 0
	s_setprio 1
	v_mfma_f32_16x16x32_bf16 v[116:119], v[174:177], v[190:193], v[116:119]
	v_mfma_f32_16x16x32_bf16 v[112:115], v[182:185], v[190:193], v[112:115]
	v_mfma_f32_16x16x32_bf16 v[100:103], v[174:177], v[198:201], v[100:103]
	v_mfma_f32_16x16x32_bf16 v[96:99], v[182:185], v[198:201], v[96:99]
	v_mfma_f32_16x16x32_bf16 v[84:87], v[174:177], v[206:209], v[84:87]
	v_mfma_f32_16x16x32_bf16 v[80:83], v[182:185], v[206:209], v[80:83]
	v_mfma_f32_16x16x32_bf16 v[68:71], v[174:177], v[218:221], v[68:71]
	v_mfma_f32_16x16x32_bf16 v[64:67], v[182:185], v[218:221], v[64:67]
	v_mfma_f32_16x16x32_bf16 v[116:119], v[178:181], v[194:197], v[116:119]
	v_mfma_f32_16x16x32_bf16 v[112:115], v[186:189], v[194:197], v[112:115]
	v_mfma_f32_16x16x32_bf16 v[100:103], v[178:181], v[202:205], v[100:103]
	v_mfma_f32_16x16x32_bf16 v[96:99], v[186:189], v[202:205], v[96:99]
	v_mfma_f32_16x16x32_bf16 v[84:87], v[178:181], v[214:217], v[84:87]
	v_mfma_f32_16x16x32_bf16 v[80:83], v[186:189], v[214:217], v[80:83]
	v_mfma_f32_16x16x32_bf16 v[68:71], v[178:181], v[222:225], v[68:71]
	v_mfma_f32_16x16x32_bf16 v[64:67], v[186:189], v[222:225], v[64:67]
	s_setprio 0
	s_barrier
	s_add_i32 s22, s12, s2
	v_lshl_add_u64 v[152:153], s[88:89], 0, v[130:131]
	s_mov_b32 m0, s22
	ds_read_b128 v[190:193], v163 offset:16384
	ds_read_b128 v[194:197], v163 offset:17408
	ds_read_b128 v[198:201], v163 offset:18432
	ds_read_b128 v[202:205], v163 offset:19456
	ds_read_b128 v[206:209], v163 offset:20480
	ds_read_b128 v[214:217], v163 offset:21504
	ds_read_b128 v[218:221], v163 offset:22528
	ds_read_b128 v[222:225], v163 offset:23552
	global_load_lds_dwordx4 v[152:153], off
	s_add_i32 m0, s22, 0x2000
	s_add_u32 s22, s88, 0x10000
	v_lshl_add_u64 v[210:211], s[88:89], 0, v[134:135]
	s_addc_u32 s23, s89, 0
	s_add_i32 s33, s13, s2
	global_load_lds_dwordx4 v[210:211], off
	v_lshl_add_u64 v[226:227], s[22:23], 0, v[130:131]
	s_mov_b32 m0, s33
	v_lshl_add_u64 v[228:229], s[90:91], 0, v[132:133]
	global_load_lds_dwordx4 v[226:227], off
	v_lshl_add_u64 v[226:227], s[22:23], 0, v[134:135]
	s_add_i32 m0, s33, 0x2000
	s_nop 0
	global_load_lds_dwordx4 v[226:227], off
	v_lshl_add_u64 v[226:227], s[90:91], 0, v[128:129]
	s_mov_b32 m0, s3
	s_nop 0
	global_load_lds_dwordx4 v[226:227], off
	s_mov_b32 m0, s14
	s_nop 0
	global_load_lds_dwordx4 v[228:229], off
	s_waitcnt vmcnt(8)
	s_waitcnt lgkmcnt(0)
	s_barrier
; #define STAGE(bufoff, gbase) STAGE_(bufoff, gbase, voffA)
; #define LDA(dst, b, h) do { _Pragma("unroll") for (int m = 0; m < 4; ++m) _Pragma("unroll") for (int k = 0; k < 2; ++k) dst[m][k] = *LDSP(const bf16x8, lds + SA(b, h) + aoff + m * 2048 + k * 1024); } while (0)
; #define LDB(dst, b, h) do { _Pragma("unroll") for (int n = 0; n < 2; ++n) _Pragma("unroll") for (int k = 0; k < 2; ++k) dst[n][k] = *LDSP(const bf16x8, lds + SB(b, h) + boff + n * 2048 + k * 1024); } while (0)
; #define MMA(ai, bj, AT, BT) do { __builtin_amdgcn_s_setprio(1); \
;     _Pragma("unroll") for (int m = 0; m < 4; ++m) _Pragma("unroll") for (int n = 0; n < 2; ++n) _Pragma("unroll") for (int k = 0; k < 2; ++k) \
;       acc[ai][bj][m][n] = __builtin_amdgcn_mfma_f32_16x16x32_bf16(BT[n][k], AT[m][k], acc[ai][bj][m][n], 0, 0, 0); \
;     __builtin_amdgcn_s_setprio(0); } while (0)
; #define WAIT_V(n) asm volatile("s_waitcnt vmcnt(" #n ")" ::: "memory")
; #define WAIT_L(n) asm volatile("s_waitcnt lgkmcnt(" #n ")" ::: "memory")
; #define BAR __builtin_amdgcn_s_barrier()
; #define SCHED __builtin_amdgcn_sched_barrier(0)
; #define WAIT_V(n) asm volatile("s_waitcnt vmcnt(" #n ")" ::: "memory")
; #define BAR do { __builtin_amdgcn_sched_barrier(0); __builtin_amdgcn_s_barrier(); asm volatile("" ::: "memory"); __builtin_amdgcn_sched_barrier(0); } while (0)
; template <bool SP2, bool ALIGN_EPI, bool DUAL, class Epi> DI void gemm_phase2(const bf16_t* A, const bf16_t* Bt, const bf16_t* A2, const bf16_t* Bt2, int M, int N, int K, const Epi& E, lds_t* lds) {
;     ...
;         WAIT_V(8); WAIT_L(0); BAR; MMA(1, 0, At, B0); MMA(1, 1, At, B1); BAR; SCHED;
;         LDB(B0, 1, 0); LDB(B1, 1, 1); SCHED; LDA(At, 1, 0); STAGE(SA(0, 1), a2 + hstep);
;         WAIT_V(8); WAIT_L(0); BAR; MMA(0, 0, At, B0); MMA(0, 1, At, B1); BAR; SCHED;
	s_setprio 1
	s_waitcnt lgkmcnt(0)
	v_mfma_f32_16x16x32_bf16 v[60:63], v[144:147], v[190:193], v[60:63]
	v_mfma_f32_16x16x32_bf16 v[56:59], v[166:169], v[190:193], v[56:59]
	v_mfma_f32_16x16x32_bf16 v[44:47], v[144:147], v[198:201], v[44:47]
	v_mfma_f32_16x16x32_bf16 v[40:43], v[166:169], v[198:201], v[40:43]
	v_mfma_f32_16x16x32_bf16 v[28:31], v[144:147], v[206:209], v[28:31]
	v_mfma_f32_16x16x32_bf16 v[24:27], v[166:169], v[206:209], v[24:27]
	v_mfma_f32_16x16x32_bf16 v[12:15], v[144:147], v[218:221], v[12:15]
	v_mfma_f32_16x16x32_bf16 v[8:11], v[166:169], v[218:221], v[8:11]
	v_mfma_f32_16x16x32_bf16 v[60:63], v[148:151], v[194:197], v[60:63]
	v_mfma_f32_16x16x32_bf16 v[56:59], v[170:173], v[194:197], v[56:59]
	v_mfma_f32_16x16x32_bf16 v[44:47], v[148:151], v[202:205], v[44:47]
	v_mfma_f32_16x16x32_bf16 v[40:43], v[170:173], v[202:205], v[40:43]
	v_mfma_f32_16x16x32_bf16 v[28:31], v[148:151], v[214:217], v[28:31]
	v_mfma_f32_16x16x32_bf16 v[24:27], v[170:173], v[214:217], v[24:27]
	v_mfma_f32_16x16x32_bf16 v[12:15], v[148:151], v[222:225], v[12:15]
	v_mfma_f32_16x16x32_bf16 v[8:11], v[170:173], v[222:225], v[8:11]
	s_setprio 0
	s_setprio 1
	v_mfma_f32_16x16x32_bf16 v[52:55], v[174:177], v[190:193], v[52:55]
	v_mfma_f32_16x16x32_bf16 v[48:51], v[182:185], v[190:193], v[48:51]
	v_mfma_f32_16x16x32_bf16 v[36:39], v[174:177], v[198:201], v[36:39]
	v_mfma_f32_16x16x32_bf16 v[32:35], v[182:185], v[198:201], v[32:35]
	v_mfma_f32_16x16x32_bf16 v[20:23], v[174:177], v[206:209], v[20:23]
	v_mfma_f32_16x16x32_bf16 v[16:19], v[182:185], v[206:209], v[16:19]
	v_mfma_f32_16x16x32_bf16 v[4:7], v[174:177], v[218:221], v[4:7]
	v_mfma_f32_16x16x32_bf16 v[0:3], v[182:185], v[218:221], v[0:3]
	v_mfma_f32_16x16x32_bf16 v[52:55], v[178:181], v[194:197], v[52:55]
	v_mfma_f32_16x16x32_bf16 v[48:51], v[186:189], v[194:197], v[48:51]
	v_mfma_f32_16x16x32_bf16 v[36:39], v[178:181], v[202:205], v[36:39]
	v_mfma_f32_16x16x32_bf16 v[32:35], v[186:189], v[202:205], v[32:35]
	v_mfma_f32_16x16x32_bf16 v[20:23], v[178:181], v[214:217], v[20:23]
	v_mfma_f32_16x16x32_bf16 v[16:19], v[186:189], v[214:217], v[16:19]
	v_mfma_f32_16x16x32_bf16 v[4:7], v[178:181], v[222:225], v[4:7]
	v_mfma_f32_16x16x32_bf16 v[0:3], v[186:189], v[222:225], v[0:3]
	s_setprio 0
	s_barrier
	s_add_i32 s33, 0, 0x18000
	s_add_i32 s34, 0, 0x1c000
	v_add_u32_e32 v170, s33, v157
	v_add_u32_e32 v186, s34, v157
	ds_read_b128 v[144:147], v170
	ds_read_b128 v[148:151], v170 offset:1024
	ds_read_b128 v[166:169], v170 offset:2048
	ds_read_b128 v[170:173], v170 offset:3072
	ds_read_b128 v[174:177], v186
	ds_read_b128 v[178:181], v186 offset:1024
	ds_read_b128 v[182:185], v186 offset:2048
	ds_read_b128 v[186:189], v186 offset:3072
	s_add_u32 s22, s90, 0x40000
	s_addc_u32 s23, s91, 0
	s_mov_b32 m0, s15
	v_lshl_add_u64 v[230:231], s[22:23], 0, v[128:129]
	ds_read_b128 v[190:193], v163 offset:32768
	ds_read_b128 v[194:197], v163 offset:33792
	ds_read_b128 v[198:201], v163 offset:34816
	ds_read_b128 v[202:205], v163 offset:35840
	ds_read_b128 v[206:209], v163 offset:36864
	ds_read_b128 v[214:217], v163 offset:37888
	ds_read_b128 v[218:221], v163 offset:38912
	ds_read_b128 v[222:225], v163 offset:39936
	global_load_lds_dwordx4 v[230:231], off
	v_lshl_add_u64 v[230:231], s[22:23], 0, v[132:133]
	s_mov_b32 m0, s35
	s_nop 0
	global_load_lds_dwordx4 v[230:231], off
	s_waitcnt vmcnt(8)
	s_waitcnt lgkmcnt(0)
	s_barrier
	s_setprio 1
	s_waitcnt lgkmcnt(0)
	v_mfma_f32_16x16x32_bf16 v[124:127], v[144:147], v[190:193], v[124:127]
	v_mfma_f32_16x16x32_bf16 v[120:123], v[166:169], v[190:193], v[120:123]
	v_mfma_f32_16x16x32_bf16 v[108:111], v[144:147], v[198:201], v[108:111]
	v_mfma_f32_16x16x32_bf16 v[104:107], v[166:169], v[198:201], v[104:107]
	v_mfma_f32_16x16x32_bf16 v[92:95], v[144:147], v[206:209], v[92:95]
	v_mfma_f32_16x16x32_bf16 v[88:91], v[166:169], v[206:209], v[88:91]
	v_mfma_f32_16x16x32_bf16 v[76:79], v[144:147], v[218:221], v[76:79]
	v_mfma_f32_16x16x32_bf16 v[72:75], v[166:169], v[218:221], v[72:75]
	v_mfma_f32_16x16x32_bf16 v[124:127], v[148:151], v[194:197], v[124:127]
	v_mfma_f32_16x16x32_bf16 v[120:123], v[170:173], v[194:197], v[120:123]
	v_mfma_f32_16x16x32_bf16 v[108:111], v[148:151], v[202:205], v[108:111]
	v_mfma_f32_16x16x32_bf16 v[104:107], v[170:173], v[202:205], v[104:107]
	v_mfma_f32_16x16x32_bf16 v[92:95], v[148:151], v[214:217], v[92:95]
	v_mfma_f32_16x16x32_bf16 v[88:91], v[170:173], v[214:217], v[88:91]
	v_mfma_f32_16x16x32_bf16 v[76:79], v[148:151], v[222:225], v[76:79]
	v_mfma_f32_16x16x32_bf16 v[72:75], v[170:173], v[222:225], v[72:75]
	s_setprio 0
	s_setprio 1
	v_mfma_f32_16x16x32_bf16 v[116:119], v[174:177], v[190:193], v[116:119]
	v_mfma_f32_16x16x32_bf16 v[112:115], v[182:185], v[190:193], v[112:115]
	v_mfma_f32_16x16x32_bf16 v[100:103], v[174:177], v[198:201], v[100:103]
	v_mfma_f32_16x16x32_bf16 v[96:99], v[182:185], v[198:201], v[96:99]
	v_mfma_f32_16x16x32_bf16 v[84:87], v[174:177], v[206:209], v[84:87]
	v_mfma_f32_16x16x32_bf16 v[80:83], v[182:185], v[206:209], v[80:83]
	v_mfma_f32_16x16x32_bf16 v[68:71], v[174:177], v[218:221], v[68:71]
	v_mfma_f32_16x16x32_bf16 v[64:67], v[182:185], v[218:221], v[64:67]
	v_mfma_f32_16x16x32_bf16 v[116:119], v[178:181], v[194:197], v[116:119]
	v_mfma_f32_16x16x32_bf16 v[112:115], v[186:189], v[194:197], v[112:115]
	v_mfma_f32_16x16x32_bf16 v[100:103], v[178:181], v[202:205], v[100:103]
	v_mfma_f32_16x16x32_bf16 v[96:99], v[186:189], v[202:205], v[96:99]
	v_mfma_f32_16x16x32_bf16 v[84:87], v[178:181], v[214:217], v[84:87]
	v_mfma_f32_16x16x32_bf16 v[80:83], v[186:189], v[214:217], v[80:83]
	v_mfma_f32_16x16x32_bf16 v[68:71], v[178:181], v[222:225], v[68:71]
	v_mfma_f32_16x16x32_bf16 v[64:67], v[186:189], v[222:225], v[64:67]
	s_setprio 0
	s_barrier
; #define STAGE(bufoff, gbase) STAGE_(bufoff, gbase, voffA)
; #define STAGEB(bufoff, gbase) STAGE_(bufoff, gbase, voffB)
; #define LDA(dst, b, h) do { _Pragma("unroll") for (int m = 0; m < 4; ++m) _Pragma("unroll") for (int k = 0; k < 2; ++k) dst[m][k] = *LDSP(const bf16x8, lds + SA(b, h) + aoff + m * 2048 + k * 1024); } while (0)
; #define MMA(ai, bj, AT, BT) do { __builtin_amdgcn_s_setprio(1); \
;     _Pragma("unroll") for (int m = 0; m < 4; ++m) _Pragma("unroll") for (int n = 0; n < 2; ++n) _Pragma("unroll") for (int k = 0; k < 2; ++k) \
;       acc[ai][bj][m][n] = __builtin_amdgcn_mfma_f32_16x16x32_bf16(BT[n][k], AT[m][k], acc[ai][bj][m][n], 0, 0, 0); \
;     __builtin_amdgcn_s_setprio(0); } while (0)
; #define WAIT_V(n) asm volatile("s_waitcnt vmcnt(" #n ")" ::: "memory")
; #define WAIT_L(n) asm volatile("s_waitcnt lgkmcnt(" #n ")" ::: "memory")
; #define BAR __builtin_amdgcn_s_barrier()
; #define SCHED __builtin_amdgcn_sched_barrier(0)
; #define WAIT_V(n) asm volatile("s_waitcnt vmcnt(" #n ")" ::: "memory")
; #define BAR do { __builtin_amdgcn_sched_barrier(0); __builtin_amdgcn_s_barrier(); asm volatile("" ::: "memory"); __builtin_amdgcn_sched_barrier(0); } while (0)
; template <bool SP2, bool ALIGN_EPI, bool DUAL, class Epi> DI void gemm_phase2(const bf16_t* A, const bf16_t* Bt, const bf16_t* A2, const bf16_t* Bt2, int M, int N, int K, const Epi& E, lds_t* lds) {
;     ...
;         LDA(At, 1, 1); STAGEB(SB(1, 0), b3); STAGEB(SB(1, 1), b3 + bstep); STAGE(SA(1, 0), a3);
;         WAIT_V(8); WAIT_L(0); BAR; MMA(1, 0, At, B0); MMA(1, 1, At, B1); BAR; SCHED;
;     ...
;     if constexpr (ALIGN_EPI) { if (wr == 0) BAR; }
	s_add_i32 s22, s33, s2
	v_lshl_add_u64 v[152:153], v[152:153], 0, s[58:59]
	s_mov_b32 m0, s22
	ds_read_b128 v[190:193], v163 offset:49152
	ds_read_b128 v[194:197], v163 offset:50176
	ds_read_b128 v[198:201], v163 offset:51200
	ds_read_b128 v[202:205], v163 offset:52224
	ds_read_b128 v[206:209], v163 offset:53248
	ds_read_b128 v[214:217], v163 offset:54272
	ds_read_b128 v[218:221], v163 offset:55296
	ds_read_b128 v[222:225], v163 offset:56320
	global_load_lds_dwordx4 v[152:153], off
	s_add_i32 m0, s22, 0x2000
	s_add_u32 s22, s88, 0x10080
	v_lshl_add_u64 v[152:153], v[210:211], 0, s[58:59]
	s_addc_u32 s23, s89, 0
	s_add_i32 s33, s34, s2
	global_load_lds_dwordx4 v[152:153], off
	v_lshl_add_u64 v[152:153], s[22:23], 0, v[130:131]
	s_mov_b32 m0, s33
	s_nop 0
	global_load_lds_dwordx4 v[152:153], off
	v_lshl_add_u64 v[152:153], s[22:23], 0, v[134:135]
	s_add_i32 m0, s33, 0x2000
	s_nop 0
	global_load_lds_dwordx4 v[152:153], off
	v_lshl_add_u64 v[152:153], v[226:227], 0, s[58:59]
	s_mov_b32 m0, s52
	s_nop 0
	global_load_lds_dwordx4 v[152:153], off
	v_lshl_add_u64 v[152:153], v[228:229], 0, s[58:59]
	s_mov_b32 m0, s53
	s_nop 0
	global_load_lds_dwordx4 v[152:153], off
	s_waitcnt vmcnt(8)
	s_waitcnt lgkmcnt(0)
	s_barrier
	s_setprio 1
	s_waitcnt lgkmcnt(0)
	v_mfma_f32_16x16x32_bf16 v[60:63], v[144:147], v[190:193], v[60:63]
	v_mfma_f32_16x16x32_bf16 v[56:59], v[166:169], v[190:193], v[56:59]
	v_mfma_f32_16x16x32_bf16 v[44:47], v[144:147], v[198:201], v[44:47]
	v_mfma_f32_16x16x32_bf16 v[40:43], v[166:169], v[198:201], v[40:43]
	v_mfma_f32_16x16x32_bf16 v[28:31], v[144:147], v[206:209], v[28:31]
	v_mfma_f32_16x16x32_bf16 v[24:27], v[166:169], v[206:209], v[24:27]
	v_mfma_f32_16x16x32_bf16 v[12:15], v[144:147], v[218:221], v[12:15]
	v_mfma_f32_16x16x32_bf16 v[8:11], v[166:169], v[218:221], v[8:11]
	v_mfma_f32_16x16x32_bf16 v[60:63], v[148:151], v[194:197], v[60:63]
	v_mfma_f32_16x16x32_bf16 v[56:59], v[170:173], v[194:197], v[56:59]
	v_mfma_f32_16x16x32_bf16 v[44:47], v[148:151], v[202:205], v[44:47]
	v_mfma_f32_16x16x32_bf16 v[40:43], v[170:173], v[202:205], v[40:43]
	v_mfma_f32_16x16x32_bf16 v[28:31], v[148:151], v[214:217], v[28:31]
	v_mfma_f32_16x16x32_bf16 v[24:27], v[170:173], v[214:217], v[24:27]
	v_mfma_f32_16x16x32_bf16 v[12:15], v[148:151], v[222:225], v[12:15]
	v_mfma_f32_16x16x32_bf16 v[8:11], v[170:173], v[222:225], v[8:11]
	s_setprio 0
	s_setprio 1
	v_mfma_f32_16x16x32_bf16 v[52:55], v[174:177], v[190:193], v[52:55]
	v_mfma_f32_16x16x32_bf16 v[48:51], v[182:185], v[190:193], v[48:51]
	v_mfma_f32_16x16x32_bf16 v[36:39], v[174:177], v[198:201], v[36:39]
	v_mfma_f32_16x16x32_bf16 v[32:35], v[182:185], v[198:201], v[32:35]
	v_mfma_f32_16x16x32_bf16 v[20:23], v[174:177], v[206:209], v[20:23]
	v_mfma_f32_16x16x32_bf16 v[16:19], v[182:185], v[206:209], v[16:19]
	v_mfma_f32_16x16x32_bf16 v[4:7], v[174:177], v[218:221], v[4:7]
	v_mfma_f32_16x16x32_bf16 v[0:3], v[182:185], v[218:221], v[0:3]
	v_mfma_f32_16x16x32_bf16 v[52:55], v[178:181], v[194:197], v[52:55]
	v_mfma_f32_16x16x32_bf16 v[48:51], v[186:189], v[194:197], v[48:51]
	v_mfma_f32_16x16x32_bf16 v[36:39], v[178:181], v[202:205], v[36:39]
	v_mfma_f32_16x16x32_bf16 v[32:35], v[186:189], v[202:205], v[32:35]
	v_mfma_f32_16x16x32_bf16 v[20:23], v[178:181], v[214:217], v[20:23]
	v_mfma_f32_16x16x32_bf16 v[16:19], v[186:189], v[214:217], v[16:19]
	v_mfma_f32_16x16x32_bf16 v[4:7], v[178:181], v[222:225], v[4:7]
	v_mfma_f32_16x16x32_bf16 v[0:3], v[186:189], v[222:225], v[0:3]
	s_setprio 0
	s_add_i32 s21, s21, 2
	s_add_u32 s8, s8, 0x100
	s_addc_u32 s9, s9, 0
	s_add_u32 s19, s19, 0x100
	s_addc_u32 s20, s20, 0
	s_cmp_gt_u32 s21, 13
	s_barrier
	s_cbranch_scc0 .LBB0_157
	s_and_b64 vcc, exec, s[60:61]
	s_cbranch_vccz .LBB0_160
	s_barrier

; #define STAGE(bufoff, gbase) STAGE_(bufoff, gbase, voffA)
; #define STAGEB(bufoff, gbase) STAGE_(bufoff, gbase, voffB)
; #define LDA(dst, b, h) do { _Pragma("unroll") for (int m = 0; m < 4; ++m) _Pragma("unroll") for (int k = 0; k < 2; ++k) dst[m][k] = *LDSP(const bf16x8, lds + SA(b, h) + aoff + m * 2048 + k * 1024); } while (0)
; #define LDB(dst, b, h) do { _Pragma("unroll") for (int n = 0; n < 2; ++n) _Pragma("unroll") for (int k = 0; k < 2; ++k) dst[n][k] = *LDSP(const bf16x8, lds + SB(b, h) + boff + n * 2048 + k * 1024); } while (0)
; #define MMA(ai, bj, AT, BT) do { __builtin_amdgcn_s_setprio(1); \
;     _Pragma("unroll") for (int m = 0; m < 4; ++m) _Pragma("unroll") for (int n = 0; n < 2; ++n) _Pragma("unroll") for (int k = 0; k < 2; ++k) \
;       acc[ai][bj][m][n] = __builtin_amdgcn_mfma_f32_16x16x32_bf16(BT[n][k], AT[m][k], acc[ai][bj][m][n], 0, 0, 0); \
;     __builtin_amdgcn_s_setprio(0); } while (0)
; #define WAIT_V(n) asm volatile("s_waitcnt vmcnt(" #n ")" ::: "memory")
; #define WAIT_L(n) asm volatile("s_waitcnt lgkmcnt(" #n ")" ::: "memory")
; #define BAR __builtin_amdgcn_s_barrier()
; #define SCHED __builtin_amdgcn_sched_barrier(0)
; #define WAIT_V(n) asm volatile("s_waitcnt vmcnt(" #n ")" ::: "memory")
; #define BAR do { __builtin_amdgcn_sched_barrier(0); __builtin_amdgcn_s_barrier(); asm volatile("" ::: "memory"); __builtin_amdgcn_sched_barrier(0); } while (0)
; template <bool SP2, bool ALIGN_EPI, bool DUAL, class Epi> DI void gemm_phase2(const bf16_t* A, const bf16_t* Bt, const bf16_t* A2, const bf16_t* Bt2, int M, int N, int K, const Epi& E, lds_t* lds) {
;     ...
;     for (int t = 0; t < nt; t += 2) {
;       const bool last = (t == nt - 2);
;       const char* a1 = cA + (size_t)(t + 1) * kstep;
;       const char* a2 = last ? nA : cA + (size_t)(t + 2) * kstep; const char* b2 = last ? nB : cB + (size_t)(t + 2) * kstep;
;       const char* a3 = a2 + kstep; const char* b3 = b2 + kstep;
;       if constexpr (SP2) {
;         LDB(B0, 0, 0); LDB(B1, 0, 1); SCHED; LDA(At, 0, 0); STAGE(SA(1, 1), a1 + hstep);
;         WAIT_V(8); WAIT_L(0); BAR; MMA(0, 0, At, B0); MMA(0, 1, At, B1); BAR; SCHED;
;         LDA(At, 0, 1); STAGEB(SB(0, 0), b2); STAGEB(SB(0, 1), b2 + bstep); STAGE(SA(0, 0), a2);
.LBB0_341:
	ds_read_b128 v[148:151], v145
	ds_read_b128 v[156:159], v145 offset:1024
	ds_read_b128 v[160:163], v145 offset:2048
	ds_read_b128 v[164:167], v145 offset:3072
	ds_read_b128 v[168:171], v146
	ds_read_b128 v[172:175], v146 offset:1024
	ds_read_b128 v[176:179], v146 offset:2048
	ds_read_b128 v[180:183], v146 offset:3072
	s_add_u32 s52, s68, 0xfffc0080
	s_addc_u32 s53, s69, -1
	s_cmp_eq_u32 s35, 12
	s_cselect_b32 s89, s0, s53
	s_cselect_b32 s88, s1, s52
	s_cselect_b32 s87, s11, s34
	s_cselect_b32 s86, s23, s33
	v_lshl_add_u64 v[152:153], s[68:69], 0, v[136:137]
	s_add_i32 m0, s3, 0xc000
	ds_read_b128 v[184:187], v147
	ds_read_b128 v[188:191], v147 offset:1024
	ds_read_b128 v[192:195], v147 offset:2048
	ds_read_b128 v[196:199], v147 offset:3072
	ds_read_b128 v[200:203], v147 offset:4096
	ds_read_b128 v[204:207], v147 offset:5120
	ds_read_b128 v[208:211], v147 offset:6144
	ds_read_b128 v[214:217], v147 offset:7168
	global_load_lds_dwordx4 v[152:153], off
	v_lshl_add_u64 v[152:153], s[68:69], 0, v[138:139]
	s_add_i32 m0, s3, 0xe000
	s_nop 0
	global_load_lds_dwordx4 v[152:153], off
	s_waitcnt vmcnt(8)
	s_waitcnt lgkmcnt(0)
	s_barrier
	s_setprio 1
	s_waitcnt lgkmcnt(0)
	v_mfma_f32_16x16x32_bf16 v[124:127], v[148:151], v[184:187], v[124:127]
	v_mfma_f32_16x16x32_bf16 v[120:123], v[160:163], v[184:187], v[120:123]
	v_mfma_f32_16x16x32_bf16 v[108:111], v[148:151], v[192:195], v[108:111]
	v_mfma_f32_16x16x32_bf16 v[104:107], v[160:163], v[192:195], v[104:107]
	v_mfma_f32_16x16x32_bf16 v[92:95], v[148:151], v[200:203], v[92:95]
	v_mfma_f32_16x16x32_bf16 v[88:91], v[160:163], v[200:203], v[88:91]
	v_mfma_f32_16x16x32_bf16 v[76:79], v[148:151], v[208:211], v[76:79]
	v_mfma_f32_16x16x32_bf16 v[72:75], v[160:163], v[208:211], v[72:75]
	v_mfma_f32_16x16x32_bf16 v[124:127], v[156:159], v[188:191], v[124:127]
	v_mfma_f32_16x16x32_bf16 v[120:123], v[164:167], v[188:191], v[120:123]
	v_mfma_f32_16x16x32_bf16 v[108:111], v[156:159], v[196:199], v[108:111]
	v_mfma_f32_16x16x32_bf16 v[104:107], v[164:167], v[196:199], v[104:107]
	v_mfma_f32_16x16x32_bf16 v[92:95], v[156:159], v[204:207], v[92:95]
	v_mfma_f32_16x16x32_bf16 v[88:91], v[164:167], v[204:207], v[88:91]
	v_mfma_f32_16x16x32_bf16 v[76:79], v[156:159], v[214:217], v[76:79]
	v_mfma_f32_16x16x32_bf16 v[72:75], v[164:167], v[214:217], v[72:75]
	s_setprio 0
	s_setprio 1
	v_mfma_f32_16x16x32_bf16 v[116:119], v[168:171], v[184:187], v[116:119]
	v_mfma_f32_16x16x32_bf16 v[112:115], v[176:179], v[184:187], v[112:115]
	v_mfma_f32_16x16x32_bf16 v[100:103], v[168:171], v[192:195], v[100:103]
	v_mfma_f32_16x16x32_bf16 v[96:99], v[176:179], v[192:195], v[96:99]
	v_mfma_f32_16x16x32_bf16 v[84:87], v[168:171], v[200:203], v[84:87]
	v_mfma_f32_16x16x32_bf16 v[80:83], v[176:179], v[200:203], v[80:83]
	v_mfma_f32_16x16x32_bf16 v[68:71], v[168:171], v[208:211], v[68:71]
	v_mfma_f32_16x16x32_bf16 v[64:67], v[176:179], v[208:211], v[64:67]
	v_mfma_f32_16x16x32_bf16 v[116:119], v[172:175], v[188:191], v[116:119]
	v_mfma_f32_16x16x32_bf16 v[112:115], v[180:183], v[188:191], v[112:115]
	v_mfma_f32_16x16x32_bf16 v[100:103], v[172:175], v[196:199], v[100:103]
	v_mfma_f32_16x16x32_bf16 v[96:99], v[180:183], v[196:199], v[96:99]
	v_mfma_f32_16x16x32_bf16 v[84:87], v[172:175], v[204:207], v[84:87]
	v_mfma_f32_16x16x32_bf16 v[80:83], v[180:183], v[204:207], v[80:83]
	v_mfma_f32_16x16x32_bf16 v[68:71], v[172:175], v[214:217], v[68:71]
	v_mfma_f32_16x16x32_bf16 v[64:67], v[180:183], v[214:217], v[64:67]
	s_setprio 0
	s_barrier
	s_add_i32 s52, s19, s2
	v_lshl_add_u64 v[152:153], s[86:87], 0, v[130:131]
	s_mov_b32 m0, s52
	ds_read_b128 v[184:187], v147 offset:16384
	ds_read_b128 v[188:191], v147 offset:17408
	ds_read_b128 v[192:195], v147 offset:18432
	ds_read_b128 v[196:199], v147 offset:19456
	ds_read_b128 v[200:203], v147 offset:20480
	ds_read_b128 v[204:207], v147 offset:21504
	ds_read_b128 v[208:211], v147 offset:22528
	ds_read_b128 v[214:217], v147 offset:23552
	global_load_lds_dwordx4 v[152:153], off
	s_add_i32 m0, s52, 0x2000
	s_add_u32 s52, s86, 0x10000
	v_lshl_add_u64 v[218:219], s[86:87], 0, v[134:135]
	s_addc_u32 s53, s87, 0
	s_add_i32 s61, s20, s2
	global_load_lds_dwordx4 v[218:219], off
	v_lshl_add_u64 v[220:221], s[52:53], 0, v[130:131]
	s_mov_b32 m0, s61
	v_lshl_add_u64 v[222:223], s[88:89], 0, v[132:133]
	global_load_lds_dwordx4 v[220:221], off
	v_lshl_add_u64 v[220:221], s[52:53], 0, v[134:135]
	s_add_i32 m0, s61, 0x2000
	s_nop 0
	global_load_lds_dwordx4 v[220:221], off
	v_lshl_add_u64 v[220:221], s[88:89], 0, v[128:129]
	s_mov_b32 m0, s3
	s_nop 0
	global_load_lds_dwordx4 v[220:221], off
	s_mov_b32 m0, s12
	s_nop 0
	global_load_lds_dwordx4 v[222:223], off
	s_waitcnt vmcnt(8)
	s_waitcnt lgkmcnt(0)
	s_barrier
; #define STAGE(bufoff, gbase) STAGE_(bufoff, gbase, voffA)
; #define LDA(dst, b, h) do { _Pragma("unroll") for (int m = 0; m < 4; ++m) _Pragma("unroll") for (int k = 0; k < 2; ++k) dst[m][k] = *LDSP(const bf16x8, lds + SA(b, h) + aoff + m * 2048 + k * 1024); } while (0)
; #define LDB(dst, b, h) do { _Pragma("unroll") for (int n = 0; n < 2; ++n) _Pragma("unroll") for (int k = 0; k < 2; ++k) dst[n][k] = *LDSP(const bf16x8, lds + SB(b, h) + boff + n * 2048 + k * 1024); } while (0)
; #define MMA(ai, bj, AT, BT) do { __builtin_amdgcn_s_setprio(1); \
;     _Pragma("unroll") for (int m = 0; m < 4; ++m) _Pragma("unroll") for (int n = 0; n < 2; ++n) _Pragma("unroll") for (int k = 0; k < 2; ++k) \
;       acc[ai][bj][m][n] = __builtin_amdgcn_mfma_f32_16x16x32_bf16(BT[n][k], AT[m][k], acc[ai][bj][m][n], 0, 0, 0); \
;     __builtin_amdgcn_s_setprio(0); } while (0)
; #define WAIT_V(n) asm volatile("s_waitcnt vmcnt(" #n ")" ::: "memory")
; #define WAIT_L(n) asm volatile("s_waitcnt lgkmcnt(" #n ")" ::: "memory")
; #define BAR __builtin_amdgcn_s_barrier()
; #define SCHED __builtin_amdgcn_sched_barrier(0)
; #define WAIT_V(n) asm volatile("s_waitcnt vmcnt(" #n ")" ::: "memory")
; #define BAR do { __builtin_amdgcn_sched_barrier(0); __builtin_amdgcn_s_barrier(); asm volatile("" ::: "memory"); __builtin_amdgcn_sched_barrier(0); } while (0)
; template <bool SP2, bool ALIGN_EPI, bool DUAL, class Epi> DI void gemm_phase2(const bf16_t* A, const bf16_t* Bt, const bf16_t* A2, const bf16_t* Bt2, int M, int N, int K, const Epi& E, lds_t* lds) {
;     ...
;         WAIT_V(8); WAIT_L(0); BAR; MMA(1, 0, At, B0); MMA(1, 1, At, B1); BAR; SCHED;
;         LDB(B0, 1, 0); LDB(B1, 1, 1); SCHED; LDA(At, 1, 0); STAGE(SA(0, 1), a2 + hstep);
;         WAIT_V(8); WAIT_L(0); BAR; MMA(0, 0, At, B0); MMA(0, 1, At, B1); BAR; SCHED;
	s_setprio 1
	s_waitcnt lgkmcnt(0)
	v_mfma_f32_16x16x32_bf16 v[60:63], v[148:151], v[184:187], v[60:63]
	v_mfma_f32_16x16x32_bf16 v[56:59], v[160:163], v[184:187], v[56:59]
	v_mfma_f32_16x16x32_bf16 v[44:47], v[148:151], v[192:195], v[44:47]
	v_mfma_f32_16x16x32_bf16 v[40:43], v[160:163], v[192:195], v[40:43]
	v_mfma_f32_16x16x32_bf16 v[28:31], v[148:151], v[200:203], v[28:31]
	v_mfma_f32_16x16x32_bf16 v[24:27], v[160:163], v[200:203], v[24:27]
	v_mfma_f32_16x16x32_bf16 v[12:15], v[148:151], v[208:211], v[12:15]
	v_mfma_f32_16x16x32_bf16 v[8:11], v[160:163], v[208:211], v[8:11]
	v_mfma_f32_16x16x32_bf16 v[60:63], v[156:159], v[188:191], v[60:63]
	v_mfma_f32_16x16x32_bf16 v[56:59], v[164:167], v[188:191], v[56:59]
	v_mfma_f32_16x16x32_bf16 v[44:47], v[156:159], v[196:199], v[44:47]
	v_mfma_f32_16x16x32_bf16 v[40:43], v[164:167], v[196:199], v[40:43]
	v_mfma_f32_16x16x32_bf16 v[28:31], v[156:159], v[204:207], v[28:31]
	v_mfma_f32_16x16x32_bf16 v[24:27], v[164:167], v[204:207], v[24:27]
	v_mfma_f32_16x16x32_bf16 v[12:15], v[156:159], v[214:217], v[12:15]
	v_mfma_f32_16x16x32_bf16 v[8:11], v[164:167], v[214:217], v[8:11]
	s_setprio 0
	s_setprio 1
	v_mfma_f32_16x16x32_bf16 v[52:55], v[168:171], v[184:187], v[52:55]
	v_mfma_f32_16x16x32_bf16 v[48:51], v[176:179], v[184:187], v[48:51]
	v_mfma_f32_16x16x32_bf16 v[36:39], v[168:171], v[192:195], v[36:39]
	v_mfma_f32_16x16x32_bf16 v[32:35], v[176:179], v[192:195], v[32:35]
	v_mfma_f32_16x16x32_bf16 v[20:23], v[168:171], v[200:203], v[20:23]
	v_mfma_f32_16x16x32_bf16 v[16:19], v[176:179], v[200:203], v[16:19]
	v_mfma_f32_16x16x32_bf16 v[4:7], v[168:171], v[208:211], v[4:7]
	v_mfma_f32_16x16x32_bf16 v[0:3], v[176:179], v[208:211], v[0:3]
	v_mfma_f32_16x16x32_bf16 v[52:55], v[172:175], v[188:191], v[52:55]
	v_mfma_f32_16x16x32_bf16 v[48:51], v[180:183], v[188:191], v[48:51]
	v_mfma_f32_16x16x32_bf16 v[36:39], v[172:175], v[196:199], v[36:39]
	v_mfma_f32_16x16x32_bf16 v[32:35], v[180:183], v[196:199], v[32:35]
	v_mfma_f32_16x16x32_bf16 v[20:23], v[172:175], v[204:207], v[20:23]
	v_mfma_f32_16x16x32_bf16 v[16:19], v[180:183], v[204:207], v[16:19]
	v_mfma_f32_16x16x32_bf16 v[4:7], v[172:175], v[214:217], v[4:7]
	v_mfma_f32_16x16x32_bf16 v[0:3], v[180:183], v[214:217], v[0:3]
	s_setprio 0
	s_barrier
	s_add_i32 s61, 0, 0x18000
	v_add_u32_e32 v155, s61, v140
	s_add_i32 s65, 0, 0x1c000
	ds_read_b128 v[148:151], v155
	ds_read_b128 v[156:159], v155 offset:1024
	ds_read_b128 v[160:163], v155 offset:2048
	ds_read_b128 v[164:167], v155 offset:3072
	v_add_u32_e32 v155, s65, v140
	ds_read_b128 v[168:171], v155
	ds_read_b128 v[172:175], v155 offset:1024
	ds_read_b128 v[176:179], v155 offset:2048
	ds_read_b128 v[180:183], v155 offset:3072
	s_add_u32 s52, s88, 0x40000
	s_addc_u32 s53, s89, 0
	s_mov_b32 m0, s13
	v_lshl_add_u64 v[224:225], s[52:53], 0, v[128:129]
	ds_read_b128 v[184:187], v147 offset:32768
	ds_read_b128 v[188:191], v147 offset:33792
	ds_read_b128 v[192:195], v147 offset:34816
	ds_read_b128 v[196:199], v147 offset:35840
	ds_read_b128 v[200:203], v147 offset:36864
	ds_read_b128 v[204:207], v147 offset:37888
	ds_read_b128 v[208:211], v147 offset:38912
	ds_read_b128 v[214:217], v147 offset:39936
	global_load_lds_dwordx4 v[224:225], off
	v_lshl_add_u64 v[224:225], s[52:53], 0, v[132:133]
	s_mov_b32 m0, s14
	s_nop 0
	global_load_lds_dwordx4 v[224:225], off
	s_waitcnt vmcnt(8)
	s_waitcnt lgkmcnt(0)
	s_barrier
	s_setprio 1
	s_waitcnt lgkmcnt(0)
	v_mfma_f32_16x16x32_bf16 v[124:127], v[148:151], v[184:187], v[124:127]
	v_mfma_f32_16x16x32_bf16 v[120:123], v[160:163], v[184:187], v[120:123]
	v_mfma_f32_16x16x32_bf16 v[108:111], v[148:151], v[192:195], v[108:111]
	v_mfma_f32_16x16x32_bf16 v[104:107], v[160:163], v[192:195], v[104:107]
	v_mfma_f32_16x16x32_bf16 v[92:95], v[148:151], v[200:203], v[92:95]
	v_mfma_f32_16x16x32_bf16 v[88:91], v[160:163], v[200:203], v[88:91]
	v_mfma_f32_16x16x32_bf16 v[76:79], v[148:151], v[208:211], v[76:79]
	v_mfma_f32_16x16x32_bf16 v[72:75], v[160:163], v[208:211], v[72:75]
	v_mfma_f32_16x16x32_bf16 v[124:127], v[156:159], v[188:191], v[124:127]
	v_mfma_f32_16x16x32_bf16 v[120:123], v[164:167], v[188:191], v[120:123]
	v_mfma_f32_16x16x32_bf16 v[108:111], v[156:159], v[196:199], v[108:111]
	v_mfma_f32_16x16x32_bf16 v[104:107], v[164:167], v[196:199], v[104:107]
	v_mfma_f32_16x16x32_bf16 v[92:95], v[156:159], v[204:207], v[92:95]
	v_mfma_f32_16x16x32_bf16 v[88:91], v[164:167], v[204:207], v[88:91]
	v_mfma_f32_16x16x32_bf16 v[76:79], v[156:159], v[214:217], v[76:79]
	v_mfma_f32_16x16x32_bf16 v[72:75], v[164:167], v[214:217], v[72:75]
	s_setprio 0
	s_setprio 1
	v_mfma_f32_16x16x32_bf16 v[116:119], v[168:171], v[184:187], v[116:119]
	v_mfma_f32_16x16x32_bf16 v[112:115], v[176:179], v[184:187], v[112:115]
	v_mfma_f32_16x16x32_bf16 v[100:103], v[168:171], v[192:195], v[100:103]
	v_mfma_f32_16x16x32_bf16 v[96:99], v[176:179], v[192:195], v[96:99]
	v_mfma_f32_16x16x32_bf16 v[84:87], v[168:171], v[200:203], v[84:87]
	v_mfma_f32_16x16x32_bf16 v[80:83], v[176:179], v[200:203], v[80:83]
	v_mfma_f32_16x16x32_bf16 v[68:71], v[168:171], v[208:211], v[68:71]
	v_mfma_f32_16x16x32_bf16 v[64:67], v[176:179], v[208:211], v[64:67]
	v_mfma_f32_16x16x32_bf16 v[116:119], v[172:175], v[188:191], v[116:119]
	v_mfma_f32_16x16x32_bf16 v[112:115], v[180:183], v[188:191], v[112:115]
	v_mfma_f32_16x16x32_bf16 v[100:103], v[172:175], v[196:199], v[100:103]
	v_mfma_f32_16x16x32_bf16 v[96:99], v[180:183], v[196:199], v[96:99]
	v_mfma_f32_16x16x32_bf16 v[84:87], v[172:175], v[204:207], v[84:87]
	v_mfma_f32_16x16x32_bf16 v[80:83], v[180:183], v[204:207], v[80:83]
	v_mfma_f32_16x16x32_bf16 v[68:71], v[172:175], v[214:217], v[68:71]
	v_mfma_f32_16x16x32_bf16 v[64:67], v[180:183], v[214:217], v[64:67]
	s_setprio 0
	s_barrier
; #define STAGE(bufoff, gbase) STAGE_(bufoff, gbase, voffA)
; #define STAGEB(bufoff, gbase) STAGE_(bufoff, gbase, voffB)
; #define LDA(dst, b, h) do { _Pragma("unroll") for (int m = 0; m < 4; ++m) _Pragma("unroll") for (int k = 0; k < 2; ++k) dst[m][k] = *LDSP(const bf16x8, lds + SA(b, h) + aoff + m * 2048 + k * 1024); } while (0)
; #define MMA(ai, bj, AT, BT) do { __builtin_amdgcn_s_setprio(1); \
;     _Pragma("unroll") for (int m = 0; m < 4; ++m) _Pragma("unroll") for (int n = 0; n < 2; ++n) _Pragma("unroll") for (int k = 0; k < 2; ++k) \
;       acc[ai][bj][m][n] = __builtin_amdgcn_mfma_f32_16x16x32_bf16(BT[n][k], AT[m][k], acc[ai][bj][m][n], 0, 0, 0); \
;     __builtin_amdgcn_s_setprio(0); } while (0)
; #define WAIT_V(n) asm volatile("s_waitcnt vmcnt(" #n ")" ::: "memory")
; #define WAIT_L(n) asm volatile("s_waitcnt lgkmcnt(" #n ")" ::: "memory")
; #define BAR __builtin_amdgcn_s_barrier()
; #define SCHED __builtin_amdgcn_sched_barrier(0)
; #define WAIT_V(n) asm volatile("s_waitcnt vmcnt(" #n ")" ::: "memory")
; #define BAR do { __builtin_amdgcn_sched_barrier(0); __builtin_amdgcn_s_barrier(); asm volatile("" ::: "memory"); __builtin_amdgcn_sched_barrier(0); } while (0)
; template <bool SP2, bool ALIGN_EPI, bool DUAL, class Epi> DI void gemm_phase2(const bf16_t* A, const bf16_t* Bt, const bf16_t* A2, const bf16_t* Bt2, int M, int N, int K, const Epi& E, lds_t* lds) {
;     ...
;         LDA(At, 1, 1); STAGEB(SB(1, 0), b3); STAGEB(SB(1, 1), b3 + bstep); STAGE(SA(1, 0), a3);
;         WAIT_V(8); WAIT_L(0); BAR; MMA(1, 0, At, B0); MMA(1, 1, At, B1); BAR; SCHED;
;     ...
;     if constexpr (ALIGN_EPI) { if (wr == 0) BAR; }
	s_add_i32 s52, s61, s2
	v_lshl_add_u64 v[152:153], v[152:153], 0, s[8:9]
	s_mov_b32 m0, s52
	ds_read_b128 v[184:187], v147 offset:49152
	ds_read_b128 v[188:191], v147 offset:50176
	ds_read_b128 v[192:195], v147 offset:51200
	ds_read_b128 v[196:199], v147 offset:52224
	ds_read_b128 v[200:203], v147 offset:53248
	ds_read_b128 v[204:207], v147 offset:54272
	ds_read_b128 v[208:211], v147 offset:55296
	ds_read_b128 v[214:217], v147 offset:56320
	global_load_lds_dwordx4 v[152:153], off
	s_add_i32 m0, s52, 0x2000
	s_add_u32 s52, s86, 0x10080
	v_lshl_add_u64 v[152:153], v[218:219], 0, s[8:9]
	s_addc_u32 s53, s87, 0
	s_add_i32 s61, s65, s2
	global_load_lds_dwordx4 v[152:153], off
	v_lshl_add_u64 v[152:153], s[52:53], 0, v[130:131]
	s_mov_b32 m0, s61
	s_nop 0
	global_load_lds_dwordx4 v[152:153], off
	v_lshl_add_u64 v[152:153], s[52:53], 0, v[134:135]
	s_add_i32 m0, s61, 0x2000
	s_nop 0
	global_load_lds_dwordx4 v[152:153], off
	v_lshl_add_u64 v[152:153], v[220:221], 0, s[8:9]
	s_mov_b32 m0, s15
	s_nop 0
	global_load_lds_dwordx4 v[152:153], off
	v_lshl_add_u64 v[152:153], v[222:223], 0, s[8:9]
	s_mov_b32 m0, s18
	s_nop 0
	global_load_lds_dwordx4 v[152:153], off
	s_waitcnt vmcnt(8)
	s_waitcnt lgkmcnt(0)
	s_barrier
	s_setprio 1
	s_waitcnt lgkmcnt(0)
	v_mfma_f32_16x16x32_bf16 v[60:63], v[148:151], v[184:187], v[60:63]
	v_mfma_f32_16x16x32_bf16 v[56:59], v[160:163], v[184:187], v[56:59]
	v_mfma_f32_16x16x32_bf16 v[44:47], v[148:151], v[192:195], v[44:47]
	v_mfma_f32_16x16x32_bf16 v[40:43], v[160:163], v[192:195], v[40:43]
	v_mfma_f32_16x16x32_bf16 v[28:31], v[148:151], v[200:203], v[28:31]
	v_mfma_f32_16x16x32_bf16 v[24:27], v[160:163], v[200:203], v[24:27]
	v_mfma_f32_16x16x32_bf16 v[12:15], v[148:151], v[208:211], v[12:15]
	v_mfma_f32_16x16x32_bf16 v[8:11], v[160:163], v[208:211], v[8:11]
	v_mfma_f32_16x16x32_bf16 v[60:63], v[156:159], v[188:191], v[60:63]
	v_mfma_f32_16x16x32_bf16 v[56:59], v[164:167], v[188:191], v[56:59]
	v_mfma_f32_16x16x32_bf16 v[44:47], v[156:159], v[196:199], v[44:47]
	v_mfma_f32_16x16x32_bf16 v[40:43], v[164:167], v[196:199], v[40:43]
	v_mfma_f32_16x16x32_bf16 v[28:31], v[156:159], v[204:207], v[28:31]
	v_mfma_f32_16x16x32_bf16 v[24:27], v[164:167], v[204:207], v[24:27]
	v_mfma_f32_16x16x32_bf16 v[12:15], v[156:159], v[214:217], v[12:15]
	v_mfma_f32_16x16x32_bf16 v[8:11], v[164:167], v[214:217], v[8:11]
	s_setprio 0
	s_setprio 1
	v_mfma_f32_16x16x32_bf16 v[52:55], v[168:171], v[184:187], v[52:55]
	v_mfma_f32_16x16x32_bf16 v[48:51], v[176:179], v[184:187], v[48:51]
	v_mfma_f32_16x16x32_bf16 v[36:39], v[168:171], v[192:195], v[36:39]
	v_mfma_f32_16x16x32_bf16 v[32:35], v[176:179], v[192:195], v[32:35]
	v_mfma_f32_16x16x32_bf16 v[20:23], v[168:171], v[200:203], v[20:23]
	v_mfma_f32_16x16x32_bf16 v[16:19], v[176:179], v[200:203], v[16:19]
	v_mfma_f32_16x16x32_bf16 v[4:7], v[168:171], v[208:211], v[4:7]
	v_mfma_f32_16x16x32_bf16 v[0:3], v[176:179], v[208:211], v[0:3]
	v_mfma_f32_16x16x32_bf16 v[52:55], v[172:175], v[188:191], v[52:55]
	v_mfma_f32_16x16x32_bf16 v[48:51], v[180:183], v[188:191], v[48:51]
	v_mfma_f32_16x16x32_bf16 v[36:39], v[172:175], v[196:199], v[36:39]
	v_mfma_f32_16x16x32_bf16 v[32:35], v[180:183], v[196:199], v[32:35]
	v_mfma_f32_16x16x32_bf16 v[20:23], v[172:175], v[204:207], v[20:23]
	v_mfma_f32_16x16x32_bf16 v[16:19], v[180:183], v[204:207], v[16:19]
	v_mfma_f32_16x16x32_bf16 v[4:7], v[172:175], v[214:217], v[4:7]
	v_mfma_f32_16x16x32_bf16 v[0:3], v[180:183], v[214:217], v[0:3]
	s_setprio 0
	s_add_i32 s35, s35, 2
	s_add_u32 s68, s68, 0x100
	s_addc_u32 s69, s69, 0
	s_add_u32 s33, s33, 0x100
	s_addc_u32 s34, s34, 0
	s_cmp_gt_u32 s35, 13
	s_barrier
	s_cbranch_scc0 .LBB0_341
	s_and_b64 vcc, exec, s[54:55]
	s_cbranch_vccz .LBB0_344
	s_barrier

; #define STAGE(bufoff, gbase) STAGE_(bufoff, gbase, voffA)
; #define STAGEB(bufoff, gbase) STAGE_(bufoff, gbase, voffB)
; #define LDA(dst, b, h) do { _Pragma("unroll") for (int m = 0; m < 4; ++m) _Pragma("unroll") for (int k = 0; k < 2; ++k) dst[m][k] = *LDSP(const bf16x8, lds + SA(b, h) + aoff + m * 2048 + k * 1024); } while (0)
; #define LDB(dst, b, h) do { _Pragma("unroll") for (int n = 0; n < 2; ++n) _Pragma("unroll") for (int k = 0; k < 2; ++k) dst[n][k] = *LDSP(const bf16x8, lds + SB(b, h) + boff + n * 2048 + k * 1024); } while (0)
; #define MMA(ai, bj, AT, BT) do { __builtin_amdgcn_s_setprio(1); \
;     _Pragma("unroll") for (int m = 0; m < 4; ++m) _Pragma("unroll") for (int n = 0; n < 2; ++n) _Pragma("unroll") for (int k = 0; k < 2; ++k) \
;       acc[ai][bj][m][n] = __builtin_amdgcn_mfma_f32_16x16x32_bf16(BT[n][k], AT[m][k], acc[ai][bj][m][n], 0, 0, 0); \
;     __builtin_amdgcn_s_setprio(0); } while (0)
; #define WAIT_V(n) asm volatile("s_waitcnt vmcnt(" #n ")" ::: "memory")
; #define WAIT_L(n) asm volatile("s_waitcnt lgkmcnt(" #n ")" ::: "memory")
; #define BAR __builtin_amdgcn_s_barrier()
; #define SCHED __builtin_amdgcn_sched_barrier(0)
; #define WAIT_V(n) asm volatile("s_waitcnt vmcnt(" #n ")" ::: "memory")
; #define BAR do { __builtin_amdgcn_sched_barrier(0); __builtin_amdgcn_s_barrier(); asm volatile("" ::: "memory"); __builtin_amdgcn_sched_barrier(0); } while (0)
; template <bool SP2, bool ALIGN_EPI, bool DUAL, class Epi> DI void gemm_phase2(const bf16_t* A, const bf16_t* Bt, const bf16_t* A2, const bf16_t* Bt2, int M, int N, int K, const Epi& E, lds_t* lds) {
;     ...
;     for (int t = 0; t < nt; t += 2) {
;       const bool last = (t == nt - 2);
;       const char* a1 = cA + (size_t)(t + 1) * kstep;
;       const char* a2 = last ? nA : cA + (size_t)(t + 2) * kstep; const char* b2 = last ? nB : cB + (size_t)(t + 2) * kstep;
;       const char* a3 = a2 + kstep; const char* b3 = b2 + kstep;
;       if constexpr (SP2) {
;         LDB(B0, 0, 0); LDB(B1, 0, 1); SCHED; LDA(At, 0, 0); STAGE(SA(1, 1), a1 + hstep);
;         WAIT_V(8); WAIT_L(0); BAR; MMA(0, 0, At, B0); MMA(0, 1, At, B1); BAR; SCHED;
;         LDA(At, 0, 1); STAGEB(SB(0, 0), b2); STAGEB(SB(0, 1), b2 + bstep); STAGE(SA(0, 0), a2);
.LBB0_482:
	v_add_u32_e32 v151, s20, v141
	ds_read_b128 v[152:155], v151
	ds_read_b128 v[156:159], v151 offset:1024
	ds_read_b128 v[160:163], v151 offset:2048
	ds_read_b128 v[164:167], v151 offset:3072
	v_add_u32_e32 v151, s21, v141
	ds_read_b128 v[168:171], v151
	ds_read_b128 v[172:175], v151 offset:1024
	ds_read_b128 v[176:179], v151 offset:2048
	ds_read_b128 v[180:183], v151 offset:3072
	s_add_u32 s41, s60, 0xfffc0080
	s_addc_u32 s59, s61, -1
	s_cmp_eq_u32 s37, 12
	s_cselect_b32 s65, s2, s59
	s_cselect_b32 s64, s3, s41
	s_cselect_b32 s63, s0, s35
	s_cselect_b32 s62, s1, s34
	v_lshl_add_u64 v[220:221], s[60:61], 0, v[136:137]
	s_add_i32 m0, s9, 0xc000
	ds_read_b128 v[184:187], v149
	ds_read_b128 v[188:191], v149 offset:1024
	ds_read_b128 v[192:195], v149 offset:2048
	ds_read_b128 v[196:199], v149 offset:3072
	ds_read_b128 v[200:203], v149 offset:4096
	ds_read_b128 v[204:207], v149 offset:5120
	ds_read_b128 v[208:211], v149 offset:6144
	ds_read_b128 v[216:219], v149 offset:7168
	global_load_lds_dwordx4 v[220:221], off
	v_lshl_add_u64 v[220:221], s[60:61], 0, v[138:139]
	s_add_i32 m0, s9, 0xe000
	s_nop 0
	global_load_lds_dwordx4 v[220:221], off
	s_waitcnt vmcnt(8)
	s_waitcnt lgkmcnt(0)
	s_barrier
	s_setprio 1
	s_waitcnt lgkmcnt(0)
	v_mfma_f32_16x16x32_bf16 v[124:127], v[152:155], v[184:187], v[124:127]
	v_mfma_f32_16x16x32_bf16 v[120:123], v[160:163], v[184:187], v[120:123]
	v_mfma_f32_16x16x32_bf16 v[116:119], v[152:155], v[192:195], v[116:119]
	v_mfma_f32_16x16x32_bf16 v[112:115], v[160:163], v[192:195], v[112:115]
	v_mfma_f32_16x16x32_bf16 v[108:111], v[152:155], v[200:203], v[108:111]
	v_mfma_f32_16x16x32_bf16 v[104:107], v[160:163], v[200:203], v[104:107]
	v_mfma_f32_16x16x32_bf16 v[100:103], v[152:155], v[208:211], v[100:103]
	v_mfma_f32_16x16x32_bf16 v[96:99], v[160:163], v[208:211], v[96:99]
	v_mfma_f32_16x16x32_bf16 v[124:127], v[156:159], v[188:191], v[124:127]
	v_mfma_f32_16x16x32_bf16 v[120:123], v[164:167], v[188:191], v[120:123]
	v_mfma_f32_16x16x32_bf16 v[116:119], v[156:159], v[196:199], v[116:119]
	v_mfma_f32_16x16x32_bf16 v[112:115], v[164:167], v[196:199], v[112:115]
	v_mfma_f32_16x16x32_bf16 v[108:111], v[156:159], v[204:207], v[108:111]
	v_mfma_f32_16x16x32_bf16 v[104:107], v[164:167], v[204:207], v[104:107]
	v_mfma_f32_16x16x32_bf16 v[100:103], v[156:159], v[216:219], v[100:103]
	v_mfma_f32_16x16x32_bf16 v[96:99], v[164:167], v[216:219], v[96:99]
	s_setprio 0
	s_setprio 1
	v_mfma_f32_16x16x32_bf16 v[92:95], v[168:171], v[184:187], v[92:95]
	v_mfma_f32_16x16x32_bf16 v[88:91], v[176:179], v[184:187], v[88:91]
	v_mfma_f32_16x16x32_bf16 v[84:87], v[168:171], v[192:195], v[84:87]
	v_mfma_f32_16x16x32_bf16 v[80:83], v[176:179], v[192:195], v[80:83]
	v_mfma_f32_16x16x32_bf16 v[76:79], v[168:171], v[200:203], v[76:79]
	v_mfma_f32_16x16x32_bf16 v[72:75], v[176:179], v[200:203], v[72:75]
	v_mfma_f32_16x16x32_bf16 v[68:71], v[168:171], v[208:211], v[68:71]
	v_mfma_f32_16x16x32_bf16 v[64:67], v[176:179], v[208:211], v[64:67]
	v_mfma_f32_16x16x32_bf16 v[92:95], v[172:175], v[188:191], v[92:95]
	v_mfma_f32_16x16x32_bf16 v[88:91], v[180:183], v[188:191], v[88:91]
	v_mfma_f32_16x16x32_bf16 v[84:87], v[172:175], v[196:199], v[84:87]
	v_mfma_f32_16x16x32_bf16 v[80:83], v[180:183], v[196:199], v[80:83]
	v_mfma_f32_16x16x32_bf16 v[76:79], v[172:175], v[204:207], v[76:79]
	v_mfma_f32_16x16x32_bf16 v[72:75], v[180:183], v[204:207], v[72:75]
	v_mfma_f32_16x16x32_bf16 v[68:71], v[172:175], v[216:219], v[68:71]
	v_mfma_f32_16x16x32_bf16 v[64:67], v[180:183], v[216:219], v[64:67]
	s_setprio 0
	s_barrier
	s_add_i32 s41, s20, s8
	v_lshl_add_u64 v[220:221], s[62:63], 0, v[130:131]
	s_mov_b32 m0, s41
	ds_read_b128 v[184:187], v149 offset:16384
	ds_read_b128 v[188:191], v149 offset:17408
	ds_read_b128 v[192:195], v149 offset:18432
	ds_read_b128 v[196:199], v149 offset:19456
	ds_read_b128 v[200:203], v149 offset:20480
	ds_read_b128 v[204:207], v149 offset:21504
	ds_read_b128 v[208:211], v149 offset:22528
	ds_read_b128 v[216:219], v149 offset:23552
	global_load_lds_dwordx4 v[220:221], off
	s_add_i32 m0, s41, 0x2000
	s_add_u32 s66, s62, 0x10000
	v_lshl_add_u64 v[222:223], s[62:63], 0, v[134:135]
	s_addc_u32 s67, s63, 0
	s_add_i32 s41, s21, s8
	global_load_lds_dwordx4 v[222:223], off
	v_lshl_add_u64 v[224:225], s[66:67], 0, v[130:131]
	s_mov_b32 m0, s41
	v_lshl_add_u64 v[226:227], s[64:65], 0, v[132:133]
	global_load_lds_dwordx4 v[224:225], off
	v_lshl_add_u64 v[224:225], s[66:67], 0, v[134:135]
	s_add_i32 m0, s41, 0x2000
	s_nop 0
	global_load_lds_dwordx4 v[224:225], off
	v_lshl_add_u64 v[224:225], s[64:65], 0, v[128:129]
	s_mov_b32 m0, s9
	s_nop 0
	global_load_lds_dwordx4 v[224:225], off
	s_mov_b32 m0, s10
	s_nop 0
	global_load_lds_dwordx4 v[226:227], off
	s_waitcnt vmcnt(8)
	s_waitcnt lgkmcnt(0)
	s_barrier
; #define STAGE(bufoff, gbase) STAGE_(bufoff, gbase, voffA)
; #define LDA(dst, b, h) do { _Pragma("unroll") for (int m = 0; m < 4; ++m) _Pragma("unroll") for (int k = 0; k < 2; ++k) dst[m][k] = *LDSP(const bf16x8, lds + SA(b, h) + aoff + m * 2048 + k * 1024); } while (0)
; #define LDB(dst, b, h) do { _Pragma("unroll") for (int n = 0; n < 2; ++n) _Pragma("unroll") for (int k = 0; k < 2; ++k) dst[n][k] = *LDSP(const bf16x8, lds + SB(b, h) + boff + n * 2048 + k * 1024); } while (0)
; #define MMA(ai, bj, AT, BT) do { __builtin_amdgcn_s_setprio(1); \
;     _Pragma("unroll") for (int m = 0; m < 4; ++m) _Pragma("unroll") for (int n = 0; n < 2; ++n) _Pragma("unroll") for (int k = 0; k < 2; ++k) \
;       acc[ai][bj][m][n] = __builtin_amdgcn_mfma_f32_16x16x32_bf16(BT[n][k], AT[m][k], acc[ai][bj][m][n], 0, 0, 0); \
;     __builtin_amdgcn_s_setprio(0); } while (0)
; #define WAIT_V(n) asm volatile("s_waitcnt vmcnt(" #n ")" ::: "memory")
; #define WAIT_L(n) asm volatile("s_waitcnt lgkmcnt(" #n ")" ::: "memory")
; #define BAR __builtin_amdgcn_s_barrier()
; #define SCHED __builtin_amdgcn_sched_barrier(0)
; #define WAIT_V(n) asm volatile("s_waitcnt vmcnt(" #n ")" ::: "memory")
; #define BAR do { __builtin_amdgcn_sched_barrier(0); __builtin_amdgcn_s_barrier(); asm volatile("" ::: "memory"); __builtin_amdgcn_sched_barrier(0); } while (0)
; template <bool SP2, bool ALIGN_EPI, bool DUAL, class Epi> DI void gemm_phase2(const bf16_t* A, const bf16_t* Bt, const bf16_t* A2, const bf16_t* Bt2, int M, int N, int K, const Epi& E, lds_t* lds) {
;     ...
;         WAIT_V(8); WAIT_L(0); BAR; MMA(1, 0, At, B0); MMA(1, 1, At, B1); BAR; SCHED;
;         LDB(B0, 1, 0); LDB(B1, 1, 1); SCHED; LDA(At, 1, 0); STAGE(SA(0, 1), a2 + hstep);
;         WAIT_V(8); WAIT_L(0); BAR; MMA(0, 0, At, B0); MMA(0, 1, At, B1); BAR; SCHED;
	s_setprio 1
	s_waitcnt lgkmcnt(0)
	v_mfma_f32_16x16x32_bf16 v[60:63], v[152:155], v[184:187], v[60:63]
	v_mfma_f32_16x16x32_bf16 v[56:59], v[160:163], v[184:187], v[56:59]
	v_mfma_f32_16x16x32_bf16 v[52:55], v[152:155], v[192:195], v[52:55]
	v_mfma_f32_16x16x32_bf16 v[48:51], v[160:163], v[192:195], v[48:51]
	v_mfma_f32_16x16x32_bf16 v[44:47], v[152:155], v[200:203], v[44:47]
	v_mfma_f32_16x16x32_bf16 v[40:43], v[160:163], v[200:203], v[40:43]
	v_mfma_f32_16x16x32_bf16 v[36:39], v[152:155], v[208:211], v[36:39]
	v_mfma_f32_16x16x32_bf16 v[32:35], v[160:163], v[208:211], v[32:35]
	v_mfma_f32_16x16x32_bf16 v[60:63], v[156:159], v[188:191], v[60:63]
	v_mfma_f32_16x16x32_bf16 v[56:59], v[164:167], v[188:191], v[56:59]
	v_mfma_f32_16x16x32_bf16 v[52:55], v[156:159], v[196:199], v[52:55]
	v_mfma_f32_16x16x32_bf16 v[48:51], v[164:167], v[196:199], v[48:51]
	v_mfma_f32_16x16x32_bf16 v[44:47], v[156:159], v[204:207], v[44:47]
	v_mfma_f32_16x16x32_bf16 v[40:43], v[164:167], v[204:207], v[40:43]
	v_mfma_f32_16x16x32_bf16 v[36:39], v[156:159], v[216:219], v[36:39]
	v_mfma_f32_16x16x32_bf16 v[32:35], v[164:167], v[216:219], v[32:35]
	s_setprio 0
	s_setprio 1
	v_mfma_f32_16x16x32_bf16 v[28:31], v[168:171], v[184:187], v[28:31]
	v_mfma_f32_16x16x32_bf16 v[24:27], v[176:179], v[184:187], v[24:27]
	v_mfma_f32_16x16x32_bf16 v[20:23], v[168:171], v[192:195], v[20:23]
	v_mfma_f32_16x16x32_bf16 v[16:19], v[176:179], v[192:195], v[16:19]
	v_mfma_f32_16x16x32_bf16 v[12:15], v[168:171], v[200:203], v[12:15]
	v_mfma_f32_16x16x32_bf16 v[8:11], v[176:179], v[200:203], v[8:11]
	v_mfma_f32_16x16x32_bf16 v[4:7], v[168:171], v[208:211], v[4:7]
	v_mfma_f32_16x16x32_bf16 v[0:3], v[176:179], v[208:211], v[0:3]
	v_mfma_f32_16x16x32_bf16 v[28:31], v[172:175], v[188:191], v[28:31]
	v_mfma_f32_16x16x32_bf16 v[24:27], v[180:183], v[188:191], v[24:27]
	v_mfma_f32_16x16x32_bf16 v[20:23], v[172:175], v[196:199], v[20:23]
	v_mfma_f32_16x16x32_bf16 v[16:19], v[180:183], v[196:199], v[16:19]
	v_mfma_f32_16x16x32_bf16 v[12:15], v[172:175], v[204:207], v[12:15]
	v_mfma_f32_16x16x32_bf16 v[8:11], v[180:183], v[204:207], v[8:11]
	v_mfma_f32_16x16x32_bf16 v[4:7], v[172:175], v[216:219], v[4:7]
	v_mfma_f32_16x16x32_bf16 v[0:3], v[180:183], v[216:219], v[0:3]
	s_setprio 0
	s_barrier
	s_add_i32 s41, 0, 0x18000
	v_add_u32_e32 v151, s41, v141
	s_add_i32 s59, 0, 0x1c000
	ds_read_b128 v[152:155], v151
	ds_read_b128 v[156:159], v151 offset:1024
	ds_read_b128 v[160:163], v151 offset:2048
	ds_read_b128 v[164:167], v151 offset:3072
	v_add_u32_e32 v151, s59, v141
	ds_read_b128 v[168:171], v151
	ds_read_b128 v[172:175], v151 offset:1024
	ds_read_b128 v[176:179], v151 offset:2048
	ds_read_b128 v[180:183], v151 offset:3072
	s_add_u32 s64, s64, 0x40000
	s_addc_u32 s65, s65, 0
	s_mov_b32 m0, s11
	v_lshl_add_u64 v[228:229], s[64:65], 0, v[128:129]
	ds_read_b128 v[184:187], v149 offset:32768
	ds_read_b128 v[188:191], v149 offset:33792
	ds_read_b128 v[192:195], v149 offset:34816
	ds_read_b128 v[196:199], v149 offset:35840
	ds_read_b128 v[200:203], v149 offset:36864
	ds_read_b128 v[204:207], v149 offset:37888
	ds_read_b128 v[208:211], v149 offset:38912
	ds_read_b128 v[216:219], v149 offset:39936
	global_load_lds_dwordx4 v[228:229], off
	v_lshl_add_u64 v[228:229], s[64:65], 0, v[132:133]
	s_mov_b32 m0, s14
	s_nop 0
	global_load_lds_dwordx4 v[228:229], off
	s_waitcnt vmcnt(8)
	s_waitcnt lgkmcnt(0)
	s_barrier
	s_setprio 1
	s_waitcnt lgkmcnt(0)
	v_mfma_f32_16x16x32_bf16 v[124:127], v[152:155], v[184:187], v[124:127]
	v_mfma_f32_16x16x32_bf16 v[120:123], v[160:163], v[184:187], v[120:123]
	v_mfma_f32_16x16x32_bf16 v[116:119], v[152:155], v[192:195], v[116:119]
	v_mfma_f32_16x16x32_bf16 v[112:115], v[160:163], v[192:195], v[112:115]
	v_mfma_f32_16x16x32_bf16 v[108:111], v[152:155], v[200:203], v[108:111]
	v_mfma_f32_16x16x32_bf16 v[104:107], v[160:163], v[200:203], v[104:107]
	v_mfma_f32_16x16x32_bf16 v[100:103], v[152:155], v[208:211], v[100:103]
	v_mfma_f32_16x16x32_bf16 v[96:99], v[160:163], v[208:211], v[96:99]
	v_mfma_f32_16x16x32_bf16 v[124:127], v[156:159], v[188:191], v[124:127]
	v_mfma_f32_16x16x32_bf16 v[120:123], v[164:167], v[188:191], v[120:123]
	v_mfma_f32_16x16x32_bf16 v[116:119], v[156:159], v[196:199], v[116:119]
	v_mfma_f32_16x16x32_bf16 v[112:115], v[164:167], v[196:199], v[112:115]
	v_mfma_f32_16x16x32_bf16 v[108:111], v[156:159], v[204:207], v[108:111]
	v_mfma_f32_16x16x32_bf16 v[104:107], v[164:167], v[204:207], v[104:107]
	v_mfma_f32_16x16x32_bf16 v[100:103], v[156:159], v[216:219], v[100:103]
	v_mfma_f32_16x16x32_bf16 v[96:99], v[164:167], v[216:219], v[96:99]
	s_setprio 0
	s_setprio 1
	v_mfma_f32_16x16x32_bf16 v[92:95], v[168:171], v[184:187], v[92:95]
	v_mfma_f32_16x16x32_bf16 v[88:91], v[176:179], v[184:187], v[88:91]
	v_mfma_f32_16x16x32_bf16 v[84:87], v[168:171], v[192:195], v[84:87]
	v_mfma_f32_16x16x32_bf16 v[80:83], v[176:179], v[192:195], v[80:83]
	v_mfma_f32_16x16x32_bf16 v[76:79], v[168:171], v[200:203], v[76:79]
	v_mfma_f32_16x16x32_bf16 v[72:75], v[176:179], v[200:203], v[72:75]
	v_mfma_f32_16x16x32_bf16 v[68:71], v[168:171], v[208:211], v[68:71]
	v_mfma_f32_16x16x32_bf16 v[64:67], v[176:179], v[208:211], v[64:67]
	v_mfma_f32_16x16x32_bf16 v[92:95], v[172:175], v[188:191], v[92:95]
	v_mfma_f32_16x16x32_bf16 v[88:91], v[180:183], v[188:191], v[88:91]
	v_mfma_f32_16x16x32_bf16 v[84:87], v[172:175], v[196:199], v[84:87]
	v_mfma_f32_16x16x32_bf16 v[80:83], v[180:183], v[196:199], v[80:83]
	v_mfma_f32_16x16x32_bf16 v[76:79], v[172:175], v[204:207], v[76:79]
	v_mfma_f32_16x16x32_bf16 v[72:75], v[180:183], v[204:207], v[72:75]
	v_mfma_f32_16x16x32_bf16 v[68:71], v[172:175], v[216:219], v[68:71]
	v_mfma_f32_16x16x32_bf16 v[64:67], v[180:183], v[216:219], v[64:67]
	s_setprio 0
	s_barrier
; #define STAGE(bufoff, gbase) STAGE_(bufoff, gbase, voffA)
; #define STAGEB(bufoff, gbase) STAGE_(bufoff, gbase, voffB)
; #define LDA(dst, b, h) do { _Pragma("unroll") for (int m = 0; m < 4; ++m) _Pragma("unroll") for (int k = 0; k < 2; ++k) dst[m][k] = *LDSP(const bf16x8, lds + SA(b, h) + aoff + m * 2048 + k * 1024); } while (0)
; #define MMA(ai, bj, AT, BT) do { __builtin_amdgcn_s_setprio(1); \
;     _Pragma("unroll") for (int m = 0; m < 4; ++m) _Pragma("unroll") for (int n = 0; n < 2; ++n) _Pragma("unroll") for (int k = 0; k < 2; ++k) \
;       acc[ai][bj][m][n] = __builtin_amdgcn_mfma_f32_16x16x32_bf16(BT[n][k], AT[m][k], acc[ai][bj][m][n], 0, 0, 0); \
;     __builtin_amdgcn_s_setprio(0); } while (0)
; #define WAIT_V(n) asm volatile("s_waitcnt vmcnt(" #n ")" ::: "memory")
; #define WAIT_L(n) asm volatile("s_waitcnt lgkmcnt(" #n ")" ::: "memory")
; #define BAR __builtin_amdgcn_s_barrier()
; #define SCHED __builtin_amdgcn_sched_barrier(0)
; #define WAIT_V(n) asm volatile("s_waitcnt vmcnt(" #n ")" ::: "memory")
; #define BAR do { __builtin_amdgcn_sched_barrier(0); __builtin_amdgcn_s_barrier(); asm volatile("" ::: "memory"); __builtin_amdgcn_sched_barrier(0); } while (0)
; template <bool SP2, bool ALIGN_EPI, bool DUAL, class Epi> DI void gemm_phase2(const bf16_t* A, const bf16_t* Bt, const bf16_t* A2, const bf16_t* Bt2, int M, int N, int K, const Epi& E, lds_t* lds) {
;     ...
;         LDA(At, 1, 1); STAGEB(SB(1, 0), b3); STAGEB(SB(1, 1), b3 + bstep); STAGE(SA(1, 0), a3);
;         WAIT_V(8); WAIT_L(0); BAR; MMA(1, 0, At, B0); MMA(1, 1, At, B1); BAR; SCHED;
;     ...
;     if constexpr (ALIGN_EPI) { if (wr == 0) BAR; }
	s_add_i32 s41, s41, s8
	v_lshl_add_u64 v[220:221], v[220:221], 0, s[30:31]
	s_mov_b32 m0, s41
	ds_read_b128 v[184:187], v149 offset:49152
	ds_read_b128 v[188:191], v149 offset:50176
	ds_read_b128 v[192:195], v149 offset:51200
	ds_read_b128 v[196:199], v149 offset:52224
	ds_read_b128 v[200:203], v149 offset:53248
	ds_read_b128 v[204:207], v149 offset:54272
	ds_read_b128 v[208:211], v149 offset:55296
	ds_read_b128 v[216:219], v149 offset:56320
	global_load_lds_dwordx4 v[220:221], off
	s_add_i32 m0, s41, 0x2000
	s_add_u32 s62, s62, 0x10080
	v_lshl_add_u64 v[220:221], v[222:223], 0, s[30:31]
	s_addc_u32 s63, s63, 0
	s_add_i32 s41, s59, s8
	global_load_lds_dwordx4 v[220:221], off
	v_lshl_add_u64 v[220:221], s[62:63], 0, v[130:131]
	s_mov_b32 m0, s41
	s_nop 0
	global_load_lds_dwordx4 v[220:221], off
	v_lshl_add_u64 v[220:221], s[62:63], 0, v[134:135]
	s_add_i32 m0, s41, 0x2000
	s_nop 0
	global_load_lds_dwordx4 v[220:221], off
	v_lshl_add_u64 v[220:221], v[224:225], 0, s[30:31]
	s_mov_b32 m0, s18
	s_nop 0
	global_load_lds_dwordx4 v[220:221], off
	v_lshl_add_u64 v[220:221], v[226:227], 0, s[30:31]
	s_mov_b32 m0, s19
	s_nop 0
	global_load_lds_dwordx4 v[220:221], off
	s_waitcnt vmcnt(8)
	s_waitcnt lgkmcnt(0)
	s_barrier
	s_setprio 1
	s_waitcnt lgkmcnt(0)
	v_mfma_f32_16x16x32_bf16 v[60:63], v[152:155], v[184:187], v[60:63]
	v_mfma_f32_16x16x32_bf16 v[56:59], v[160:163], v[184:187], v[56:59]
	v_mfma_f32_16x16x32_bf16 v[52:55], v[152:155], v[192:195], v[52:55]
	v_mfma_f32_16x16x32_bf16 v[48:51], v[160:163], v[192:195], v[48:51]
	v_mfma_f32_16x16x32_bf16 v[44:47], v[152:155], v[200:203], v[44:47]
	v_mfma_f32_16x16x32_bf16 v[40:43], v[160:163], v[200:203], v[40:43]
	v_mfma_f32_16x16x32_bf16 v[36:39], v[152:155], v[208:211], v[36:39]
	v_mfma_f32_16x16x32_bf16 v[32:35], v[160:163], v[208:211], v[32:35]
	v_mfma_f32_16x16x32_bf16 v[60:63], v[156:159], v[188:191], v[60:63]
	v_mfma_f32_16x16x32_bf16 v[56:59], v[164:167], v[188:191], v[56:59]
	v_mfma_f32_16x16x32_bf16 v[52:55], v[156:159], v[196:199], v[52:55]
	v_mfma_f32_16x16x32_bf16 v[48:51], v[164:167], v[196:199], v[48:51]
	v_mfma_f32_16x16x32_bf16 v[44:47], v[156:159], v[204:207], v[44:47]
	v_mfma_f32_16x16x32_bf16 v[40:43], v[164:167], v[204:207], v[40:43]
	v_mfma_f32_16x16x32_bf16 v[36:39], v[156:159], v[216:219], v[36:39]
	v_mfma_f32_16x16x32_bf16 v[32:35], v[164:167], v[216:219], v[32:35]
	s_setprio 0
	s_setprio 1
	v_mfma_f32_16x16x32_bf16 v[28:31], v[168:171], v[184:187], v[28:31]
	v_mfma_f32_16x16x32_bf16 v[24:27], v[176:179], v[184:187], v[24:27]
	v_mfma_f32_16x16x32_bf16 v[20:23], v[168:171], v[192:195], v[20:23]
	v_mfma_f32_16x16x32_bf16 v[16:19], v[176:179], v[192:195], v[16:19]
	v_mfma_f32_16x16x32_bf16 v[12:15], v[168:171], v[200:203], v[12:15]
	v_mfma_f32_16x16x32_bf16 v[8:11], v[176:179], v[200:203], v[8:11]
	v_mfma_f32_16x16x32_bf16 v[4:7], v[168:171], v[208:211], v[4:7]
	v_mfma_f32_16x16x32_bf16 v[0:3], v[176:179], v[208:211], v[0:3]
	v_mfma_f32_16x16x32_bf16 v[28:31], v[172:175], v[188:191], v[28:31]
	v_mfma_f32_16x16x32_bf16 v[24:27], v[180:183], v[188:191], v[24:27]
	v_mfma_f32_16x16x32_bf16 v[20:23], v[172:175], v[196:199], v[20:23]
	v_mfma_f32_16x16x32_bf16 v[16:19], v[180:183], v[196:199], v[16:19]
	v_mfma_f32_16x16x32_bf16 v[12:15], v[172:175], v[204:207], v[12:15]
	v_mfma_f32_16x16x32_bf16 v[8:11], v[180:183], v[204:207], v[8:11]
	v_mfma_f32_16x16x32_bf16 v[4:7], v[172:175], v[216:219], v[4:7]
	v_mfma_f32_16x16x32_bf16 v[0:3], v[180:183], v[216:219], v[0:3]
	s_setprio 0
	s_add_i32 s37, s37, 2
	s_add_u32 s60, s60, 0x100
	s_addc_u32 s61, s61, 0
	s_add_u32 s34, s34, 0x100
	s_addc_u32 s35, s35, 0
	s_cmp_gt_u32 s37, 13
	s_barrier
	s_cbranch_scc0 .LBB0_482
	s_and_b64 vcc, exec, s[38:39]
	s_cbranch_vccz .LBB0_485
	s_barrier

; #define STAGE(bufoff, gbase) STAGE_(bufoff, gbase, voffA)
; #define STAGEB(bufoff, gbase) STAGE_(bufoff, gbase, voffB)
; #define LDA(dst, b, h) do { _Pragma("unroll") for (int m = 0; m < 4; ++m) _Pragma("unroll") for (int k = 0; k < 2; ++k) dst[m][k] = *LDSP(const bf16x8, lds + SA(b, h) + aoff + m * 2048 + k * 1024); } while (0)
; #define LDB(dst, b, h) do { _Pragma("unroll") for (int n = 0; n < 2; ++n) _Pragma("unroll") for (int k = 0; k < 2; ++k) dst[n][k] = *LDSP(const bf16x8, lds + SB(b, h) + boff + n * 2048 + k * 1024); } while (0)
; #define MMA(ai, bj, AT, BT) do { __builtin_amdgcn_s_setprio(1); \
;     _Pragma("unroll") for (int m = 0; m < 4; ++m) _Pragma("unroll") for (int n = 0; n < 2; ++n) _Pragma("unroll") for (int k = 0; k < 2; ++k) \
;       acc[ai][bj][m][n] = __builtin_amdgcn_mfma_f32_16x16x32_bf16(BT[n][k], AT[m][k], acc[ai][bj][m][n], 0, 0, 0); \
;     __builtin_amdgcn_s_setprio(0); } while (0)
; #define WAIT_V(n) asm volatile("s_waitcnt vmcnt(" #n ")" ::: "memory")
; #define WAIT_L(n) asm volatile("s_waitcnt lgkmcnt(" #n ")" ::: "memory")
; #define BAR __builtin_amdgcn_s_barrier()
; #define SCHED __builtin_amdgcn_sched_barrier(0)
; #define WAIT_V(n) asm volatile("s_waitcnt vmcnt(" #n ")" ::: "memory")
; #define BAR do { __builtin_amdgcn_sched_barrier(0); __builtin_amdgcn_s_barrier(); asm volatile("" ::: "memory"); __builtin_amdgcn_sched_barrier(0); } while (0)
; template <bool SP2, bool ALIGN_EPI, bool DUAL, class Epi> DI void gemm_phase2(const bf16_t* A, const bf16_t* Bt, const bf16_t* A2, const bf16_t* Bt2, int M, int N, int K, const Epi& E, lds_t* lds) {
;     ...
;     for (int t = 0; t < nt; t += 2) {
;       const bool last = (t == nt - 2);
;       const char* a1 = cA + (size_t)(t + 1) * kstep;
;       const char* a2 = last ? nA : cA + (size_t)(t + 2) * kstep; const char* b2 = last ? nB : cB + (size_t)(t + 2) * kstep;
;       const char* a3 = a2 + kstep; const char* b3 = b2 + kstep;
;       if constexpr (SP2) {
;         LDB(B0, 0, 0); LDB(B1, 0, 1); SCHED; LDA(At, 0, 0); STAGE(SA(1, 1), a1 + hstep);
;         WAIT_V(8); WAIT_L(0); BAR; MMA(0, 0, At, B0); MMA(0, 1, At, B1); BAR; SCHED;
;         LDA(At, 0, 1); STAGEB(SB(0, 0), b2); STAGEB(SB(0, 1), b2 + bstep); STAGE(SA(0, 0), a2);
.LBB0_551:
	ds_read_b128 v[152:155], v148
	ds_read_b128 v[156:159], v148 offset:1024
	ds_read_b128 v[160:163], v148 offset:2048
	ds_read_b128 v[164:167], v148 offset:3072
	ds_read_b128 v[168:171], v149
	ds_read_b128 v[172:175], v149 offset:1024
	ds_read_b128 v[176:179], v149 offset:2048
	ds_read_b128 v[180:183], v149 offset:3072
	s_add_u32 s35, s60, 0xfffc0080
	s_addc_u32 s37, s61, -1
	s_cmp_eq_u32 s34, 12
	s_cselect_b32 s65, s0, s37
	s_cselect_b32 s64, s1, s35
	s_cselect_b32 s63, s21, s33
	s_cselect_b32 s62, s22, s23
	v_lshl_add_u64 v[140:141], s[60:61], 0, v[136:137]
	s_add_i32 m0, s3, 0xc000
	ds_read_b128 v[184:187], v150
	ds_read_b128 v[188:191], v150 offset:1024
	ds_read_b128 v[192:195], v150 offset:2048
	ds_read_b128 v[196:199], v150 offset:3072
	ds_read_b128 v[200:203], v150 offset:4096
	ds_read_b128 v[204:207], v150 offset:5120
	ds_read_b128 v[208:211], v150 offset:6144
	ds_read_b128 v[216:219], v150 offset:7168
	global_load_lds_dwordx4 v[140:141], off
	v_lshl_add_u64 v[140:141], s[60:61], 0, v[138:139]
	s_add_i32 m0, s3, 0xe000
	s_nop 0
	global_load_lds_dwordx4 v[140:141], off
	s_waitcnt vmcnt(8)
	s_waitcnt lgkmcnt(0)
	s_barrier
	s_setprio 1
	s_waitcnt lgkmcnt(0)
	v_mfma_f32_16x16x32_bf16 v[124:127], v[152:155], v[184:187], v[124:127]
	v_mfma_f32_16x16x32_bf16 v[120:123], v[160:163], v[184:187], v[120:123]
	v_mfma_f32_16x16x32_bf16 v[108:111], v[152:155], v[192:195], v[108:111]
	v_mfma_f32_16x16x32_bf16 v[104:107], v[160:163], v[192:195], v[104:107]
	v_mfma_f32_16x16x32_bf16 v[92:95], v[152:155], v[200:203], v[92:95]
	v_mfma_f32_16x16x32_bf16 v[88:91], v[160:163], v[200:203], v[88:91]
	v_mfma_f32_16x16x32_bf16 v[76:79], v[152:155], v[208:211], v[76:79]
	v_mfma_f32_16x16x32_bf16 v[72:75], v[160:163], v[208:211], v[72:75]
	v_mfma_f32_16x16x32_bf16 v[124:127], v[156:159], v[188:191], v[124:127]
	v_mfma_f32_16x16x32_bf16 v[120:123], v[164:167], v[188:191], v[120:123]
	v_mfma_f32_16x16x32_bf16 v[108:111], v[156:159], v[196:199], v[108:111]
	v_mfma_f32_16x16x32_bf16 v[104:107], v[164:167], v[196:199], v[104:107]
	v_mfma_f32_16x16x32_bf16 v[92:95], v[156:159], v[204:207], v[92:95]
	v_mfma_f32_16x16x32_bf16 v[88:91], v[164:167], v[204:207], v[88:91]
	v_mfma_f32_16x16x32_bf16 v[76:79], v[156:159], v[216:219], v[76:79]
	v_mfma_f32_16x16x32_bf16 v[72:75], v[164:167], v[216:219], v[72:75]
	s_setprio 0
	s_setprio 1
	v_mfma_f32_16x16x32_bf16 v[116:119], v[168:171], v[184:187], v[116:119]
	v_mfma_f32_16x16x32_bf16 v[112:115], v[176:179], v[184:187], v[112:115]
	v_mfma_f32_16x16x32_bf16 v[100:103], v[168:171], v[192:195], v[100:103]
	v_mfma_f32_16x16x32_bf16 v[96:99], v[176:179], v[192:195], v[96:99]
	v_mfma_f32_16x16x32_bf16 v[84:87], v[168:171], v[200:203], v[84:87]
	v_mfma_f32_16x16x32_bf16 v[80:83], v[176:179], v[200:203], v[80:83]
	v_mfma_f32_16x16x32_bf16 v[68:71], v[168:171], v[208:211], v[68:71]
	v_mfma_f32_16x16x32_bf16 v[64:67], v[176:179], v[208:211], v[64:67]
	v_mfma_f32_16x16x32_bf16 v[116:119], v[172:175], v[188:191], v[116:119]
	v_mfma_f32_16x16x32_bf16 v[112:115], v[180:183], v[188:191], v[112:115]
	v_mfma_f32_16x16x32_bf16 v[100:103], v[172:175], v[196:199], v[100:103]
	v_mfma_f32_16x16x32_bf16 v[96:99], v[180:183], v[196:199], v[96:99]
	v_mfma_f32_16x16x32_bf16 v[84:87], v[172:175], v[204:207], v[84:87]
	v_mfma_f32_16x16x32_bf16 v[80:83], v[180:183], v[204:207], v[80:83]
	v_mfma_f32_16x16x32_bf16 v[68:71], v[172:175], v[216:219], v[68:71]
	v_mfma_f32_16x16x32_bf16 v[64:67], v[180:183], v[216:219], v[64:67]
	s_setprio 0
	s_barrier
	s_add_i32 s35, s18, s2
	v_lshl_add_u64 v[140:141], s[62:63], 0, v[130:131]
	s_mov_b32 m0, s35
	ds_read_b128 v[184:187], v150 offset:16384
	ds_read_b128 v[188:191], v150 offset:17408
	ds_read_b128 v[192:195], v150 offset:18432
	ds_read_b128 v[196:199], v150 offset:19456
	ds_read_b128 v[200:203], v150 offset:20480
	ds_read_b128 v[204:207], v150 offset:21504
	ds_read_b128 v[208:211], v150 offset:22528
	ds_read_b128 v[216:219], v150 offset:23552
	global_load_lds_dwordx4 v[140:141], off
	s_add_i32 m0, s35, 0x2000
	s_add_u32 s66, s62, 0x10000
	v_lshl_add_u64 v[220:221], s[62:63], 0, v[134:135]
	s_addc_u32 s67, s63, 0
	s_add_i32 s35, s19, s2
	global_load_lds_dwordx4 v[220:221], off
	v_lshl_add_u64 v[222:223], s[66:67], 0, v[130:131]
	s_mov_b32 m0, s35
	v_lshl_add_u64 v[224:225], s[64:65], 0, v[132:133]
	global_load_lds_dwordx4 v[222:223], off
	v_lshl_add_u64 v[222:223], s[66:67], 0, v[134:135]
	s_add_i32 m0, s35, 0x2000
	s_nop 0
	global_load_lds_dwordx4 v[222:223], off
	v_lshl_add_u64 v[222:223], s[64:65], 0, v[128:129]
	s_mov_b32 m0, s3
	s_nop 0
	global_load_lds_dwordx4 v[222:223], off
	s_mov_b32 m0, s8
	s_nop 0
	global_load_lds_dwordx4 v[224:225], off
	s_waitcnt vmcnt(8)
	s_waitcnt lgkmcnt(0)
	s_barrier
; #define STAGE(bufoff, gbase) STAGE_(bufoff, gbase, voffA)
; #define LDA(dst, b, h) do { _Pragma("unroll") for (int m = 0; m < 4; ++m) _Pragma("unroll") for (int k = 0; k < 2; ++k) dst[m][k] = *LDSP(const bf16x8, lds + SA(b, h) + aoff + m * 2048 + k * 1024); } while (0)
; #define LDB(dst, b, h) do { _Pragma("unroll") for (int n = 0; n < 2; ++n) _Pragma("unroll") for (int k = 0; k < 2; ++k) dst[n][k] = *LDSP(const bf16x8, lds + SB(b, h) + boff + n * 2048 + k * 1024); } while (0)
; #define MMA(ai, bj, AT, BT) do { __builtin_amdgcn_s_setprio(1); \
;     _Pragma("unroll") for (int m = 0; m < 4; ++m) _Pragma("unroll") for (int n = 0; n < 2; ++n) _Pragma("unroll") for (int k = 0; k < 2; ++k) \
;       acc[ai][bj][m][n] = __builtin_amdgcn_mfma_f32_16x16x32_bf16(BT[n][k], AT[m][k], acc[ai][bj][m][n], 0, 0, 0); \
;     __builtin_amdgcn_s_setprio(0); } while (0)
; #define WAIT_V(n) asm volatile("s_waitcnt vmcnt(" #n ")" ::: "memory")
; #define WAIT_L(n) asm volatile("s_waitcnt lgkmcnt(" #n ")" ::: "memory")
; #define BAR __builtin_amdgcn_s_barrier()
; #define SCHED __builtin_amdgcn_sched_barrier(0)
; #define WAIT_V(n) asm volatile("s_waitcnt vmcnt(" #n ")" ::: "memory")
; #define BAR do { __builtin_amdgcn_sched_barrier(0); __builtin_amdgcn_s_barrier(); asm volatile("" ::: "memory"); __builtin_amdgcn_sched_barrier(0); } while (0)
; template <bool SP2, bool ALIGN_EPI, bool DUAL, class Epi> DI void gemm_phase2(const bf16_t* A, const bf16_t* Bt, const bf16_t* A2, const bf16_t* Bt2, int M, int N, int K, const Epi& E, lds_t* lds) {
;     ...
;         WAIT_V(8); WAIT_L(0); BAR; MMA(1, 0, At, B0); MMA(1, 1, At, B1); BAR; SCHED;
;         LDB(B0, 1, 0); LDB(B1, 1, 1); SCHED; LDA(At, 1, 0); STAGE(SA(0, 1), a2 + hstep);
;         WAIT_V(8); WAIT_L(0); BAR; MMA(0, 0, At, B0); MMA(0, 1, At, B1); BAR; SCHED;
	s_setprio 1
	s_waitcnt lgkmcnt(0)
	v_mfma_f32_16x16x32_bf16 v[60:63], v[152:155], v[184:187], v[60:63]
	v_mfma_f32_16x16x32_bf16 v[56:59], v[160:163], v[184:187], v[56:59]
	v_mfma_f32_16x16x32_bf16 v[44:47], v[152:155], v[192:195], v[44:47]
	v_mfma_f32_16x16x32_bf16 v[40:43], v[160:163], v[192:195], v[40:43]
	v_mfma_f32_16x16x32_bf16 v[28:31], v[152:155], v[200:203], v[28:31]
	v_mfma_f32_16x16x32_bf16 v[24:27], v[160:163], v[200:203], v[24:27]
	v_mfma_f32_16x16x32_bf16 v[12:15], v[152:155], v[208:211], v[12:15]
	v_mfma_f32_16x16x32_bf16 v[8:11], v[160:163], v[208:211], v[8:11]
	v_mfma_f32_16x16x32_bf16 v[60:63], v[156:159], v[188:191], v[60:63]
	v_mfma_f32_16x16x32_bf16 v[56:59], v[164:167], v[188:191], v[56:59]
	v_mfma_f32_16x16x32_bf16 v[44:47], v[156:159], v[196:199], v[44:47]
	v_mfma_f32_16x16x32_bf16 v[40:43], v[164:167], v[196:199], v[40:43]
	v_mfma_f32_16x16x32_bf16 v[28:31], v[156:159], v[204:207], v[28:31]
	v_mfma_f32_16x16x32_bf16 v[24:27], v[164:167], v[204:207], v[24:27]
	v_mfma_f32_16x16x32_bf16 v[12:15], v[156:159], v[216:219], v[12:15]
	v_mfma_f32_16x16x32_bf16 v[8:11], v[164:167], v[216:219], v[8:11]
	s_setprio 0
	s_setprio 1
	v_mfma_f32_16x16x32_bf16 v[52:55], v[168:171], v[184:187], v[52:55]
	v_mfma_f32_16x16x32_bf16 v[48:51], v[176:179], v[184:187], v[48:51]
	v_mfma_f32_16x16x32_bf16 v[36:39], v[168:171], v[192:195], v[36:39]
	v_mfma_f32_16x16x32_bf16 v[32:35], v[176:179], v[192:195], v[32:35]
	v_mfma_f32_16x16x32_bf16 v[20:23], v[168:171], v[200:203], v[20:23]
	v_mfma_f32_16x16x32_bf16 v[16:19], v[176:179], v[200:203], v[16:19]
	v_mfma_f32_16x16x32_bf16 v[4:7], v[168:171], v[208:211], v[4:7]
	v_mfma_f32_16x16x32_bf16 v[0:3], v[176:179], v[208:211], v[0:3]
	v_mfma_f32_16x16x32_bf16 v[52:55], v[172:175], v[188:191], v[52:55]
	v_mfma_f32_16x16x32_bf16 v[48:51], v[180:183], v[188:191], v[48:51]
	v_mfma_f32_16x16x32_bf16 v[36:39], v[172:175], v[196:199], v[36:39]
	v_mfma_f32_16x16x32_bf16 v[32:35], v[180:183], v[196:199], v[32:35]
	v_mfma_f32_16x16x32_bf16 v[20:23], v[172:175], v[204:207], v[20:23]
	v_mfma_f32_16x16x32_bf16 v[16:19], v[180:183], v[204:207], v[16:19]
	v_mfma_f32_16x16x32_bf16 v[4:7], v[172:175], v[216:219], v[4:7]
	v_mfma_f32_16x16x32_bf16 v[0:3], v[180:183], v[216:219], v[0:3]
	s_setprio 0
	s_barrier
	s_add_i32 s35, 0, 0x18000
	s_add_i32 s37, 0, 0x1c000
	v_add_u32_e32 v164, s35, v143
	v_add_u32_e32 v180, s37, v143
	ds_read_b128 v[152:155], v164
	ds_read_b128 v[156:159], v164 offset:1024
	ds_read_b128 v[160:163], v164 offset:2048
	ds_read_b128 v[164:167], v164 offset:3072
	ds_read_b128 v[168:171], v180
	ds_read_b128 v[172:175], v180 offset:1024
	ds_read_b128 v[176:179], v180 offset:2048
	ds_read_b128 v[180:183], v180 offset:3072
	s_add_u32 s64, s64, 0x40000
	s_addc_u32 s65, s65, 0
	s_mov_b32 m0, s9
	v_lshl_add_u64 v[226:227], s[64:65], 0, v[128:129]
	ds_read_b128 v[184:187], v150 offset:32768
	ds_read_b128 v[188:191], v150 offset:33792
	ds_read_b128 v[192:195], v150 offset:34816
	ds_read_b128 v[196:199], v150 offset:35840
	ds_read_b128 v[200:203], v150 offset:36864
	ds_read_b128 v[204:207], v150 offset:37888
	ds_read_b128 v[208:211], v150 offset:38912
	ds_read_b128 v[216:219], v150 offset:39936
	global_load_lds_dwordx4 v[226:227], off
	v_lshl_add_u64 v[226:227], s[64:65], 0, v[132:133]
	s_mov_b32 m0, s10
	s_nop 0
	global_load_lds_dwordx4 v[226:227], off
	s_waitcnt vmcnt(8)
	s_waitcnt lgkmcnt(0)
	s_barrier
	s_setprio 1
	s_waitcnt lgkmcnt(0)
	v_mfma_f32_16x16x32_bf16 v[124:127], v[152:155], v[184:187], v[124:127]
	v_mfma_f32_16x16x32_bf16 v[120:123], v[160:163], v[184:187], v[120:123]
	v_mfma_f32_16x16x32_bf16 v[108:111], v[152:155], v[192:195], v[108:111]
	v_mfma_f32_16x16x32_bf16 v[104:107], v[160:163], v[192:195], v[104:107]
	v_mfma_f32_16x16x32_bf16 v[92:95], v[152:155], v[200:203], v[92:95]
	v_mfma_f32_16x16x32_bf16 v[88:91], v[160:163], v[200:203], v[88:91]
	v_mfma_f32_16x16x32_bf16 v[76:79], v[152:155], v[208:211], v[76:79]
	v_mfma_f32_16x16x32_bf16 v[72:75], v[160:163], v[208:211], v[72:75]
	v_mfma_f32_16x16x32_bf16 v[124:127], v[156:159], v[188:191], v[124:127]
	v_mfma_f32_16x16x32_bf16 v[120:123], v[164:167], v[188:191], v[120:123]
	v_mfma_f32_16x16x32_bf16 v[108:111], v[156:159], v[196:199], v[108:111]
	v_mfma_f32_16x16x32_bf16 v[104:107], v[164:167], v[196:199], v[104:107]
	v_mfma_f32_16x16x32_bf16 v[92:95], v[156:159], v[204:207], v[92:95]
	v_mfma_f32_16x16x32_bf16 v[88:91], v[164:167], v[204:207], v[88:91]
	v_mfma_f32_16x16x32_bf16 v[76:79], v[156:159], v[216:219], v[76:79]
	v_mfma_f32_16x16x32_bf16 v[72:75], v[164:167], v[216:219], v[72:75]
	s_setprio 0
	s_setprio 1
	v_mfma_f32_16x16x32_bf16 v[116:119], v[168:171], v[184:187], v[116:119]
	v_mfma_f32_16x16x32_bf16 v[112:115], v[176:179], v[184:187], v[112:115]
	v_mfma_f32_16x16x32_bf16 v[100:103], v[168:171], v[192:195], v[100:103]
	v_mfma_f32_16x16x32_bf16 v[96:99], v[176:179], v[192:195], v[96:99]
	v_mfma_f32_16x16x32_bf16 v[84:87], v[168:171], v[200:203], v[84:87]
	v_mfma_f32_16x16x32_bf16 v[80:83], v[176:179], v[200:203], v[80:83]
	v_mfma_f32_16x16x32_bf16 v[68:71], v[168:171], v[208:211], v[68:71]
	v_mfma_f32_16x16x32_bf16 v[64:67], v[176:179], v[208:211], v[64:67]
	v_mfma_f32_16x16x32_bf16 v[116:119], v[172:175], v[188:191], v[116:119]
	v_mfma_f32_16x16x32_bf16 v[112:115], v[180:183], v[188:191], v[112:115]
	v_mfma_f32_16x16x32_bf16 v[100:103], v[172:175], v[196:199], v[100:103]
	v_mfma_f32_16x16x32_bf16 v[96:99], v[180:183], v[196:199], v[96:99]
	v_mfma_f32_16x16x32_bf16 v[84:87], v[172:175], v[204:207], v[84:87]
	v_mfma_f32_16x16x32_bf16 v[80:83], v[180:183], v[204:207], v[80:83]
	v_mfma_f32_16x16x32_bf16 v[68:71], v[172:175], v[216:219], v[68:71]
	v_mfma_f32_16x16x32_bf16 v[64:67], v[180:183], v[216:219], v[64:67]
	s_setprio 0
	s_barrier
; #define STAGE(bufoff, gbase) STAGE_(bufoff, gbase, voffA)
; #define STAGEB(bufoff, gbase) STAGE_(bufoff, gbase, voffB)
; #define LDA(dst, b, h) do { _Pragma("unroll") for (int m = 0; m < 4; ++m) _Pragma("unroll") for (int k = 0; k < 2; ++k) dst[m][k] = *LDSP(const bf16x8, lds + SA(b, h) + aoff + m * 2048 + k * 1024); } while (0)
; #define MMA(ai, bj, AT, BT) do { __builtin_amdgcn_s_setprio(1); \
;     _Pragma("unroll") for (int m = 0; m < 4; ++m) _Pragma("unroll") for (int n = 0; n < 2; ++n) _Pragma("unroll") for (int k = 0; k < 2; ++k) \
;       acc[ai][bj][m][n] = __builtin_amdgcn_mfma_f32_16x16x32_bf16(BT[n][k], AT[m][k], acc[ai][bj][m][n], 0, 0, 0); \
;     __builtin_amdgcn_s_setprio(0); } while (0)
; #define WAIT_V(n) asm volatile("s_waitcnt vmcnt(" #n ")" ::: "memory")
; #define WAIT_L(n) asm volatile("s_waitcnt lgkmcnt(" #n ")" ::: "memory")
; #define BAR __builtin_amdgcn_s_barrier()
; #define SCHED __builtin_amdgcn_sched_barrier(0)
; #define WAIT_V(n) asm volatile("s_waitcnt vmcnt(" #n ")" ::: "memory")
; #define BAR do { __builtin_amdgcn_sched_barrier(0); __builtin_amdgcn_s_barrier(); asm volatile("" ::: "memory"); __builtin_amdgcn_sched_barrier(0); } while (0)
; template <bool SP2, bool ALIGN_EPI, bool DUAL, class Epi> DI void gemm_phase2(const bf16_t* A, const bf16_t* Bt, const bf16_t* A2, const bf16_t* Bt2, int M, int N, int K, const Epi& E, lds_t* lds) {
;     ...
;         LDA(At, 1, 1); STAGEB(SB(1, 0), b3); STAGEB(SB(1, 1), b3 + bstep); STAGE(SA(1, 0), a3);
;         WAIT_V(8); WAIT_L(0); BAR; MMA(1, 0, At, B0); MMA(1, 1, At, B1); BAR; SCHED;
;     ...
;     if constexpr (ALIGN_EPI) { if (wr == 0) BAR; }
	s_add_i32 s35, s35, s2
	v_lshl_add_u64 v[140:141], v[140:141], 0, s[30:31]
	s_mov_b32 m0, s35
	ds_read_b128 v[184:187], v150 offset:49152
	ds_read_b128 v[188:191], v150 offset:50176
	ds_read_b128 v[192:195], v150 offset:51200
	ds_read_b128 v[196:199], v150 offset:52224
	ds_read_b128 v[200:203], v150 offset:53248
	ds_read_b128 v[204:207], v150 offset:54272
	ds_read_b128 v[208:211], v150 offset:55296
	ds_read_b128 v[216:219], v150 offset:56320
	global_load_lds_dwordx4 v[140:141], off
	s_add_i32 m0, s35, 0x2000
	s_add_u32 s62, s62, 0x10080
	v_lshl_add_u64 v[140:141], v[220:221], 0, s[30:31]
	s_addc_u32 s63, s63, 0
	s_add_i32 s35, s37, s2
	global_load_lds_dwordx4 v[140:141], off
	v_lshl_add_u64 v[140:141], s[62:63], 0, v[130:131]
	s_mov_b32 m0, s35
	s_nop 0
	global_load_lds_dwordx4 v[140:141], off
	v_lshl_add_u64 v[140:141], s[62:63], 0, v[134:135]
	s_add_i32 m0, s35, 0x2000
	s_nop 0
	global_load_lds_dwordx4 v[140:141], off
	v_lshl_add_u64 v[140:141], v[222:223], 0, s[30:31]
	s_mov_b32 m0, s14
	s_nop 0
	global_load_lds_dwordx4 v[140:141], off
	v_lshl_add_u64 v[140:141], v[224:225], 0, s[30:31]
	s_mov_b32 m0, s15
	s_nop 0
	global_load_lds_dwordx4 v[140:141], off
	s_waitcnt vmcnt(8)
	s_waitcnt lgkmcnt(0)
	s_barrier
	s_setprio 1
	s_waitcnt lgkmcnt(0)
	v_mfma_f32_16x16x32_bf16 v[60:63], v[152:155], v[184:187], v[60:63]
	v_mfma_f32_16x16x32_bf16 v[56:59], v[160:163], v[184:187], v[56:59]
	v_mfma_f32_16x16x32_bf16 v[44:47], v[152:155], v[192:195], v[44:47]
	v_mfma_f32_16x16x32_bf16 v[40:43], v[160:163], v[192:195], v[40:43]
	v_mfma_f32_16x16x32_bf16 v[28:31], v[152:155], v[200:203], v[28:31]
	v_mfma_f32_16x16x32_bf16 v[24:27], v[160:163], v[200:203], v[24:27]
	v_mfma_f32_16x16x32_bf16 v[12:15], v[152:155], v[208:211], v[12:15]
	v_mfma_f32_16x16x32_bf16 v[8:11], v[160:163], v[208:211], v[8:11]
	v_mfma_f32_16x16x32_bf16 v[60:63], v[156:159], v[188:191], v[60:63]
	v_mfma_f32_16x16x32_bf16 v[56:59], v[164:167], v[188:191], v[56:59]
	v_mfma_f32_16x16x32_bf16 v[44:47], v[156:159], v[196:199], v[44:47]
	v_mfma_f32_16x16x32_bf16 v[40:43], v[164:167], v[196:199], v[40:43]
	v_mfma_f32_16x16x32_bf16 v[28:31], v[156:159], v[204:207], v[28:31]
	v_mfma_f32_16x16x32_bf16 v[24:27], v[164:167], v[204:207], v[24:27]
	v_mfma_f32_16x16x32_bf16 v[12:15], v[156:159], v[216:219], v[12:15]
	v_mfma_f32_16x16x32_bf16 v[8:11], v[164:167], v[216:219], v[8:11]
	s_setprio 0
	s_setprio 1
	v_mfma_f32_16x16x32_bf16 v[52:55], v[168:171], v[184:187], v[52:55]
	v_mfma_f32_16x16x32_bf16 v[48:51], v[176:179], v[184:187], v[48:51]
	v_mfma_f32_16x16x32_bf16 v[36:39], v[168:171], v[192:195], v[36:39]
	v_mfma_f32_16x16x32_bf16 v[32:35], v[176:179], v[192:195], v[32:35]
	v_mfma_f32_16x16x32_bf16 v[20:23], v[168:171], v[200:203], v[20:23]
	v_mfma_f32_16x16x32_bf16 v[16:19], v[176:179], v[200:203], v[16:19]
	v_mfma_f32_16x16x32_bf16 v[4:7], v[168:171], v[208:211], v[4:7]
	v_mfma_f32_16x16x32_bf16 v[0:3], v[176:179], v[208:211], v[0:3]
	v_mfma_f32_16x16x32_bf16 v[52:55], v[172:175], v[188:191], v[52:55]
	v_mfma_f32_16x16x32_bf16 v[48:51], v[180:183], v[188:191], v[48:51]
	v_mfma_f32_16x16x32_bf16 v[36:39], v[172:175], v[196:199], v[36:39]
	v_mfma_f32_16x16x32_bf16 v[32:35], v[180:183], v[196:199], v[32:35]
	v_mfma_f32_16x16x32_bf16 v[20:23], v[172:175], v[204:207], v[20:23]
	v_mfma_f32_16x16x32_bf16 v[16:19], v[180:183], v[204:207], v[16:19]
	v_mfma_f32_16x16x32_bf16 v[4:7], v[172:175], v[216:219], v[4:7]
	v_mfma_f32_16x16x32_bf16 v[0:3], v[180:183], v[216:219], v[0:3]
	s_setprio 0
	s_add_i32 s34, s34, 2
	s_add_u32 s60, s60, 0x100
	s_addc_u32 s61, s61, 0
	s_add_u32 s23, s23, 0x100
	s_addc_u32 s33, s33, 0
	s_cmp_gt_u32 s34, 13
	s_barrier
	s_cbranch_scc0 .LBB0_551
	s_and_b64 vcc, exec, s[38:39]
	s_cbranch_vccz .LBB0_554
	s_barrier

; #define STAGE(bufoff, gbase) STAGE_(bufoff, gbase, voffA)
; #define STAGEB(bufoff, gbase) STAGE_(bufoff, gbase, voffB)
; #define LDA(dst, b, h) do { _Pragma("unroll") for (int m = 0; m < 4; ++m) _Pragma("unroll") for (int k = 0; k < 2; ++k) dst[m][k] = *LDSP(const bf16x8, lds + SA(b, h) + aoff + m * 2048 + k * 1024); } while (0)
; #define LDB(dst, b, h) do { _Pragma("unroll") for (int n = 0; n < 2; ++n) _Pragma("unroll") for (int k = 0; k < 2; ++k) dst[n][k] = *LDSP(const bf16x8, lds + SB(b, h) + boff + n * 2048 + k * 1024); } while (0)
; #define MMA(ai, bj, AT, BT) do { __builtin_amdgcn_s_setprio(1); \
;     _Pragma("unroll") for (int m = 0; m < 4; ++m) _Pragma("unroll") for (int n = 0; n < 2; ++n) _Pragma("unroll") for (int k = 0; k < 2; ++k) \
;       acc[ai][bj][m][n] = __builtin_amdgcn_mfma_f32_16x16x32_bf16(BT[n][k], AT[m][k], acc[ai][bj][m][n], 0, 0, 0); \
;     __builtin_amdgcn_s_setprio(0); } while (0)
; #define WAIT_V(n) asm volatile("s_waitcnt vmcnt(" #n ")" ::: "memory")
; #define WAIT_L(n) asm volatile("s_waitcnt lgkmcnt(" #n ")" ::: "memory")
; #define BAR __builtin_amdgcn_s_barrier()
; #define SCHED __builtin_amdgcn_sched_barrier(0)
; #define WAIT_V(n) asm volatile("s_waitcnt vmcnt(" #n ")" ::: "memory")
; #define BAR do { __builtin_amdgcn_sched_barrier(0); __builtin_amdgcn_s_barrier(); asm volatile("" ::: "memory"); __builtin_amdgcn_sched_barrier(0); } while (0)
; template <bool SP2, bool ALIGN_EPI, bool DUAL, class Epi> DI void gemm_phase2(const bf16_t* A, const bf16_t* Bt, const bf16_t* A2, const bf16_t* Bt2, int M, int N, int K, const Epi& E, lds_t* lds) {
;     ...
;     for (int t = 0; t < nt; t += 2) {
;       const bool last = (t == nt - 2);
;       const char* a1 = cA + (size_t)(t + 1) * kstep;
;       const char* a2 = last ? nA : cA + (size_t)(t + 2) * kstep; const char* b2 = last ? nB : cB + (size_t)(t + 2) * kstep;
;       const char* a3 = a2 + kstep; const char* b3 = b2 + kstep;
;       if constexpr (SP2) {
;         LDB(B0, 0, 0); LDB(B1, 0, 1); SCHED; LDA(At, 0, 0); STAGE(SA(1, 1), a1 + hstep);
;         WAIT_V(8); WAIT_L(0); BAR; MMA(0, 0, At, B0); MMA(0, 1, At, B1); BAR; SCHED;
;         LDA(At, 0, 1); STAGEB(SB(0, 0), b2); STAGEB(SB(0, 1), b2 + bstep); STAGE(SA(0, 0), a2);
.LBB0_620:
	ds_read_b128 v[150:153], v146
	ds_read_b128 v[154:157], v146 offset:1024
	ds_read_b128 v[158:161], v146 offset:2048
	ds_read_b128 v[162:165], v146 offset:3072
	ds_read_b128 v[166:169], v147
	ds_read_b128 v[170:173], v147 offset:1024
	ds_read_b128 v[174:177], v147 offset:2048
	ds_read_b128 v[178:181], v147 offset:3072
	s_add_u32 s47, s52, 0xfffc0080
	s_addc_u32 s54, s53, -1
	s_cmp_eq_u32 s37, 12
	s_cselect_b32 s57, s1, s54
	s_cselect_b32 s56, s23, s47
	s_cselect_b32 s55, s29, s35
	s_cselect_b32 s54, s33, s34
	v_lshl_add_u64 v[210:211], s[52:53], 0, v[136:137]
	s_add_i32 m0, s3, 0xc000
	ds_read_b128 v[182:185], v148
	ds_read_b128 v[186:189], v148 offset:1024
	ds_read_b128 v[190:193], v148 offset:2048
	ds_read_b128 v[194:197], v148 offset:3072
	ds_read_b128 v[198:201], v148 offset:4096
	ds_read_b128 v[202:205], v148 offset:5120
	ds_read_b128 v[206:209], v148 offset:6144
	ds_read_b128 v[216:219], v148 offset:7168
	global_load_lds_dwordx4 v[210:211], off
	v_lshl_add_u64 v[210:211], s[52:53], 0, v[138:139]
	s_add_i32 m0, s3, 0xe000
	s_nop 0
	global_load_lds_dwordx4 v[210:211], off
	s_waitcnt vmcnt(8)
	s_waitcnt lgkmcnt(0)
	s_barrier
	s_setprio 1
	s_waitcnt lgkmcnt(0)
	v_mfma_f32_16x16x32_bf16 v[124:127], v[150:153], v[182:185], v[124:127]
	v_mfma_f32_16x16x32_bf16 v[120:123], v[158:161], v[182:185], v[120:123]
	v_mfma_f32_16x16x32_bf16 v[108:111], v[150:153], v[190:193], v[108:111]
	v_mfma_f32_16x16x32_bf16 v[104:107], v[158:161], v[190:193], v[104:107]
	v_mfma_f32_16x16x32_bf16 v[92:95], v[150:153], v[198:201], v[92:95]
	v_mfma_f32_16x16x32_bf16 v[88:91], v[158:161], v[198:201], v[88:91]
	v_mfma_f32_16x16x32_bf16 v[76:79], v[150:153], v[206:209], v[76:79]
	v_mfma_f32_16x16x32_bf16 v[72:75], v[158:161], v[206:209], v[72:75]
	v_mfma_f32_16x16x32_bf16 v[124:127], v[154:157], v[186:189], v[124:127]
	v_mfma_f32_16x16x32_bf16 v[120:123], v[162:165], v[186:189], v[120:123]
	v_mfma_f32_16x16x32_bf16 v[108:111], v[154:157], v[194:197], v[108:111]
	v_mfma_f32_16x16x32_bf16 v[104:107], v[162:165], v[194:197], v[104:107]
	v_mfma_f32_16x16x32_bf16 v[92:95], v[154:157], v[202:205], v[92:95]
	v_mfma_f32_16x16x32_bf16 v[88:91], v[162:165], v[202:205], v[88:91]
	v_mfma_f32_16x16x32_bf16 v[76:79], v[154:157], v[216:219], v[76:79]
	v_mfma_f32_16x16x32_bf16 v[72:75], v[162:165], v[216:219], v[72:75]
	s_setprio 0
	s_setprio 1
	v_mfma_f32_16x16x32_bf16 v[116:119], v[166:169], v[182:185], v[116:119]
	v_mfma_f32_16x16x32_bf16 v[112:115], v[174:177], v[182:185], v[112:115]
	v_mfma_f32_16x16x32_bf16 v[100:103], v[166:169], v[190:193], v[100:103]
	v_mfma_f32_16x16x32_bf16 v[96:99], v[174:177], v[190:193], v[96:99]
	v_mfma_f32_16x16x32_bf16 v[84:87], v[166:169], v[198:201], v[84:87]
	v_mfma_f32_16x16x32_bf16 v[80:83], v[174:177], v[198:201], v[80:83]
	v_mfma_f32_16x16x32_bf16 v[68:71], v[166:169], v[206:209], v[68:71]
	v_mfma_f32_16x16x32_bf16 v[64:67], v[174:177], v[206:209], v[64:67]
	v_mfma_f32_16x16x32_bf16 v[116:119], v[170:173], v[186:189], v[116:119]
	v_mfma_f32_16x16x32_bf16 v[112:115], v[178:181], v[186:189], v[112:115]
	v_mfma_f32_16x16x32_bf16 v[100:103], v[170:173], v[194:197], v[100:103]
	v_mfma_f32_16x16x32_bf16 v[96:99], v[178:181], v[194:197], v[96:99]
	v_mfma_f32_16x16x32_bf16 v[84:87], v[170:173], v[202:205], v[84:87]
	v_mfma_f32_16x16x32_bf16 v[80:83], v[178:181], v[202:205], v[80:83]
	v_mfma_f32_16x16x32_bf16 v[68:71], v[170:173], v[216:219], v[68:71]
	v_mfma_f32_16x16x32_bf16 v[64:67], v[178:181], v[216:219], v[64:67]
	s_setprio 0
	s_barrier
	s_add_i32 s47, s19, s2
	v_lshl_add_u64 v[210:211], s[54:55], 0, v[132:133]
	s_mov_b32 m0, s47
	ds_read_b128 v[182:185], v148 offset:16384
	ds_read_b128 v[186:189], v148 offset:17408
	ds_read_b128 v[190:193], v148 offset:18432
	ds_read_b128 v[194:197], v148 offset:19456
	ds_read_b128 v[198:201], v148 offset:20480
	ds_read_b128 v[202:205], v148 offset:21504
	ds_read_b128 v[206:209], v148 offset:22528
	ds_read_b128 v[216:219], v148 offset:23552
	global_load_lds_dwordx4 v[210:211], off
	s_add_i32 m0, s47, 0x2000
	s_add_u32 s58, s54, 0x10000
	v_lshl_add_u64 v[220:221], s[54:55], 0, v[128:129]
	s_addc_u32 s59, s55, 0
	s_add_i32 s47, s20, s2
	global_load_lds_dwordx4 v[220:221], off
	v_lshl_add_u64 v[222:223], s[58:59], 0, v[132:133]
	s_mov_b32 m0, s47
	v_lshl_add_u64 v[224:225], s[56:57], 0, v[130:131]
	global_load_lds_dwordx4 v[222:223], off
	v_lshl_add_u64 v[222:223], s[58:59], 0, v[128:129]
	s_add_i32 m0, s47, 0x2000
	s_nop 0
	global_load_lds_dwordx4 v[222:223], off
	v_lshl_add_u64 v[222:223], s[56:57], 0, v[134:135]
	s_mov_b32 m0, s3
	s_nop 0
	global_load_lds_dwordx4 v[222:223], off
	s_mov_b32 m0, s8
	s_nop 0
	global_load_lds_dwordx4 v[224:225], off
	s_waitcnt vmcnt(8)
	s_waitcnt lgkmcnt(0)
	s_barrier
; #define STAGE(bufoff, gbase) STAGE_(bufoff, gbase, voffA)
; #define LDA(dst, b, h) do { _Pragma("unroll") for (int m = 0; m < 4; ++m) _Pragma("unroll") for (int k = 0; k < 2; ++k) dst[m][k] = *LDSP(const bf16x8, lds + SA(b, h) + aoff + m * 2048 + k * 1024); } while (0)
; #define LDB(dst, b, h) do { _Pragma("unroll") for (int n = 0; n < 2; ++n) _Pragma("unroll") for (int k = 0; k < 2; ++k) dst[n][k] = *LDSP(const bf16x8, lds + SB(b, h) + boff + n * 2048 + k * 1024); } while (0)
; #define MMA(ai, bj, AT, BT) do { __builtin_amdgcn_s_setprio(1); \
;     _Pragma("unroll") for (int m = 0; m < 4; ++m) _Pragma("unroll") for (int n = 0; n < 2; ++n) _Pragma("unroll") for (int k = 0; k < 2; ++k) \
;       acc[ai][bj][m][n] = __builtin_amdgcn_mfma_f32_16x16x32_bf16(BT[n][k], AT[m][k], acc[ai][bj][m][n], 0, 0, 0); \
;     __builtin_amdgcn_s_setprio(0); } while (0)
; #define WAIT_V(n) asm volatile("s_waitcnt vmcnt(" #n ")" ::: "memory")
; #define WAIT_L(n) asm volatile("s_waitcnt lgkmcnt(" #n ")" ::: "memory")
; #define BAR __builtin_amdgcn_s_barrier()
; #define SCHED __builtin_amdgcn_sched_barrier(0)
; #define WAIT_V(n) asm volatile("s_waitcnt vmcnt(" #n ")" ::: "memory")
; #define BAR do { __builtin_amdgcn_sched_barrier(0); __builtin_amdgcn_s_barrier(); asm volatile("" ::: "memory"); __builtin_amdgcn_sched_barrier(0); } while (0)
; template <bool SP2, bool ALIGN_EPI, bool DUAL, class Epi> DI void gemm_phase2(const bf16_t* A, const bf16_t* Bt, const bf16_t* A2, const bf16_t* Bt2, int M, int N, int K, const Epi& E, lds_t* lds) {
;     ...
;         WAIT_V(8); WAIT_L(0); BAR; MMA(1, 0, At, B0); MMA(1, 1, At, B1); BAR; SCHED;
;         LDB(B0, 1, 0); LDB(B1, 1, 1); SCHED; LDA(At, 1, 0); STAGE(SA(0, 1), a2 + hstep);
;         WAIT_V(8); WAIT_L(0); BAR; MMA(0, 0, At, B0); MMA(0, 1, At, B1); BAR; SCHED;
	s_setprio 1
	s_waitcnt lgkmcnt(0)
	v_mfma_f32_16x16x32_bf16 v[60:63], v[150:153], v[182:185], v[60:63]
	v_mfma_f32_16x16x32_bf16 v[56:59], v[158:161], v[182:185], v[56:59]
	v_mfma_f32_16x16x32_bf16 v[44:47], v[150:153], v[190:193], v[44:47]
	v_mfma_f32_16x16x32_bf16 v[40:43], v[158:161], v[190:193], v[40:43]
	v_mfma_f32_16x16x32_bf16 v[28:31], v[150:153], v[198:201], v[28:31]
	v_mfma_f32_16x16x32_bf16 v[24:27], v[158:161], v[198:201], v[24:27]
	v_mfma_f32_16x16x32_bf16 v[12:15], v[150:153], v[206:209], v[12:15]
	v_mfma_f32_16x16x32_bf16 v[8:11], v[158:161], v[206:209], v[8:11]
	v_mfma_f32_16x16x32_bf16 v[60:63], v[154:157], v[186:189], v[60:63]
	v_mfma_f32_16x16x32_bf16 v[56:59], v[162:165], v[186:189], v[56:59]
	v_mfma_f32_16x16x32_bf16 v[44:47], v[154:157], v[194:197], v[44:47]
	v_mfma_f32_16x16x32_bf16 v[40:43], v[162:165], v[194:197], v[40:43]
	v_mfma_f32_16x16x32_bf16 v[28:31], v[154:157], v[202:205], v[28:31]
	v_mfma_f32_16x16x32_bf16 v[24:27], v[162:165], v[202:205], v[24:27]
	v_mfma_f32_16x16x32_bf16 v[12:15], v[154:157], v[216:219], v[12:15]
	v_mfma_f32_16x16x32_bf16 v[8:11], v[162:165], v[216:219], v[8:11]
	s_setprio 0
	s_setprio 1
	v_mfma_f32_16x16x32_bf16 v[52:55], v[166:169], v[182:185], v[52:55]
	v_mfma_f32_16x16x32_bf16 v[48:51], v[174:177], v[182:185], v[48:51]
	v_mfma_f32_16x16x32_bf16 v[36:39], v[166:169], v[190:193], v[36:39]
	v_mfma_f32_16x16x32_bf16 v[32:35], v[174:177], v[190:193], v[32:35]
	v_mfma_f32_16x16x32_bf16 v[20:23], v[166:169], v[198:201], v[20:23]
	v_mfma_f32_16x16x32_bf16 v[16:19], v[174:177], v[198:201], v[16:19]
	v_mfma_f32_16x16x32_bf16 v[4:7], v[166:169], v[206:209], v[4:7]
	v_mfma_f32_16x16x32_bf16 v[0:3], v[174:177], v[206:209], v[0:3]
	v_mfma_f32_16x16x32_bf16 v[52:55], v[170:173], v[186:189], v[52:55]
	v_mfma_f32_16x16x32_bf16 v[48:51], v[178:181], v[186:189], v[48:51]
	v_mfma_f32_16x16x32_bf16 v[36:39], v[170:173], v[194:197], v[36:39]
	v_mfma_f32_16x16x32_bf16 v[32:35], v[178:181], v[194:197], v[32:35]
	v_mfma_f32_16x16x32_bf16 v[20:23], v[170:173], v[202:205], v[20:23]
	v_mfma_f32_16x16x32_bf16 v[16:19], v[178:181], v[202:205], v[16:19]
	v_mfma_f32_16x16x32_bf16 v[4:7], v[170:173], v[216:219], v[4:7]
	v_mfma_f32_16x16x32_bf16 v[0:3], v[178:181], v[216:219], v[0:3]
	s_setprio 0
	s_barrier
	s_add_i32 s47, 0, 0x18000
	s_add_i32 s58, 0, 0x1c000
	v_add_u32_e32 v162, s47, v141
	v_add_u32_e32 v178, s58, v141
	ds_read_b128 v[150:153], v162
	ds_read_b128 v[154:157], v162 offset:1024
	ds_read_b128 v[158:161], v162 offset:2048
	ds_read_b128 v[162:165], v162 offset:3072
	ds_read_b128 v[166:169], v178
	ds_read_b128 v[170:173], v178 offset:1024
	ds_read_b128 v[174:177], v178 offset:2048
	ds_read_b128 v[178:181], v178 offset:3072
	s_add_u32 s56, s56, 0x40000
	s_addc_u32 s57, s57, 0
	s_mov_b32 m0, s9
	v_lshl_add_u64 v[226:227], s[56:57], 0, v[134:135]
	ds_read_b128 v[182:185], v148 offset:32768
	ds_read_b128 v[186:189], v148 offset:33792
	ds_read_b128 v[190:193], v148 offset:34816
	ds_read_b128 v[194:197], v148 offset:35840
	ds_read_b128 v[198:201], v148 offset:36864
	ds_read_b128 v[202:205], v148 offset:37888
	ds_read_b128 v[206:209], v148 offset:38912
	ds_read_b128 v[216:219], v148 offset:39936
	global_load_lds_dwordx4 v[226:227], off
	v_lshl_add_u64 v[226:227], s[56:57], 0, v[130:131]
	s_mov_b32 m0, s10
	s_nop 0
	global_load_lds_dwordx4 v[226:227], off
	s_waitcnt vmcnt(8)
	s_waitcnt lgkmcnt(0)
	s_barrier
	s_setprio 1
	s_waitcnt lgkmcnt(0)
	v_mfma_f32_16x16x32_bf16 v[124:127], v[150:153], v[182:185], v[124:127]
	v_mfma_f32_16x16x32_bf16 v[120:123], v[158:161], v[182:185], v[120:123]
	v_mfma_f32_16x16x32_bf16 v[108:111], v[150:153], v[190:193], v[108:111]
	v_mfma_f32_16x16x32_bf16 v[104:107], v[158:161], v[190:193], v[104:107]
	v_mfma_f32_16x16x32_bf16 v[92:95], v[150:153], v[198:201], v[92:95]
	v_mfma_f32_16x16x32_bf16 v[88:91], v[158:161], v[198:201], v[88:91]
	v_mfma_f32_16x16x32_bf16 v[76:79], v[150:153], v[206:209], v[76:79]
	v_mfma_f32_16x16x32_bf16 v[72:75], v[158:161], v[206:209], v[72:75]
	v_mfma_f32_16x16x32_bf16 v[124:127], v[154:157], v[186:189], v[124:127]
	v_mfma_f32_16x16x32_bf16 v[120:123], v[162:165], v[186:189], v[120:123]
	v_mfma_f32_16x16x32_bf16 v[108:111], v[154:157], v[194:197], v[108:111]
	v_mfma_f32_16x16x32_bf16 v[104:107], v[162:165], v[194:197], v[104:107]
	v_mfma_f32_16x16x32_bf16 v[92:95], v[154:157], v[202:205], v[92:95]
	v_mfma_f32_16x16x32_bf16 v[88:91], v[162:165], v[202:205], v[88:91]
	v_mfma_f32_16x16x32_bf16 v[76:79], v[154:157], v[216:219], v[76:79]
	v_mfma_f32_16x16x32_bf16 v[72:75], v[162:165], v[216:219], v[72:75]
	s_setprio 0
	s_setprio 1
	v_mfma_f32_16x16x32_bf16 v[116:119], v[166:169], v[182:185], v[116:119]
	v_mfma_f32_16x16x32_bf16 v[112:115], v[174:177], v[182:185], v[112:115]
	v_mfma_f32_16x16x32_bf16 v[100:103], v[166:169], v[190:193], v[100:103]
	v_mfma_f32_16x16x32_bf16 v[96:99], v[174:177], v[190:193], v[96:99]
	v_mfma_f32_16x16x32_bf16 v[84:87], v[166:169], v[198:201], v[84:87]
	v_mfma_f32_16x16x32_bf16 v[80:83], v[174:177], v[198:201], v[80:83]
	v_mfma_f32_16x16x32_bf16 v[68:71], v[166:169], v[206:209], v[68:71]
	v_mfma_f32_16x16x32_bf16 v[64:67], v[174:177], v[206:209], v[64:67]
	v_mfma_f32_16x16x32_bf16 v[116:119], v[170:173], v[186:189], v[116:119]
	v_mfma_f32_16x16x32_bf16 v[112:115], v[178:181], v[186:189], v[112:115]
	v_mfma_f32_16x16x32_bf16 v[100:103], v[170:173], v[194:197], v[100:103]
	v_mfma_f32_16x16x32_bf16 v[96:99], v[178:181], v[194:197], v[96:99]
	v_mfma_f32_16x16x32_bf16 v[84:87], v[170:173], v[202:205], v[84:87]
	v_mfma_f32_16x16x32_bf16 v[80:83], v[178:181], v[202:205], v[80:83]
	v_mfma_f32_16x16x32_bf16 v[68:71], v[170:173], v[216:219], v[68:71]
	v_mfma_f32_16x16x32_bf16 v[64:67], v[178:181], v[216:219], v[64:67]
	s_setprio 0
	s_barrier
; #define STAGE(bufoff, gbase) STAGE_(bufoff, gbase, voffA)
; #define STAGEB(bufoff, gbase) STAGE_(bufoff, gbase, voffB)
; #define LDA(dst, b, h) do { _Pragma("unroll") for (int m = 0; m < 4; ++m) _Pragma("unroll") for (int k = 0; k < 2; ++k) dst[m][k] = *LDSP(const bf16x8, lds + SA(b, h) + aoff + m * 2048 + k * 1024); } while (0)
; #define MMA(ai, bj, AT, BT) do { __builtin_amdgcn_s_setprio(1); \
;     _Pragma("unroll") for (int m = 0; m < 4; ++m) _Pragma("unroll") for (int n = 0; n < 2; ++n) _Pragma("unroll") for (int k = 0; k < 2; ++k) \
;       acc[ai][bj][m][n] = __builtin_amdgcn_mfma_f32_16x16x32_bf16(BT[n][k], AT[m][k], acc[ai][bj][m][n], 0, 0, 0); \
;     __builtin_amdgcn_s_setprio(0); } while (0)
; #define WAIT_V(n) asm volatile("s_waitcnt vmcnt(" #n ")" ::: "memory")
; #define WAIT_L(n) asm volatile("s_waitcnt lgkmcnt(" #n ")" ::: "memory")
; #define BAR __builtin_amdgcn_s_barrier()
; #define SCHED __builtin_amdgcn_sched_barrier(0)
; #define WAIT_V(n) asm volatile("s_waitcnt vmcnt(" #n ")" ::: "memory")
; #define BAR do { __builtin_amdgcn_sched_barrier(0); __builtin_amdgcn_s_barrier(); asm volatile("" ::: "memory"); __builtin_amdgcn_sched_barrier(0); } while (0)
; template <bool SP2, bool ALIGN_EPI, bool DUAL, class Epi> DI void gemm_phase2(const bf16_t* A, const bf16_t* Bt, const bf16_t* A2, const bf16_t* Bt2, int M, int N, int K, const Epi& E, lds_t* lds) {
;     ...
;         LDA(At, 1, 1); STAGEB(SB(1, 0), b3); STAGEB(SB(1, 1), b3 + bstep); STAGE(SA(1, 0), a3);
;         WAIT_V(8); WAIT_L(0); BAR; MMA(1, 0, At, B0); MMA(1, 1, At, B1); BAR; SCHED;
;     ...
;     if constexpr (ALIGN_EPI) { if (wr == 0) BAR; }
	s_add_i32 s47, s47, s2
	v_lshl_add_u64 v[210:211], v[210:211], 0, s[16:17]
	s_mov_b32 m0, s47
	ds_read_b128 v[182:185], v148 offset:49152
	ds_read_b128 v[186:189], v148 offset:50176
	ds_read_b128 v[190:193], v148 offset:51200
	ds_read_b128 v[194:197], v148 offset:52224
	ds_read_b128 v[198:201], v148 offset:53248
	ds_read_b128 v[202:205], v148 offset:54272
	ds_read_b128 v[206:209], v148 offset:55296
	ds_read_b128 v[216:219], v148 offset:56320
	global_load_lds_dwordx4 v[210:211], off
	s_add_i32 m0, s47, 0x2000
	s_add_u32 s54, s54, 0x10080
	v_lshl_add_u64 v[210:211], v[220:221], 0, s[16:17]
	s_addc_u32 s55, s55, 0
	s_add_i32 s47, s58, s2
	global_load_lds_dwordx4 v[210:211], off
	v_lshl_add_u64 v[210:211], s[54:55], 0, v[132:133]
	s_mov_b32 m0, s47
	s_nop 0
	global_load_lds_dwordx4 v[210:211], off
	v_lshl_add_u64 v[210:211], s[54:55], 0, v[128:129]
	s_add_i32 m0, s47, 0x2000
	s_nop 0
	global_load_lds_dwordx4 v[210:211], off
	v_lshl_add_u64 v[210:211], v[222:223], 0, s[16:17]
	s_mov_b32 m0, s15
	s_nop 0
	global_load_lds_dwordx4 v[210:211], off
	v_lshl_add_u64 v[210:211], v[224:225], 0, s[16:17]
	s_mov_b32 m0, s18
	s_nop 0
	global_load_lds_dwordx4 v[210:211], off
	s_waitcnt vmcnt(8)
	s_waitcnt lgkmcnt(0)
	s_barrier
	s_setprio 1
	s_waitcnt lgkmcnt(0)
	v_mfma_f32_16x16x32_bf16 v[60:63], v[150:153], v[182:185], v[60:63]
	v_mfma_f32_16x16x32_bf16 v[56:59], v[158:161], v[182:185], v[56:59]
	v_mfma_f32_16x16x32_bf16 v[44:47], v[150:153], v[190:193], v[44:47]
	v_mfma_f32_16x16x32_bf16 v[40:43], v[158:161], v[190:193], v[40:43]
	v_mfma_f32_16x16x32_bf16 v[28:31], v[150:153], v[198:201], v[28:31]
	v_mfma_f32_16x16x32_bf16 v[24:27], v[158:161], v[198:201], v[24:27]
	v_mfma_f32_16x16x32_bf16 v[12:15], v[150:153], v[206:209], v[12:15]
	v_mfma_f32_16x16x32_bf16 v[8:11], v[158:161], v[206:209], v[8:11]
	v_mfma_f32_16x16x32_bf16 v[60:63], v[154:157], v[186:189], v[60:63]
	v_mfma_f32_16x16x32_bf16 v[56:59], v[162:165], v[186:189], v[56:59]
	v_mfma_f32_16x16x32_bf16 v[44:47], v[154:157], v[194:197], v[44:47]
	v_mfma_f32_16x16x32_bf16 v[40:43], v[162:165], v[194:197], v[40:43]
	v_mfma_f32_16x16x32_bf16 v[28:31], v[154:157], v[202:205], v[28:31]
	v_mfma_f32_16x16x32_bf16 v[24:27], v[162:165], v[202:205], v[24:27]
	v_mfma_f32_16x16x32_bf16 v[12:15], v[154:157], v[216:219], v[12:15]
	v_mfma_f32_16x16x32_bf16 v[8:11], v[162:165], v[216:219], v[8:11]
	s_setprio 0
	s_setprio 1
	v_mfma_f32_16x16x32_bf16 v[52:55], v[166:169], v[182:185], v[52:55]
	v_mfma_f32_16x16x32_bf16 v[48:51], v[174:177], v[182:185], v[48:51]
	v_mfma_f32_16x16x32_bf16 v[36:39], v[166:169], v[190:193], v[36:39]
	v_mfma_f32_16x16x32_bf16 v[32:35], v[174:177], v[190:193], v[32:35]
	v_mfma_f32_16x16x32_bf16 v[20:23], v[166:169], v[198:201], v[20:23]
	v_mfma_f32_16x16x32_bf16 v[16:19], v[174:177], v[198:201], v[16:19]
	v_mfma_f32_16x16x32_bf16 v[4:7], v[166:169], v[206:209], v[4:7]
	v_mfma_f32_16x16x32_bf16 v[0:3], v[174:177], v[206:209], v[0:3]
	v_mfma_f32_16x16x32_bf16 v[52:55], v[170:173], v[186:189], v[52:55]
	v_mfma_f32_16x16x32_bf16 v[48:51], v[178:181], v[186:189], v[48:51]
	v_mfma_f32_16x16x32_bf16 v[36:39], v[170:173], v[194:197], v[36:39]
	v_mfma_f32_16x16x32_bf16 v[32:35], v[178:181], v[194:197], v[32:35]
	v_mfma_f32_16x16x32_bf16 v[20:23], v[170:173], v[202:205], v[20:23]
	v_mfma_f32_16x16x32_bf16 v[16:19], v[178:181], v[202:205], v[16:19]
	v_mfma_f32_16x16x32_bf16 v[4:7], v[170:173], v[216:219], v[4:7]
	v_mfma_f32_16x16x32_bf16 v[0:3], v[178:181], v[216:219], v[0:3]
	s_setprio 0
	s_add_i32 s37, s37, 2
	s_add_u32 s52, s52, 0x100
	s_addc_u32 s53, s53, 0
	s_add_u32 s34, s34, 0x100
	s_addc_u32 s35, s35, 0
	s_cmp_gt_u32 s37, 13
	s_barrier
	s_cbranch_scc0 .LBB0_620
	s_and_b64 vcc, exec, s[30:31]
	s_cbranch_vccz .LBB0_623
	s_barrier

; #define STAGE(bufoff, gbase) STAGE_(bufoff, gbase, voffA)
; #define STAGEB(bufoff, gbase) STAGE_(bufoff, gbase, voffB)
; #define LDA(dst, b, h) do { _Pragma("unroll") for (int m = 0; m < 4; ++m) _Pragma("unroll") for (int k = 0; k < 2; ++k) dst[m][k] = *LDSP(const bf16x8, lds + SA(b, h) + aoff + m * 2048 + k * 1024); } while (0)
; #define LDB(dst, b, h) do { _Pragma("unroll") for (int n = 0; n < 2; ++n) _Pragma("unroll") for (int k = 0; k < 2; ++k) dst[n][k] = *LDSP(const bf16x8, lds + SB(b, h) + boff + n * 2048 + k * 1024); } while (0)
; #define MMA(ai, bj, AT, BT) do { __builtin_amdgcn_s_setprio(1); \
;     _Pragma("unroll") for (int m = 0; m < 4; ++m) _Pragma("unroll") for (int n = 0; n < 2; ++n) _Pragma("unroll") for (int k = 0; k < 2; ++k) \
;       acc[ai][bj][m][n] = __builtin_amdgcn_mfma_f32_16x16x32_bf16(BT[n][k], AT[m][k], acc[ai][bj][m][n], 0, 0, 0); \
;     __builtin_amdgcn_s_setprio(0); } while (0)
; #define WAIT_V(n) asm volatile("s_waitcnt vmcnt(" #n ")" ::: "memory")
; #define WAIT_L(n) asm volatile("s_waitcnt lgkmcnt(" #n ")" ::: "memory")
; #define BAR __builtin_amdgcn_s_barrier()
; #define SCHED __builtin_amdgcn_sched_barrier(0)
; #define WAIT_V(n) asm volatile("s_waitcnt vmcnt(" #n ")" ::: "memory")
; #define BAR do { __builtin_amdgcn_sched_barrier(0); __builtin_amdgcn_s_barrier(); asm volatile("" ::: "memory"); __builtin_amdgcn_sched_barrier(0); } while (0)
; template <bool SP2, bool ALIGN_EPI, bool DUAL, class Epi> DI void gemm_phase2(const bf16_t* A, const bf16_t* Bt, const bf16_t* A2, const bf16_t* Bt2, int M, int N, int K, const Epi& E, lds_t* lds) {
;     ...
;     for (int t = 0; t < nt; t += 2) {
;       const bool last = (t == nt - 2);
;       const char* a1 = cA + (size_t)(t + 1) * kstep;
;       const char* a2 = last ? nA : cA + (size_t)(t + 2) * kstep; const char* b2 = last ? nB : cB + (size_t)(t + 2) * kstep;
;       const char* a3 = a2 + kstep; const char* b3 = b2 + kstep;
;       if constexpr (SP2) {
;         LDB(B0, 0, 0); LDB(B1, 0, 1); SCHED; LDA(At, 0, 0); STAGE(SA(1, 1), a1 + hstep);
;         WAIT_V(8); WAIT_L(0); BAR; MMA(0, 0, At, B0); MMA(0, 1, At, B1); BAR; SCHED;
;         LDA(At, 0, 1); STAGEB(SB(0, 0), b2); STAGEB(SB(0, 1), b2 + bstep); STAGE(SA(0, 0), a2);
.LBB0_691:
	ds_read_b128 v[152:155], v148
	ds_read_b128 v[156:159], v148 offset:1024
	ds_read_b128 v[160:163], v148 offset:2048
	ds_read_b128 v[164:167], v148 offset:3072
	ds_read_b128 v[168:171], v149
	ds_read_b128 v[172:175], v149 offset:1024
	ds_read_b128 v[176:179], v149 offset:2048
	ds_read_b128 v[180:183], v149 offset:3072
	s_add_u32 s34, s52, 0xfffc0080
	s_addc_u32 s35, s53, -1
	s_cmp_eq_u32 s33, 12
	s_cselect_b32 s57, s0, s35
	s_cselect_b32 s56, s1, s34
	s_cselect_b32 s55, s21, s31
	s_cselect_b32 s54, s22, s23
	v_lshl_add_u64 v[140:141], s[52:53], 0, v[136:137]
	s_add_i32 m0, s3, 0xc000
	ds_read_b128 v[184:187], v150
	ds_read_b128 v[188:191], v150 offset:1024
	ds_read_b128 v[192:195], v150 offset:2048
	ds_read_b128 v[196:199], v150 offset:3072
	ds_read_b128 v[200:203], v150 offset:4096
	ds_read_b128 v[204:207], v150 offset:5120
	ds_read_b128 v[208:211], v150 offset:6144
	ds_read_b128 v[216:219], v150 offset:7168
	global_load_lds_dwordx4 v[140:141], off
	v_lshl_add_u64 v[140:141], s[52:53], 0, v[138:139]
	s_add_i32 m0, s3, 0xe000
	s_nop 0
	global_load_lds_dwordx4 v[140:141], off
	s_waitcnt vmcnt(8)
	s_waitcnt lgkmcnt(0)
	s_barrier
	s_setprio 1
	s_waitcnt lgkmcnt(0)
	v_mfma_f32_16x16x32_bf16 v[124:127], v[152:155], v[184:187], v[124:127]
	v_mfma_f32_16x16x32_bf16 v[120:123], v[160:163], v[184:187], v[120:123]
	v_mfma_f32_16x16x32_bf16 v[108:111], v[152:155], v[192:195], v[108:111]
	v_mfma_f32_16x16x32_bf16 v[104:107], v[160:163], v[192:195], v[104:107]
	v_mfma_f32_16x16x32_bf16 v[92:95], v[152:155], v[200:203], v[92:95]
	v_mfma_f32_16x16x32_bf16 v[88:91], v[160:163], v[200:203], v[88:91]
	v_mfma_f32_16x16x32_bf16 v[76:79], v[152:155], v[208:211], v[76:79]
	v_mfma_f32_16x16x32_bf16 v[72:75], v[160:163], v[208:211], v[72:75]
	v_mfma_f32_16x16x32_bf16 v[124:127], v[156:159], v[188:191], v[124:127]
	v_mfma_f32_16x16x32_bf16 v[120:123], v[164:167], v[188:191], v[120:123]
	v_mfma_f32_16x16x32_bf16 v[108:111], v[156:159], v[196:199], v[108:111]
	v_mfma_f32_16x16x32_bf16 v[104:107], v[164:167], v[196:199], v[104:107]
	v_mfma_f32_16x16x32_bf16 v[92:95], v[156:159], v[204:207], v[92:95]
	v_mfma_f32_16x16x32_bf16 v[88:91], v[164:167], v[204:207], v[88:91]
	v_mfma_f32_16x16x32_bf16 v[76:79], v[156:159], v[216:219], v[76:79]
	v_mfma_f32_16x16x32_bf16 v[72:75], v[164:167], v[216:219], v[72:75]
	s_setprio 0
	s_setprio 1
	v_mfma_f32_16x16x32_bf16 v[116:119], v[168:171], v[184:187], v[116:119]
	v_mfma_f32_16x16x32_bf16 v[112:115], v[176:179], v[184:187], v[112:115]
	v_mfma_f32_16x16x32_bf16 v[100:103], v[168:171], v[192:195], v[100:103]
	v_mfma_f32_16x16x32_bf16 v[96:99], v[176:179], v[192:195], v[96:99]
	v_mfma_f32_16x16x32_bf16 v[84:87], v[168:171], v[200:203], v[84:87]
	v_mfma_f32_16x16x32_bf16 v[80:83], v[176:179], v[200:203], v[80:83]
	v_mfma_f32_16x16x32_bf16 v[68:71], v[168:171], v[208:211], v[68:71]
	v_mfma_f32_16x16x32_bf16 v[64:67], v[176:179], v[208:211], v[64:67]
	v_mfma_f32_16x16x32_bf16 v[116:119], v[172:175], v[188:191], v[116:119]
	v_mfma_f32_16x16x32_bf16 v[112:115], v[180:183], v[188:191], v[112:115]
	v_mfma_f32_16x16x32_bf16 v[100:103], v[172:175], v[196:199], v[100:103]
	v_mfma_f32_16x16x32_bf16 v[96:99], v[180:183], v[196:199], v[96:99]
	v_mfma_f32_16x16x32_bf16 v[84:87], v[172:175], v[204:207], v[84:87]
	v_mfma_f32_16x16x32_bf16 v[80:83], v[180:183], v[204:207], v[80:83]
	v_mfma_f32_16x16x32_bf16 v[68:71], v[172:175], v[216:219], v[68:71]
	v_mfma_f32_16x16x32_bf16 v[64:67], v[180:183], v[216:219], v[64:67]
	s_setprio 0
	s_barrier
	s_add_i32 s34, s18, s2
	v_lshl_add_u64 v[140:141], s[54:55], 0, v[130:131]
	s_mov_b32 m0, s34
	ds_read_b128 v[184:187], v150 offset:16384
	ds_read_b128 v[188:191], v150 offset:17408
	ds_read_b128 v[192:195], v150 offset:18432
	ds_read_b128 v[196:199], v150 offset:19456
	ds_read_b128 v[200:203], v150 offset:20480
	ds_read_b128 v[204:207], v150 offset:21504
	ds_read_b128 v[208:211], v150 offset:22528
	ds_read_b128 v[216:219], v150 offset:23552
	global_load_lds_dwordx4 v[140:141], off
	s_add_i32 m0, s34, 0x2000
	s_add_u32 s34, s54, 0x10000
	v_lshl_add_u64 v[220:221], s[54:55], 0, v[134:135]
	s_addc_u32 s35, s55, 0
	s_add_i32 s41, s19, s2
	global_load_lds_dwordx4 v[220:221], off
	v_lshl_add_u64 v[222:223], s[34:35], 0, v[130:131]
	s_mov_b32 m0, s41
	v_lshl_add_u64 v[224:225], s[56:57], 0, v[132:133]
	global_load_lds_dwordx4 v[222:223], off
	v_lshl_add_u64 v[222:223], s[34:35], 0, v[134:135]
	s_add_i32 m0, s41, 0x2000
	s_nop 0
	global_load_lds_dwordx4 v[222:223], off
	v_lshl_add_u64 v[222:223], s[56:57], 0, v[128:129]
	s_mov_b32 m0, s3
	s_nop 0
	global_load_lds_dwordx4 v[222:223], off
	s_mov_b32 m0, s8
	s_nop 0
	global_load_lds_dwordx4 v[224:225], off
	s_waitcnt vmcnt(8)
	s_waitcnt lgkmcnt(0)
	s_barrier
; #define STAGE(bufoff, gbase) STAGE_(bufoff, gbase, voffA)
; #define LDA(dst, b, h) do { _Pragma("unroll") for (int m = 0; m < 4; ++m) _Pragma("unroll") for (int k = 0; k < 2; ++k) dst[m][k] = *LDSP(const bf16x8, lds + SA(b, h) + aoff + m * 2048 + k * 1024); } while (0)
; #define LDB(dst, b, h) do { _Pragma("unroll") for (int n = 0; n < 2; ++n) _Pragma("unroll") for (int k = 0; k < 2; ++k) dst[n][k] = *LDSP(const bf16x8, lds + SB(b, h) + boff + n * 2048 + k * 1024); } while (0)
; #define MMA(ai, bj, AT, BT) do { __builtin_amdgcn_s_setprio(1); \
;     _Pragma("unroll") for (int m = 0; m < 4; ++m) _Pragma("unroll") for (int n = 0; n < 2; ++n) _Pragma("unroll") for (int k = 0; k < 2; ++k) \
;       acc[ai][bj][m][n] = __builtin_amdgcn_mfma_f32_16x16x32_bf16(BT[n][k], AT[m][k], acc[ai][bj][m][n], 0, 0, 0); \
;     __builtin_amdgcn_s_setprio(0); } while (0)
; #define WAIT_V(n) asm volatile("s_waitcnt vmcnt(" #n ")" ::: "memory")
; #define WAIT_L(n) asm volatile("s_waitcnt lgkmcnt(" #n ")" ::: "memory")
; #define BAR __builtin_amdgcn_s_barrier()
; #define SCHED __builtin_amdgcn_sched_barrier(0)
; #define WAIT_V(n) asm volatile("s_waitcnt vmcnt(" #n ")" ::: "memory")
; #define BAR do { __builtin_amdgcn_sched_barrier(0); __builtin_amdgcn_s_barrier(); asm volatile("" ::: "memory"); __builtin_amdgcn_sched_barrier(0); } while (0)
; template <bool SP2, bool ALIGN_EPI, bool DUAL, class Epi> DI void gemm_phase2(const bf16_t* A, const bf16_t* Bt, const bf16_t* A2, const bf16_t* Bt2, int M, int N, int K, const Epi& E, lds_t* lds) {
;     ...
;         WAIT_V(8); WAIT_L(0); BAR; MMA(1, 0, At, B0); MMA(1, 1, At, B1); BAR; SCHED;
;         LDB(B0, 1, 0); LDB(B1, 1, 1); SCHED; LDA(At, 1, 0); STAGE(SA(0, 1), a2 + hstep);
;         WAIT_V(8); WAIT_L(0); BAR; MMA(0, 0, At, B0); MMA(0, 1, At, B1); BAR; SCHED;
	s_setprio 1
	s_waitcnt lgkmcnt(0)
	v_mfma_f32_16x16x32_bf16 v[60:63], v[152:155], v[184:187], v[60:63]
	v_mfma_f32_16x16x32_bf16 v[56:59], v[160:163], v[184:187], v[56:59]
	v_mfma_f32_16x16x32_bf16 v[44:47], v[152:155], v[192:195], v[44:47]
	v_mfma_f32_16x16x32_bf16 v[40:43], v[160:163], v[192:195], v[40:43]
	v_mfma_f32_16x16x32_bf16 v[28:31], v[152:155], v[200:203], v[28:31]
	v_mfma_f32_16x16x32_bf16 v[24:27], v[160:163], v[200:203], v[24:27]
	v_mfma_f32_16x16x32_bf16 v[12:15], v[152:155], v[208:211], v[12:15]
	v_mfma_f32_16x16x32_bf16 v[8:11], v[160:163], v[208:211], v[8:11]
	v_mfma_f32_16x16x32_bf16 v[60:63], v[156:159], v[188:191], v[60:63]
	v_mfma_f32_16x16x32_bf16 v[56:59], v[164:167], v[188:191], v[56:59]
	v_mfma_f32_16x16x32_bf16 v[44:47], v[156:159], v[196:199], v[44:47]
	v_mfma_f32_16x16x32_bf16 v[40:43], v[164:167], v[196:199], v[40:43]
	v_mfma_f32_16x16x32_bf16 v[28:31], v[156:159], v[204:207], v[28:31]
	v_mfma_f32_16x16x32_bf16 v[24:27], v[164:167], v[204:207], v[24:27]
	v_mfma_f32_16x16x32_bf16 v[12:15], v[156:159], v[216:219], v[12:15]
	v_mfma_f32_16x16x32_bf16 v[8:11], v[164:167], v[216:219], v[8:11]
	s_setprio 0
	s_setprio 1
	v_mfma_f32_16x16x32_bf16 v[52:55], v[168:171], v[184:187], v[52:55]
	v_mfma_f32_16x16x32_bf16 v[48:51], v[176:179], v[184:187], v[48:51]
	v_mfma_f32_16x16x32_bf16 v[36:39], v[168:171], v[192:195], v[36:39]
	v_mfma_f32_16x16x32_bf16 v[32:35], v[176:179], v[192:195], v[32:35]
	v_mfma_f32_16x16x32_bf16 v[20:23], v[168:171], v[200:203], v[20:23]
	v_mfma_f32_16x16x32_bf16 v[16:19], v[176:179], v[200:203], v[16:19]
	v_mfma_f32_16x16x32_bf16 v[4:7], v[168:171], v[208:211], v[4:7]
	v_mfma_f32_16x16x32_bf16 v[0:3], v[176:179], v[208:211], v[0:3]
	v_mfma_f32_16x16x32_bf16 v[52:55], v[172:175], v[188:191], v[52:55]
	v_mfma_f32_16x16x32_bf16 v[48:51], v[180:183], v[188:191], v[48:51]
	v_mfma_f32_16x16x32_bf16 v[36:39], v[172:175], v[196:199], v[36:39]
	v_mfma_f32_16x16x32_bf16 v[32:35], v[180:183], v[196:199], v[32:35]
	v_mfma_f32_16x16x32_bf16 v[20:23], v[172:175], v[204:207], v[20:23]
	v_mfma_f32_16x16x32_bf16 v[16:19], v[180:183], v[204:207], v[16:19]
	v_mfma_f32_16x16x32_bf16 v[4:7], v[172:175], v[216:219], v[4:7]
	v_mfma_f32_16x16x32_bf16 v[0:3], v[180:183], v[216:219], v[0:3]
	s_setprio 0
	s_barrier
	s_add_i32 s41, 0, 0x18000
	s_add_i32 s49, 0, 0x1c000
	v_add_u32_e32 v164, s41, v143
	v_add_u32_e32 v180, s49, v143
	ds_read_b128 v[152:155], v164
	ds_read_b128 v[156:159], v164 offset:1024
	ds_read_b128 v[160:163], v164 offset:2048
	ds_read_b128 v[164:167], v164 offset:3072
	ds_read_b128 v[168:171], v180
	ds_read_b128 v[172:175], v180 offset:1024
	ds_read_b128 v[176:179], v180 offset:2048
	ds_read_b128 v[180:183], v180 offset:3072
	s_add_u32 s34, s56, 0x40000
	s_addc_u32 s35, s57, 0
	s_mov_b32 m0, s9
	v_lshl_add_u64 v[226:227], s[34:35], 0, v[128:129]
	ds_read_b128 v[184:187], v150 offset:32768
	ds_read_b128 v[188:191], v150 offset:33792
	ds_read_b128 v[192:195], v150 offset:34816
	ds_read_b128 v[196:199], v150 offset:35840
	ds_read_b128 v[200:203], v150 offset:36864
	ds_read_b128 v[204:207], v150 offset:37888
	ds_read_b128 v[208:211], v150 offset:38912
	ds_read_b128 v[216:219], v150 offset:39936
	global_load_lds_dwordx4 v[226:227], off
	v_lshl_add_u64 v[226:227], s[34:35], 0, v[132:133]
	s_mov_b32 m0, s10
	s_nop 0
	global_load_lds_dwordx4 v[226:227], off
	s_waitcnt vmcnt(8)
	s_waitcnt lgkmcnt(0)
	s_barrier
	s_setprio 1
	s_waitcnt lgkmcnt(0)
	v_mfma_f32_16x16x32_bf16 v[124:127], v[152:155], v[184:187], v[124:127]
	v_mfma_f32_16x16x32_bf16 v[120:123], v[160:163], v[184:187], v[120:123]
	v_mfma_f32_16x16x32_bf16 v[108:111], v[152:155], v[192:195], v[108:111]
	v_mfma_f32_16x16x32_bf16 v[104:107], v[160:163], v[192:195], v[104:107]
	v_mfma_f32_16x16x32_bf16 v[92:95], v[152:155], v[200:203], v[92:95]
	v_mfma_f32_16x16x32_bf16 v[88:91], v[160:163], v[200:203], v[88:91]
	v_mfma_f32_16x16x32_bf16 v[76:79], v[152:155], v[208:211], v[76:79]
	v_mfma_f32_16x16x32_bf16 v[72:75], v[160:163], v[208:211], v[72:75]
	v_mfma_f32_16x16x32_bf16 v[124:127], v[156:159], v[188:191], v[124:127]
	v_mfma_f32_16x16x32_bf16 v[120:123], v[164:167], v[188:191], v[120:123]
	v_mfma_f32_16x16x32_bf16 v[108:111], v[156:159], v[196:199], v[108:111]
	v_mfma_f32_16x16x32_bf16 v[104:107], v[164:167], v[196:199], v[104:107]
	v_mfma_f32_16x16x32_bf16 v[92:95], v[156:159], v[204:207], v[92:95]
	v_mfma_f32_16x16x32_bf16 v[88:91], v[164:167], v[204:207], v[88:91]
	v_mfma_f32_16x16x32_bf16 v[76:79], v[156:159], v[216:219], v[76:79]
	v_mfma_f32_16x16x32_bf16 v[72:75], v[164:167], v[216:219], v[72:75]
	s_setprio 0
	s_setprio 1
	v_mfma_f32_16x16x32_bf16 v[116:119], v[168:171], v[184:187], v[116:119]
	v_mfma_f32_16x16x32_bf16 v[112:115], v[176:179], v[184:187], v[112:115]
	v_mfma_f32_16x16x32_bf16 v[100:103], v[168:171], v[192:195], v[100:103]
	v_mfma_f32_16x16x32_bf16 v[96:99], v[176:179], v[192:195], v[96:99]
	v_mfma_f32_16x16x32_bf16 v[84:87], v[168:171], v[200:203], v[84:87]
	v_mfma_f32_16x16x32_bf16 v[80:83], v[176:179], v[200:203], v[80:83]
	v_mfma_f32_16x16x32_bf16 v[68:71], v[168:171], v[208:211], v[68:71]
	v_mfma_f32_16x16x32_bf16 v[64:67], v[176:179], v[208:211], v[64:67]
	v_mfma_f32_16x16x32_bf16 v[116:119], v[172:175], v[188:191], v[116:119]
	v_mfma_f32_16x16x32_bf16 v[112:115], v[180:183], v[188:191], v[112:115]
	v_mfma_f32_16x16x32_bf16 v[100:103], v[172:175], v[196:199], v[100:103]
	v_mfma_f32_16x16x32_bf16 v[96:99], v[180:183], v[196:199], v[96:99]
	v_mfma_f32_16x16x32_bf16 v[84:87], v[172:175], v[204:207], v[84:87]
	v_mfma_f32_16x16x32_bf16 v[80:83], v[180:183], v[204:207], v[80:83]
	v_mfma_f32_16x16x32_bf16 v[68:71], v[172:175], v[216:219], v[68:71]
	v_mfma_f32_16x16x32_bf16 v[64:67], v[180:183], v[216:219], v[64:67]
	s_setprio 0
	s_barrier
; #define STAGE(bufoff, gbase) STAGE_(bufoff, gbase, voffA)
; #define STAGEB(bufoff, gbase) STAGE_(bufoff, gbase, voffB)
; #define LDA(dst, b, h) do { _Pragma("unroll") for (int m = 0; m < 4; ++m) _Pragma("unroll") for (int k = 0; k < 2; ++k) dst[m][k] = *LDSP(const bf16x8, lds + SA(b, h) + aoff + m * 2048 + k * 1024); } while (0)
; #define MMA(ai, bj, AT, BT) do { __builtin_amdgcn_s_setprio(1); \
;     _Pragma("unroll") for (int m = 0; m < 4; ++m) _Pragma("unroll") for (int n = 0; n < 2; ++n) _Pragma("unroll") for (int k = 0; k < 2; ++k) \
;       acc[ai][bj][m][n] = __builtin_amdgcn_mfma_f32_16x16x32_bf16(BT[n][k], AT[m][k], acc[ai][bj][m][n], 0, 0, 0); \
;     __builtin_amdgcn_s_setprio(0); } while (0)
; #define WAIT_V(n) asm volatile("s_waitcnt vmcnt(" #n ")" ::: "memory")
; #define WAIT_L(n) asm volatile("s_waitcnt lgkmcnt(" #n ")" ::: "memory")
; #define BAR __builtin_amdgcn_s_barrier()
; #define SCHED __builtin_amdgcn_sched_barrier(0)
; #define WAIT_V(n) asm volatile("s_waitcnt vmcnt(" #n ")" ::: "memory")
; #define BAR do { __builtin_amdgcn_sched_barrier(0); __builtin_amdgcn_s_barrier(); asm volatile("" ::: "memory"); __builtin_amdgcn_sched_barrier(0); } while (0)
; template <bool SP2, bool ALIGN_EPI, bool DUAL, class Epi> DI void gemm_phase2(const bf16_t* A, const bf16_t* Bt, const bf16_t* A2, const bf16_t* Bt2, int M, int N, int K, const Epi& E, lds_t* lds) {
;     ...
;     for (int t = 0; t < nt; t += 2) {
;       const bool last = (t == nt - 2);
;       const char* a1 = cA + (size_t)(t + 1) * kstep;
;       const char* a2 = last ? nA : cA + (size_t)(t + 2) * kstep; const char* b2 = last ? nB : cB + (size_t)(t + 2) * kstep;
;       const char* a3 = a2 + kstep; const char* b3 = b2 + kstep;
;     ...
;         LDA(At, 1, 1); STAGEB(SB(1, 0), b3); STAGEB(SB(1, 1), b3 + bstep); STAGE(SA(1, 0), a3);
;         WAIT_V(8); WAIT_L(0); BAR; MMA(1, 0, At, B0); MMA(1, 1, At, B1); BAR; SCHED;
	s_add_i32 s34, s41, s2
	v_lshl_add_u64 v[140:141], v[140:141], 0, s[28:29]
	s_mov_b32 m0, s34
	ds_read_b128 v[184:187], v150 offset:49152
	ds_read_b128 v[188:191], v150 offset:50176
	ds_read_b128 v[192:195], v150 offset:51200
	ds_read_b128 v[196:199], v150 offset:52224
	ds_read_b128 v[200:203], v150 offset:53248
	ds_read_b128 v[204:207], v150 offset:54272
	ds_read_b128 v[208:211], v150 offset:55296
	ds_read_b128 v[216:219], v150 offset:56320
	global_load_lds_dwordx4 v[140:141], off
	s_add_i32 m0, s34, 0x2000
	s_add_u32 s34, s54, 0x10080
	v_lshl_add_u64 v[140:141], v[220:221], 0, s[28:29]
	s_addc_u32 s35, s55, 0
	s_add_i32 s41, s49, s2
	global_load_lds_dwordx4 v[140:141], off
	v_lshl_add_u64 v[140:141], s[34:35], 0, v[130:131]
	s_mov_b32 m0, s41
	s_nop 0
	global_load_lds_dwordx4 v[140:141], off
	v_lshl_add_u64 v[140:141], s[34:35], 0, v[134:135]
	s_add_i32 m0, s41, 0x2000
	s_nop 0
	global_load_lds_dwordx4 v[140:141], off
	v_lshl_add_u64 v[140:141], v[222:223], 0, s[28:29]
	s_mov_b32 m0, s14
	s_nop 0
	global_load_lds_dwordx4 v[140:141], off
	v_lshl_add_u64 v[140:141], v[224:225], 0, s[28:29]
	s_mov_b32 m0, s15
	s_nop 0
	global_load_lds_dwordx4 v[140:141], off
	s_waitcnt vmcnt(8)
	s_waitcnt lgkmcnt(0)
	s_barrier
	s_setprio 1
	s_waitcnt lgkmcnt(0)
	v_mfma_f32_16x16x32_bf16 v[60:63], v[152:155], v[184:187], v[60:63]
	v_mfma_f32_16x16x32_bf16 v[56:59], v[160:163], v[184:187], v[56:59]
	v_mfma_f32_16x16x32_bf16 v[44:47], v[152:155], v[192:195], v[44:47]
	v_mfma_f32_16x16x32_bf16 v[40:43], v[160:163], v[192:195], v[40:43]
	v_mfma_f32_16x16x32_bf16 v[28:31], v[152:155], v[200:203], v[28:31]
	v_mfma_f32_16x16x32_bf16 v[24:27], v[160:163], v[200:203], v[24:27]
	v_mfma_f32_16x16x32_bf16 v[12:15], v[152:155], v[208:211], v[12:15]
	v_mfma_f32_16x16x32_bf16 v[8:11], v[160:163], v[208:211], v[8:11]
	v_mfma_f32_16x16x32_bf16 v[60:63], v[156:159], v[188:191], v[60:63]
	v_mfma_f32_16x16x32_bf16 v[56:59], v[164:167], v[188:191], v[56:59]
	v_mfma_f32_16x16x32_bf16 v[44:47], v[156:159], v[196:199], v[44:47]
	v_mfma_f32_16x16x32_bf16 v[40:43], v[164:167], v[196:199], v[40:43]
	v_mfma_f32_16x16x32_bf16 v[28:31], v[156:159], v[204:207], v[28:31]
	v_mfma_f32_16x16x32_bf16 v[24:27], v[164:167], v[204:207], v[24:27]
	v_mfma_f32_16x16x32_bf16 v[12:15], v[156:159], v[216:219], v[12:15]
	v_mfma_f32_16x16x32_bf16 v[8:11], v[164:167], v[216:219], v[8:11]
	s_setprio 0
	s_setprio 1
	v_mfma_f32_16x16x32_bf16 v[52:55], v[168:171], v[184:187], v[52:55]
	v_mfma_f32_16x16x32_bf16 v[48:51], v[176:179], v[184:187], v[48:51]
	v_mfma_f32_16x16x32_bf16 v[36:39], v[168:171], v[192:195], v[36:39]
	v_mfma_f32_16x16x32_bf16 v[32:35], v[176:179], v[192:195], v[32:35]
	v_mfma_f32_16x16x32_bf16 v[20:23], v[168:171], v[200:203], v[20:23]
	v_mfma_f32_16x16x32_bf16 v[16:19], v[176:179], v[200:203], v[16:19]
	v_mfma_f32_16x16x32_bf16 v[4:7], v[168:171], v[208:211], v[4:7]
	v_mfma_f32_16x16x32_bf16 v[0:3], v[176:179], v[208:211], v[0:3]
	v_mfma_f32_16x16x32_bf16 v[52:55], v[172:175], v[188:191], v[52:55]
	v_mfma_f32_16x16x32_bf16 v[48:51], v[180:183], v[188:191], v[48:51]
	v_mfma_f32_16x16x32_bf16 v[36:39], v[172:175], v[196:199], v[36:39]
	v_mfma_f32_16x16x32_bf16 v[32:35], v[180:183], v[196:199], v[32:35]
	v_mfma_f32_16x16x32_bf16 v[20:23], v[172:175], v[204:207], v[20:23]
	v_mfma_f32_16x16x32_bf16 v[16:19], v[180:183], v[204:207], v[16:19]
	v_mfma_f32_16x16x32_bf16 v[4:7], v[172:175], v[216:219], v[4:7]
	v_mfma_f32_16x16x32_bf16 v[0:3], v[180:183], v[216:219], v[0:3]
	s_setprio 0
	s_add_i32 s33, s33, 2
	s_add_u32 s52, s52, 0x100
	s_addc_u32 s53, s53, 0
	s_add_u32 s23, s23, 0x100
	s_addc_u32 s31, s31, 0
	s_cmp_gt_u32 s33, 13
	s_barrier
	s_cbranch_scc0 .LBB0_691
	s_and_b64 vcc, exec, s[36:37]
	s_cbranch_vccz .LBB0_694
	s_barrier

; #define STAGE(bufoff, gbase) STAGE_(bufoff, gbase, voffA)
; #define STAGEB(bufoff, gbase) STAGE_(bufoff, gbase, voffB)
; #define LDA(dst, b, h) do { _Pragma("unroll") for (int m = 0; m < 4; ++m) _Pragma("unroll") for (int k = 0; k < 2; ++k) dst[m][k] = *LDSP(const bf16x8, lds + SA(b, h) + aoff + m * 2048 + k * 1024); } while (0)
; #define LDB(dst, b, h) do { _Pragma("unroll") for (int n = 0; n < 2; ++n) _Pragma("unroll") for (int k = 0; k < 2; ++k) dst[n][k] = *LDSP(const bf16x8, lds + SB(b, h) + boff + n * 2048 + k * 1024); } while (0)
; #define MMA(ai, bj, AT, BT) do { __builtin_amdgcn_s_setprio(1); \
;     _Pragma("unroll") for (int m = 0; m < 4; ++m) _Pragma("unroll") for (int n = 0; n < 2; ++n) _Pragma("unroll") for (int k = 0; k < 2; ++k) \
;       acc[ai][bj][m][n] = __builtin_amdgcn_mfma_f32_16x16x32_bf16(BT[n][k], AT[m][k], acc[ai][bj][m][n], 0, 0, 0); \
;     __builtin_amdgcn_s_setprio(0); } while (0)
; #define WAIT_V(n) asm volatile("s_waitcnt vmcnt(" #n ")" ::: "memory")
; #define WAIT_L(n) asm volatile("s_waitcnt lgkmcnt(" #n ")" ::: "memory")
; #define BAR __builtin_amdgcn_s_barrier()
; #define SCHED __builtin_amdgcn_sched_barrier(0)
; #define WAIT_V(n) asm volatile("s_waitcnt vmcnt(" #n ")" ::: "memory")
; #define BAR do { __builtin_amdgcn_sched_barrier(0); __builtin_amdgcn_s_barrier(); asm volatile("" ::: "memory"); __builtin_amdgcn_sched_barrier(0); } while (0)
; template <bool SP2, bool ALIGN_EPI, bool DUAL, class Epi> DI void gemm_phase2(const bf16_t* A, const bf16_t* Bt, const bf16_t* A2, const bf16_t* Bt2, int M, int N, int K, const Epi& E, lds_t* lds) {
;     ...
;     for (int t = 0; t < nt; t += 2) {
;       const bool last = (t == nt - 2);
;       const char* a1 = cA + (size_t)(t + 1) * kstep;
;       const char* a2 = last ? nA : cA + (size_t)(t + 2) * kstep; const char* b2 = last ? nB : cB + (size_t)(t + 2) * kstep;
;       const char* a3 = a2 + kstep; const char* b3 = b2 + kstep;
;       if constexpr (SP2) {
;         LDB(B0, 0, 0); LDB(B1, 0, 1); SCHED; LDA(At, 0, 0); STAGE(SA(1, 1), a1 + hstep);
;         WAIT_V(8); WAIT_L(0); BAR; MMA(0, 0, At, B0); MMA(0, 1, At, B1); BAR; SCHED;
;         LDA(At, 0, 1); STAGEB(SB(0, 0), b2); STAGEB(SB(0, 1), b2 + bstep); STAGE(SA(0, 0), a2);
;         WAIT_V(8); WAIT_L(0); BAR; MMA(1, 0, At, B0); MMA(1, 1, At, B1); BAR; SCHED;
.LBB0_760:
	ds_read_b128 v[150:153], v146
	ds_read_b128 v[154:157], v146 offset:1024
	ds_read_b128 v[158:161], v146 offset:2048
	ds_read_b128 v[162:165], v146 offset:3072
	ds_read_b128 v[166:169], v147
	ds_read_b128 v[170:173], v147 offset:1024
	ds_read_b128 v[174:177], v147 offset:2048
	ds_read_b128 v[178:181], v147 offset:3072
	s_add_u32 s46, s44, 0xfffc0080
	s_addc_u32 s47, s45, -1
	s_cmp_eq_u32 s50, 12
	s_cselect_b32 s49, s0, s47
	s_cselect_b32 s48, s27, s46
	s_cselect_b32 s47, s31, s43
	s_cselect_b32 s46, s34, s35
	v_lshl_add_u64 v[210:211], s[44:45], 0, v[136:137]
	s_add_i32 m0, s3, 0xc000
	ds_read_b128 v[182:185], v148
	ds_read_b128 v[186:189], v148 offset:1024
	ds_read_b128 v[190:193], v148 offset:2048
	ds_read_b128 v[194:197], v148 offset:3072
	ds_read_b128 v[198:201], v148 offset:4096
	ds_read_b128 v[202:205], v148 offset:5120
	ds_read_b128 v[206:209], v148 offset:6144
	ds_read_b128 v[216:219], v148 offset:7168
	global_load_lds_dwordx4 v[210:211], off
	v_lshl_add_u64 v[210:211], s[44:45], 0, v[138:139]
	s_add_i32 m0, s3, 0xe000
	s_nop 0
	global_load_lds_dwordx4 v[210:211], off
	s_waitcnt vmcnt(8)
	s_waitcnt lgkmcnt(0)
	s_barrier
	s_setprio 1
	s_waitcnt lgkmcnt(0)
	v_mfma_f32_16x16x32_bf16 v[124:127], v[150:153], v[182:185], v[124:127]
	v_mfma_f32_16x16x32_bf16 v[120:123], v[158:161], v[182:185], v[120:123]
	v_mfma_f32_16x16x32_bf16 v[108:111], v[150:153], v[190:193], v[108:111]
	v_mfma_f32_16x16x32_bf16 v[104:107], v[158:161], v[190:193], v[104:107]
	v_mfma_f32_16x16x32_bf16 v[92:95], v[150:153], v[198:201], v[92:95]
	v_mfma_f32_16x16x32_bf16 v[88:91], v[158:161], v[198:201], v[88:91]
	v_mfma_f32_16x16x32_bf16 v[76:79], v[150:153], v[206:209], v[76:79]
	v_mfma_f32_16x16x32_bf16 v[72:75], v[158:161], v[206:209], v[72:75]
	v_mfma_f32_16x16x32_bf16 v[124:127], v[154:157], v[186:189], v[124:127]
	v_mfma_f32_16x16x32_bf16 v[120:123], v[162:165], v[186:189], v[120:123]
	v_mfma_f32_16x16x32_bf16 v[108:111], v[154:157], v[194:197], v[108:111]
	v_mfma_f32_16x16x32_bf16 v[104:107], v[162:165], v[194:197], v[104:107]
	v_mfma_f32_16x16x32_bf16 v[92:95], v[154:157], v[202:205], v[92:95]
	v_mfma_f32_16x16x32_bf16 v[88:91], v[162:165], v[202:205], v[88:91]
	v_mfma_f32_16x16x32_bf16 v[76:79], v[154:157], v[216:219], v[76:79]
	v_mfma_f32_16x16x32_bf16 v[72:75], v[162:165], v[216:219], v[72:75]
	s_setprio 0
	s_setprio 1
	v_mfma_f32_16x16x32_bf16 v[116:119], v[166:169], v[182:185], v[116:119]
	v_mfma_f32_16x16x32_bf16 v[112:115], v[174:177], v[182:185], v[112:115]
	v_mfma_f32_16x16x32_bf16 v[100:103], v[166:169], v[190:193], v[100:103]
	v_mfma_f32_16x16x32_bf16 v[96:99], v[174:177], v[190:193], v[96:99]
	v_mfma_f32_16x16x32_bf16 v[84:87], v[166:169], v[198:201], v[84:87]
	v_mfma_f32_16x16x32_bf16 v[80:83], v[174:177], v[198:201], v[80:83]
	v_mfma_f32_16x16x32_bf16 v[68:71], v[166:169], v[206:209], v[68:71]
	v_mfma_f32_16x16x32_bf16 v[64:67], v[174:177], v[206:209], v[64:67]
	v_mfma_f32_16x16x32_bf16 v[116:119], v[170:173], v[186:189], v[116:119]
	v_mfma_f32_16x16x32_bf16 v[112:115], v[178:181], v[186:189], v[112:115]
	v_mfma_f32_16x16x32_bf16 v[100:103], v[170:173], v[194:197], v[100:103]
	v_mfma_f32_16x16x32_bf16 v[96:99], v[178:181], v[194:197], v[96:99]
	v_mfma_f32_16x16x32_bf16 v[84:87], v[170:173], v[202:205], v[84:87]
	v_mfma_f32_16x16x32_bf16 v[80:83], v[178:181], v[202:205], v[80:83]
	v_mfma_f32_16x16x32_bf16 v[68:71], v[170:173], v[216:219], v[68:71]
	v_mfma_f32_16x16x32_bf16 v[64:67], v[178:181], v[216:219], v[64:67]
	s_setprio 0
	s_barrier
	s_add_i32 s51, s19, s2
	v_lshl_add_u64 v[210:211], s[46:47], 0, v[132:133]
	s_mov_b32 m0, s51
	ds_read_b128 v[182:185], v148 offset:16384
	ds_read_b128 v[186:189], v148 offset:17408
	ds_read_b128 v[190:193], v148 offset:18432
	ds_read_b128 v[194:197], v148 offset:19456
	ds_read_b128 v[198:201], v148 offset:20480
	ds_read_b128 v[202:205], v148 offset:21504
	ds_read_b128 v[206:209], v148 offset:22528
	ds_read_b128 v[216:219], v148 offset:23552
	global_load_lds_dwordx4 v[210:211], off
	s_add_i32 m0, s51, 0x2000
	s_add_u32 s52, s46, 0x10000
	v_lshl_add_u64 v[220:221], s[46:47], 0, v[128:129]
	s_addc_u32 s53, s47, 0
	s_add_i32 s51, s20, s2
	global_load_lds_dwordx4 v[220:221], off
	v_lshl_add_u64 v[222:223], s[52:53], 0, v[132:133]
	s_mov_b32 m0, s51
	v_lshl_add_u64 v[224:225], s[48:49], 0, v[130:131]
	global_load_lds_dwordx4 v[222:223], off
	v_lshl_add_u64 v[222:223], s[52:53], 0, v[128:129]
	s_add_i32 m0, s51, 0x2000
	s_nop 0
	global_load_lds_dwordx4 v[222:223], off
	v_lshl_add_u64 v[222:223], s[48:49], 0, v[134:135]
	s_mov_b32 m0, s3
	s_nop 0
	global_load_lds_dwordx4 v[222:223], off
	s_mov_b32 m0, s8
	s_nop 0
	global_load_lds_dwordx4 v[224:225], off
	s_waitcnt vmcnt(8)
	s_waitcnt lgkmcnt(0)
	s_barrier
; #define STAGE(bufoff, gbase) STAGE_(bufoff, gbase, voffA)
; #define LDA(dst, b, h) do { _Pragma("unroll") for (int m = 0; m < 4; ++m) _Pragma("unroll") for (int k = 0; k < 2; ++k) dst[m][k] = *LDSP(const bf16x8, lds + SA(b, h) + aoff + m * 2048 + k * 1024); } while (0)
; #define LDB(dst, b, h) do { _Pragma("unroll") for (int n = 0; n < 2; ++n) _Pragma("unroll") for (int k = 0; k < 2; ++k) dst[n][k] = *LDSP(const bf16x8, lds + SB(b, h) + boff + n * 2048 + k * 1024); } while (0)
; #define MMA(ai, bj, AT, BT) do { __builtin_amdgcn_s_setprio(1); \
;     _Pragma("unroll") for (int m = 0; m < 4; ++m) _Pragma("unroll") for (int n = 0; n < 2; ++n) _Pragma("unroll") for (int k = 0; k < 2; ++k) \
;       acc[ai][bj][m][n] = __builtin_amdgcn_mfma_f32_16x16x32_bf16(BT[n][k], AT[m][k], acc[ai][bj][m][n], 0, 0, 0); \
;     __builtin_amdgcn_s_setprio(0); } while (0)
; #define WAIT_V(n) asm volatile("s_waitcnt vmcnt(" #n ")" ::: "memory")
; #define WAIT_L(n) asm volatile("s_waitcnt lgkmcnt(" #n ")" ::: "memory")
; #define BAR __builtin_amdgcn_s_barrier()
; #define SCHED __builtin_amdgcn_sched_barrier(0)
; #define WAIT_V(n) asm volatile("s_waitcnt vmcnt(" #n ")" ::: "memory")
; #define BAR do { __builtin_amdgcn_sched_barrier(0); __builtin_amdgcn_s_barrier(); asm volatile("" ::: "memory"); __builtin_amdgcn_sched_barrier(0); } while (0)
; template <bool SP2, bool ALIGN_EPI, bool DUAL, class Epi> DI void gemm_phase2(const bf16_t* A, const bf16_t* Bt, const bf16_t* A2, const bf16_t* Bt2, int M, int N, int K, const Epi& E, lds_t* lds) {
;     ...
;         WAIT_V(8); WAIT_L(0); BAR; MMA(1, 0, At, B0); MMA(1, 1, At, B1); BAR; SCHED;
;         LDB(B0, 1, 0); LDB(B1, 1, 1); SCHED; LDA(At, 1, 0); STAGE(SA(0, 1), a2 + hstep);
;         WAIT_V(8); WAIT_L(0); BAR; MMA(0, 0, At, B0); MMA(0, 1, At, B1); BAR; SCHED;
	s_setprio 1
	s_waitcnt lgkmcnt(0)
	v_mfma_f32_16x16x32_bf16 v[60:63], v[150:153], v[182:185], v[60:63]
	v_mfma_f32_16x16x32_bf16 v[56:59], v[158:161], v[182:185], v[56:59]
	v_mfma_f32_16x16x32_bf16 v[44:47], v[150:153], v[190:193], v[44:47]
	v_mfma_f32_16x16x32_bf16 v[40:43], v[158:161], v[190:193], v[40:43]
	v_mfma_f32_16x16x32_bf16 v[28:31], v[150:153], v[198:201], v[28:31]
	v_mfma_f32_16x16x32_bf16 v[24:27], v[158:161], v[198:201], v[24:27]
	v_mfma_f32_16x16x32_bf16 v[12:15], v[150:153], v[206:209], v[12:15]
	v_mfma_f32_16x16x32_bf16 v[8:11], v[158:161], v[206:209], v[8:11]
	v_mfma_f32_16x16x32_bf16 v[60:63], v[154:157], v[186:189], v[60:63]
	v_mfma_f32_16x16x32_bf16 v[56:59], v[162:165], v[186:189], v[56:59]
	v_mfma_f32_16x16x32_bf16 v[44:47], v[154:157], v[194:197], v[44:47]
	v_mfma_f32_16x16x32_bf16 v[40:43], v[162:165], v[194:197], v[40:43]
	v_mfma_f32_16x16x32_bf16 v[28:31], v[154:157], v[202:205], v[28:31]
	v_mfma_f32_16x16x32_bf16 v[24:27], v[162:165], v[202:205], v[24:27]
	v_mfma_f32_16x16x32_bf16 v[12:15], v[154:157], v[216:219], v[12:15]
	v_mfma_f32_16x16x32_bf16 v[8:11], v[162:165], v[216:219], v[8:11]
	s_setprio 0
	s_setprio 1
	v_mfma_f32_16x16x32_bf16 v[52:55], v[166:169], v[182:185], v[52:55]
	v_mfma_f32_16x16x32_bf16 v[48:51], v[174:177], v[182:185], v[48:51]
	v_mfma_f32_16x16x32_bf16 v[36:39], v[166:169], v[190:193], v[36:39]
	v_mfma_f32_16x16x32_bf16 v[32:35], v[174:177], v[190:193], v[32:35]
	v_mfma_f32_16x16x32_bf16 v[20:23], v[166:169], v[198:201], v[20:23]
	v_mfma_f32_16x16x32_bf16 v[16:19], v[174:177], v[198:201], v[16:19]
	v_mfma_f32_16x16x32_bf16 v[4:7], v[166:169], v[206:209], v[4:7]
	v_mfma_f32_16x16x32_bf16 v[0:3], v[174:177], v[206:209], v[0:3]
	v_mfma_f32_16x16x32_bf16 v[52:55], v[170:173], v[186:189], v[52:55]
	v_mfma_f32_16x16x32_bf16 v[48:51], v[178:181], v[186:189], v[48:51]
	v_mfma_f32_16x16x32_bf16 v[36:39], v[170:173], v[194:197], v[36:39]
	v_mfma_f32_16x16x32_bf16 v[32:35], v[178:181], v[194:197], v[32:35]
	v_mfma_f32_16x16x32_bf16 v[20:23], v[170:173], v[202:205], v[20:23]
	v_mfma_f32_16x16x32_bf16 v[16:19], v[178:181], v[202:205], v[16:19]
	v_mfma_f32_16x16x32_bf16 v[4:7], v[170:173], v[216:219], v[4:7]
	v_mfma_f32_16x16x32_bf16 v[0:3], v[178:181], v[216:219], v[0:3]
	s_setprio 0
	s_barrier
	s_add_i32 s51, 0, 0x18000
	s_add_i32 s52, 0, 0x1c000
	v_add_u32_e32 v162, s51, v141
	v_add_u32_e32 v178, s52, v141
	ds_read_b128 v[150:153], v162
	ds_read_b128 v[154:157], v162 offset:1024
	ds_read_b128 v[158:161], v162 offset:2048
	ds_read_b128 v[162:165], v162 offset:3072
	ds_read_b128 v[166:169], v178
	ds_read_b128 v[170:173], v178 offset:1024
	ds_read_b128 v[174:177], v178 offset:2048
	ds_read_b128 v[178:181], v178 offset:3072
	s_add_u32 s48, s48, 0x40000
	s_addc_u32 s49, s49, 0
	s_mov_b32 m0, s9
	v_lshl_add_u64 v[226:227], s[48:49], 0, v[134:135]
	ds_read_b128 v[182:185], v148 offset:32768
	ds_read_b128 v[186:189], v148 offset:33792
	ds_read_b128 v[190:193], v148 offset:34816
	ds_read_b128 v[194:197], v148 offset:35840
	ds_read_b128 v[198:201], v148 offset:36864
	ds_read_b128 v[202:205], v148 offset:37888
	ds_read_b128 v[206:209], v148 offset:38912
	ds_read_b128 v[216:219], v148 offset:39936
	global_load_lds_dwordx4 v[226:227], off
	v_lshl_add_u64 v[226:227], s[48:49], 0, v[130:131]
	s_mov_b32 m0, s10
	s_nop 0
	global_load_lds_dwordx4 v[226:227], off
	s_waitcnt vmcnt(8)
	s_waitcnt lgkmcnt(0)
	s_barrier
	s_setprio 1
	s_waitcnt lgkmcnt(0)
	v_mfma_f32_16x16x32_bf16 v[124:127], v[150:153], v[182:185], v[124:127]
	v_mfma_f32_16x16x32_bf16 v[120:123], v[158:161], v[182:185], v[120:123]
	v_mfma_f32_16x16x32_bf16 v[108:111], v[150:153], v[190:193], v[108:111]
	v_mfma_f32_16x16x32_bf16 v[104:107], v[158:161], v[190:193], v[104:107]
	v_mfma_f32_16x16x32_bf16 v[92:95], v[150:153], v[198:201], v[92:95]
	v_mfma_f32_16x16x32_bf16 v[88:91], v[158:161], v[198:201], v[88:91]
	v_mfma_f32_16x16x32_bf16 v[76:79], v[150:153], v[206:209], v[76:79]
	v_mfma_f32_16x16x32_bf16 v[72:75], v[158:161], v[206:209], v[72:75]
	v_mfma_f32_16x16x32_bf16 v[124:127], v[154:157], v[186:189], v[124:127]
	v_mfma_f32_16x16x32_bf16 v[120:123], v[162:165], v[186:189], v[120:123]
	v_mfma_f32_16x16x32_bf16 v[108:111], v[154:157], v[194:197], v[108:111]
	v_mfma_f32_16x16x32_bf16 v[104:107], v[162:165], v[194:197], v[104:107]
	v_mfma_f32_16x16x32_bf16 v[92:95], v[154:157], v[202:205], v[92:95]
	v_mfma_f32_16x16x32_bf16 v[88:91], v[162:165], v[202:205], v[88:91]
	v_mfma_f32_16x16x32_bf16 v[76:79], v[154:157], v[216:219], v[76:79]
	v_mfma_f32_16x16x32_bf16 v[72:75], v[162:165], v[216:219], v[72:75]
	s_setprio 0
	s_setprio 1
	v_mfma_f32_16x16x32_bf16 v[116:119], v[166:169], v[182:185], v[116:119]
	v_mfma_f32_16x16x32_bf16 v[112:115], v[174:177], v[182:185], v[112:115]
	v_mfma_f32_16x16x32_bf16 v[100:103], v[166:169], v[190:193], v[100:103]
	v_mfma_f32_16x16x32_bf16 v[96:99], v[174:177], v[190:193], v[96:99]
	v_mfma_f32_16x16x32_bf16 v[84:87], v[166:169], v[198:201], v[84:87]
	v_mfma_f32_16x16x32_bf16 v[80:83], v[174:177], v[198:201], v[80:83]
	v_mfma_f32_16x16x32_bf16 v[68:71], v[166:169], v[206:209], v[68:71]
	v_mfma_f32_16x16x32_bf16 v[64:67], v[174:177], v[206:209], v[64:67]
	v_mfma_f32_16x16x32_bf16 v[116:119], v[170:173], v[186:189], v[116:119]
	v_mfma_f32_16x16x32_bf16 v[112:115], v[178:181], v[186:189], v[112:115]
	v_mfma_f32_16x16x32_bf16 v[100:103], v[170:173], v[194:197], v[100:103]
	v_mfma_f32_16x16x32_bf16 v[96:99], v[178:181], v[194:197], v[96:99]
	v_mfma_f32_16x16x32_bf16 v[84:87], v[170:173], v[202:205], v[84:87]
	v_mfma_f32_16x16x32_bf16 v[80:83], v[178:181], v[202:205], v[80:83]
	v_mfma_f32_16x16x32_bf16 v[68:71], v[170:173], v[216:219], v[68:71]
	v_mfma_f32_16x16x32_bf16 v[64:67], v[178:181], v[216:219], v[64:67]
	s_setprio 0
	s_barrier
; #define STAGE(bufoff, gbase) STAGE_(bufoff, gbase, voffA)
; #define STAGEB(bufoff, gbase) STAGE_(bufoff, gbase, voffB)
; #define LDA(dst, b, h) do { _Pragma("unroll") for (int m = 0; m < 4; ++m) _Pragma("unroll") for (int k = 0; k < 2; ++k) dst[m][k] = *LDSP(const bf16x8, lds + SA(b, h) + aoff + m * 2048 + k * 1024); } while (0)
; #define MMA(ai, bj, AT, BT) do { __builtin_amdgcn_s_setprio(1); \
;     _Pragma("unroll") for (int m = 0; m < 4; ++m) _Pragma("unroll") for (int n = 0; n < 2; ++n) _Pragma("unroll") for (int k = 0; k < 2; ++k) \
;       acc[ai][bj][m][n] = __builtin_amdgcn_mfma_f32_16x16x32_bf16(BT[n][k], AT[m][k], acc[ai][bj][m][n], 0, 0, 0); \
;     __builtin_amdgcn_s_setprio(0); } while (0)
; #define WAIT_V(n) asm volatile("s_waitcnt vmcnt(" #n ")" ::: "memory")
; #define WAIT_L(n) asm volatile("s_waitcnt lgkmcnt(" #n ")" ::: "memory")
; #define BAR __builtin_amdgcn_s_barrier()
; #define SCHED __builtin_amdgcn_sched_barrier(0)
; #define WAIT_V(n) asm volatile("s_waitcnt vmcnt(" #n ")" ::: "memory")
; #define BAR do { __builtin_amdgcn_sched_barrier(0); __builtin_amdgcn_s_barrier(); asm volatile("" ::: "memory"); __builtin_amdgcn_sched_barrier(0); } while (0)
; template <bool SP2, bool ALIGN_EPI, bool DUAL, class Epi> DI void gemm_phase2(const bf16_t* A, const bf16_t* Bt, const bf16_t* A2, const bf16_t* Bt2, int M, int N, int K, const Epi& E, lds_t* lds) {
;     ...
;     for (int t = 0; t < nt; t += 2) {
;       const bool last = (t == nt - 2);
;       const char* a1 = cA + (size_t)(t + 1) * kstep;
;       const char* a2 = last ? nA : cA + (size_t)(t + 2) * kstep; const char* b2 = last ? nB : cB + (size_t)(t + 2) * kstep;
;       const char* a3 = a2 + kstep; const char* b3 = b2 + kstep;
;     ...
;         LDA(At, 1, 1); STAGEB(SB(1, 0), b3); STAGEB(SB(1, 1), b3 + bstep); STAGE(SA(1, 0), a3);
;         WAIT_V(8); WAIT_L(0); BAR; MMA(1, 0, At, B0); MMA(1, 1, At, B1); BAR; SCHED;
	s_add_i32 s48, s51, s2
	v_lshl_add_u64 v[210:211], v[210:211], 0, s[22:23]
	s_mov_b32 m0, s48
	ds_read_b128 v[182:185], v148 offset:49152
	ds_read_b128 v[186:189], v148 offset:50176
	ds_read_b128 v[190:193], v148 offset:51200
	ds_read_b128 v[194:197], v148 offset:52224
	ds_read_b128 v[198:201], v148 offset:53248
	ds_read_b128 v[202:205], v148 offset:54272
	ds_read_b128 v[206:209], v148 offset:55296
	ds_read_b128 v[216:219], v148 offset:56320
	global_load_lds_dwordx4 v[210:211], off
	s_add_i32 m0, s48, 0x2000
	s_add_u32 s46, s46, 0x10080
	v_lshl_add_u64 v[210:211], v[220:221], 0, s[22:23]
	s_addc_u32 s47, s47, 0
	s_add_i32 s48, s52, s2
	global_load_lds_dwordx4 v[210:211], off
	v_lshl_add_u64 v[210:211], s[46:47], 0, v[132:133]
	s_mov_b32 m0, s48
	s_nop 0
	global_load_lds_dwordx4 v[210:211], off
	v_lshl_add_u64 v[210:211], s[46:47], 0, v[128:129]
	s_add_i32 m0, s48, 0x2000
	s_nop 0
	global_load_lds_dwordx4 v[210:211], off
	v_lshl_add_u64 v[210:211], v[222:223], 0, s[22:23]
	s_mov_b32 m0, s15
	s_nop 0
	global_load_lds_dwordx4 v[210:211], off
	v_lshl_add_u64 v[210:211], v[224:225], 0, s[22:23]
	s_mov_b32 m0, s18
	s_nop 0
	global_load_lds_dwordx4 v[210:211], off
	s_waitcnt vmcnt(8)
	s_waitcnt lgkmcnt(0)
	s_barrier
	s_setprio 1
	s_waitcnt lgkmcnt(0)
	v_mfma_f32_16x16x32_bf16 v[60:63], v[150:153], v[182:185], v[60:63]
	v_mfma_f32_16x16x32_bf16 v[56:59], v[158:161], v[182:185], v[56:59]
	v_mfma_f32_16x16x32_bf16 v[44:47], v[150:153], v[190:193], v[44:47]
	v_mfma_f32_16x16x32_bf16 v[40:43], v[158:161], v[190:193], v[40:43]
	v_mfma_f32_16x16x32_bf16 v[28:31], v[150:153], v[198:201], v[28:31]
	v_mfma_f32_16x16x32_bf16 v[24:27], v[158:161], v[198:201], v[24:27]
	v_mfma_f32_16x16x32_bf16 v[12:15], v[150:153], v[206:209], v[12:15]
	v_mfma_f32_16x16x32_bf16 v[8:11], v[158:161], v[206:209], v[8:11]
	v_mfma_f32_16x16x32_bf16 v[60:63], v[154:157], v[186:189], v[60:63]
	v_mfma_f32_16x16x32_bf16 v[56:59], v[162:165], v[186:189], v[56:59]
	v_mfma_f32_16x16x32_bf16 v[44:47], v[154:157], v[194:197], v[44:47]
	v_mfma_f32_16x16x32_bf16 v[40:43], v[162:165], v[194:197], v[40:43]
	v_mfma_f32_16x16x32_bf16 v[28:31], v[154:157], v[202:205], v[28:31]
	v_mfma_f32_16x16x32_bf16 v[24:27], v[162:165], v[202:205], v[24:27]
	v_mfma_f32_16x16x32_bf16 v[12:15], v[154:157], v[216:219], v[12:15]
	v_mfma_f32_16x16x32_bf16 v[8:11], v[162:165], v[216:219], v[8:11]
	s_setprio 0
	s_setprio 1
	v_mfma_f32_16x16x32_bf16 v[52:55], v[166:169], v[182:185], v[52:55]
	v_mfma_f32_16x16x32_bf16 v[48:51], v[174:177], v[182:185], v[48:51]
	v_mfma_f32_16x16x32_bf16 v[36:39], v[166:169], v[190:193], v[36:39]
	v_mfma_f32_16x16x32_bf16 v[32:35], v[174:177], v[190:193], v[32:35]
	v_mfma_f32_16x16x32_bf16 v[20:23], v[166:169], v[198:201], v[20:23]
	v_mfma_f32_16x16x32_bf16 v[16:19], v[174:177], v[198:201], v[16:19]
	v_mfma_f32_16x16x32_bf16 v[4:7], v[166:169], v[206:209], v[4:7]
	v_mfma_f32_16x16x32_bf16 v[0:3], v[174:177], v[206:209], v[0:3]
	v_mfma_f32_16x16x32_bf16 v[52:55], v[170:173], v[186:189], v[52:55]
	v_mfma_f32_16x16x32_bf16 v[48:51], v[178:181], v[186:189], v[48:51]
	v_mfma_f32_16x16x32_bf16 v[36:39], v[170:173], v[194:197], v[36:39]
	v_mfma_f32_16x16x32_bf16 v[32:35], v[178:181], v[194:197], v[32:35]
	v_mfma_f32_16x16x32_bf16 v[20:23], v[170:173], v[202:205], v[20:23]
	v_mfma_f32_16x16x32_bf16 v[16:19], v[178:181], v[202:205], v[16:19]
	v_mfma_f32_16x16x32_bf16 v[4:7], v[170:173], v[216:219], v[4:7]
	v_mfma_f32_16x16x32_bf16 v[0:3], v[178:181], v[216:219], v[0:3]
	s_setprio 0
	s_add_i32 s50, s50, 2
	s_add_u32 s44, s44, 0x100
	s_addc_u32 s45, s45, 0
	s_add_u32 s35, s35, 0x100
	s_addc_u32 s43, s43, 0
	s_cmp_gt_u32 s50, 13
	s_barrier
	s_cbranch_scc0 .LBB0_760
	s_and_b64 vcc, exec, s[28:29]
	s_cbranch_vccz .LBB0_763
	s_barrier

; #define STAGE(bufoff, gbase) STAGE_(bufoff, gbase, voffA)
; #define STAGEB(bufoff, gbase) STAGE_(bufoff, gbase, voffB)
; #define LDA(dst, b, h) do { _Pragma("unroll") for (int m = 0; m < 4; ++m) _Pragma("unroll") for (int k = 0; k < 2; ++k) dst[m][k] = *LDSP(const bf16x8, lds + SA(b, h) + aoff + m * 2048 + k * 1024); } while (0)
; #define LDB(dst, b, h) do { _Pragma("unroll") for (int n = 0; n < 2; ++n) _Pragma("unroll") for (int k = 0; k < 2; ++k) dst[n][k] = *LDSP(const bf16x8, lds + SB(b, h) + boff + n * 2048 + k * 1024); } while (0)
; #define MMA(ai, bj, AT, BT) do { __builtin_amdgcn_s_setprio(1); \
;     _Pragma("unroll") for (int m = 0; m < 4; ++m) _Pragma("unroll") for (int n = 0; n < 2; ++n) _Pragma("unroll") for (int k = 0; k < 2; ++k) \
;       acc[ai][bj][m][n] = __builtin_amdgcn_mfma_f32_16x16x32_bf16(BT[n][k], AT[m][k], acc[ai][bj][m][n], 0, 0, 0); \
;     __builtin_amdgcn_s_setprio(0); } while (0)
; #define WAIT_V(n) asm volatile("s_waitcnt vmcnt(" #n ")" ::: "memory")
; #define WAIT_L(n) asm volatile("s_waitcnt lgkmcnt(" #n ")" ::: "memory")
; #define BAR __builtin_amdgcn_s_barrier()
; #define SCHED __builtin_amdgcn_sched_barrier(0)
; #define WAIT_V(n) asm volatile("s_waitcnt vmcnt(" #n ")" ::: "memory")
; #define BAR do { __builtin_amdgcn_sched_barrier(0); __builtin_amdgcn_s_barrier(); asm volatile("" ::: "memory"); __builtin_amdgcn_sched_barrier(0); } while (0)
; template <bool SP2, bool ALIGN_EPI, bool DUAL, class Epi> DI void gemm_phase2(const bf16_t* A, const bf16_t* Bt, const bf16_t* A2, const bf16_t* Bt2, int M, int N, int K, const Epi& E, lds_t* lds) {
;     ...
;     for (int t = 0; t < nt; t += 2) {
;       const bool last = (t == nt - 2);
;       const char* a1 = cA + (size_t)(t + 1) * kstep;
;       const char* a2 = last ? nA : cA + (size_t)(t + 2) * kstep; const char* b2 = last ? nB : cB + (size_t)(t + 2) * kstep;
;       const char* a3 = a2 + kstep; const char* b3 = b2 + kstep;
;       if constexpr (SP2) {
;         LDB(B0, 0, 0); LDB(B1, 0, 1); SCHED; LDA(At, 0, 0); STAGE(SA(1, 1), a1 + hstep);
;         WAIT_V(8); WAIT_L(0); BAR; MMA(0, 0, At, B0); MMA(0, 1, At, B1); BAR; SCHED;
;         LDA(At, 0, 1); STAGEB(SB(0, 0), b2); STAGEB(SB(0, 1), b2 + bstep); STAGE(SA(0, 0), a2);
;         WAIT_V(8); WAIT_L(0); BAR; MMA(1, 0, At, B0); MMA(1, 1, At, B1); BAR; SCHED;
.LBB0_824:
	ds_read_b128 v[152:155], v149
	ds_read_b128 v[156:159], v149 offset:1024
	ds_read_b128 v[160:163], v149 offset:2048
	ds_read_b128 v[164:167], v149 offset:3072
	ds_read_b128 v[168:171], v150
	ds_read_b128 v[172:175], v150 offset:1024
	ds_read_b128 v[176:179], v150 offset:2048
	ds_read_b128 v[180:183], v150 offset:3072
	s_add_u32 s45, s46, 0xfff00080
	s_addc_u32 s48, s47, -1
	s_cmp_eq_u32 s39, 60
	s_cselect_b32 s51, s0, s48
	s_cselect_b32 s50, s1, s45
	s_cselect_b32 s49, s7, s35
	s_cselect_b32 s48, s27, s34
	v_lshl_add_u64 v[140:141], s[46:47], 0, v[136:137]
	s_add_i32 m0, s3, 0xc000
	ds_read_b128 v[184:187], v151
	ds_read_b128 v[188:191], v151 offset:1024
	ds_read_b128 v[192:195], v151 offset:2048
	ds_read_b128 v[196:199], v151 offset:3072
	ds_read_b128 v[200:203], v151 offset:4096
	ds_read_b128 v[204:207], v151 offset:5120
	ds_read_b128 v[208:211], v151 offset:6144
	ds_read_b128 v[216:219], v151 offset:7168
	global_load_lds_dwordx4 v[140:141], off
	v_lshl_add_u64 v[140:141], s[46:47], 0, v[138:139]
	s_add_i32 m0, s3, 0xe000
	s_nop 0
	global_load_lds_dwordx4 v[140:141], off
	s_waitcnt vmcnt(8)
	s_waitcnt lgkmcnt(0)
	s_barrier
	s_setprio 1
	s_waitcnt lgkmcnt(0)
	v_mfma_f32_16x16x32_bf16 v[124:127], v[152:155], v[184:187], v[124:127]
	v_mfma_f32_16x16x32_bf16 v[120:123], v[160:163], v[184:187], v[120:123]
	v_mfma_f32_16x16x32_bf16 v[108:111], v[152:155], v[192:195], v[108:111]
	v_mfma_f32_16x16x32_bf16 v[104:107], v[160:163], v[192:195], v[104:107]
	v_mfma_f32_16x16x32_bf16 v[92:95], v[152:155], v[200:203], v[92:95]
	v_mfma_f32_16x16x32_bf16 v[88:91], v[160:163], v[200:203], v[88:91]
	v_mfma_f32_16x16x32_bf16 v[76:79], v[152:155], v[208:211], v[76:79]
	v_mfma_f32_16x16x32_bf16 v[72:75], v[160:163], v[208:211], v[72:75]
	v_mfma_f32_16x16x32_bf16 v[124:127], v[156:159], v[188:191], v[124:127]
	v_mfma_f32_16x16x32_bf16 v[120:123], v[164:167], v[188:191], v[120:123]
	v_mfma_f32_16x16x32_bf16 v[108:111], v[156:159], v[196:199], v[108:111]
	v_mfma_f32_16x16x32_bf16 v[104:107], v[164:167], v[196:199], v[104:107]
	v_mfma_f32_16x16x32_bf16 v[92:95], v[156:159], v[204:207], v[92:95]
	v_mfma_f32_16x16x32_bf16 v[88:91], v[164:167], v[204:207], v[88:91]
	v_mfma_f32_16x16x32_bf16 v[76:79], v[156:159], v[216:219], v[76:79]
	v_mfma_f32_16x16x32_bf16 v[72:75], v[164:167], v[216:219], v[72:75]
	s_setprio 0
	s_setprio 1
	v_mfma_f32_16x16x32_bf16 v[116:119], v[168:171], v[184:187], v[116:119]
	v_mfma_f32_16x16x32_bf16 v[112:115], v[176:179], v[184:187], v[112:115]
	v_mfma_f32_16x16x32_bf16 v[100:103], v[168:171], v[192:195], v[100:103]
	v_mfma_f32_16x16x32_bf16 v[96:99], v[176:179], v[192:195], v[96:99]
	v_mfma_f32_16x16x32_bf16 v[84:87], v[168:171], v[200:203], v[84:87]
	v_mfma_f32_16x16x32_bf16 v[80:83], v[176:179], v[200:203], v[80:83]
	v_mfma_f32_16x16x32_bf16 v[68:71], v[168:171], v[208:211], v[68:71]
	v_mfma_f32_16x16x32_bf16 v[64:67], v[176:179], v[208:211], v[64:67]
	v_mfma_f32_16x16x32_bf16 v[116:119], v[172:175], v[188:191], v[116:119]
	v_mfma_f32_16x16x32_bf16 v[112:115], v[180:183], v[188:191], v[112:115]
	v_mfma_f32_16x16x32_bf16 v[100:103], v[172:175], v[196:199], v[100:103]
	v_mfma_f32_16x16x32_bf16 v[96:99], v[180:183], v[196:199], v[96:99]
	v_mfma_f32_16x16x32_bf16 v[84:87], v[172:175], v[204:207], v[84:87]
	v_mfma_f32_16x16x32_bf16 v[80:83], v[180:183], v[204:207], v[80:83]
	v_mfma_f32_16x16x32_bf16 v[68:71], v[172:175], v[216:219], v[68:71]
	v_mfma_f32_16x16x32_bf16 v[64:67], v[180:183], v[216:219], v[64:67]
	s_setprio 0
	s_barrier
	s_add_i32 s45, s18, s2
	v_lshl_add_u64 v[140:141], s[48:49], 0, v[130:131]
	s_mov_b32 m0, s45
	ds_read_b128 v[184:187], v151 offset:16384
	ds_read_b128 v[188:191], v151 offset:17408
	ds_read_b128 v[192:195], v151 offset:18432
	ds_read_b128 v[196:199], v151 offset:19456
	ds_read_b128 v[200:203], v151 offset:20480
	ds_read_b128 v[204:207], v151 offset:21504
	ds_read_b128 v[208:211], v151 offset:22528
	ds_read_b128 v[216:219], v151 offset:23552
	global_load_lds_dwordx4 v[140:141], off
	s_add_i32 m0, s45, 0x2000
	s_add_u32 s52, s48, 0x40000
	v_lshl_add_u64 v[220:221], s[48:49], 0, v[134:135]
	s_addc_u32 s53, s49, 0
	s_add_i32 s45, s19, s2
	global_load_lds_dwordx4 v[220:221], off
	v_lshl_add_u64 v[222:223], s[52:53], 0, v[130:131]
	s_mov_b32 m0, s45
	v_lshl_add_u64 v[224:225], s[50:51], 0, v[132:133]
	global_load_lds_dwordx4 v[222:223], off
	v_lshl_add_u64 v[222:223], s[52:53], 0, v[134:135]
	s_add_i32 m0, s45, 0x2000
	s_nop 0
	global_load_lds_dwordx4 v[222:223], off
	v_lshl_add_u64 v[222:223], s[50:51], 0, v[128:129]
	s_mov_b32 m0, s3
	s_nop 0
	global_load_lds_dwordx4 v[222:223], off
	s_mov_b32 m0, s8
	s_nop 0
	global_load_lds_dwordx4 v[224:225], off
	s_waitcnt vmcnt(8)
	s_waitcnt lgkmcnt(0)
	s_barrier
; #define STAGE(bufoff, gbase) STAGE_(bufoff, gbase, voffA)
; #define LDA(dst, b, h) do { _Pragma("unroll") for (int m = 0; m < 4; ++m) _Pragma("unroll") for (int k = 0; k < 2; ++k) dst[m][k] = *LDSP(const bf16x8, lds + SA(b, h) + aoff + m * 2048 + k * 1024); } while (0)
; #define LDB(dst, b, h) do { _Pragma("unroll") for (int n = 0; n < 2; ++n) _Pragma("unroll") for (int k = 0; k < 2; ++k) dst[n][k] = *LDSP(const bf16x8, lds + SB(b, h) + boff + n * 2048 + k * 1024); } while (0)
; #define MMA(ai, bj, AT, BT) do { __builtin_amdgcn_s_setprio(1); \
;     _Pragma("unroll") for (int m = 0; m < 4; ++m) _Pragma("unroll") for (int n = 0; n < 2; ++n) _Pragma("unroll") for (int k = 0; k < 2; ++k) \
;       acc[ai][bj][m][n] = __builtin_amdgcn_mfma_f32_16x16x32_bf16(BT[n][k], AT[m][k], acc[ai][bj][m][n], 0, 0, 0); \
;     __builtin_amdgcn_s_setprio(0); } while (0)
; #define WAIT_V(n) asm volatile("s_waitcnt vmcnt(" #n ")" ::: "memory")
; #define WAIT_L(n) asm volatile("s_waitcnt lgkmcnt(" #n ")" ::: "memory")
; #define BAR __builtin_amdgcn_s_barrier()
; #define SCHED __builtin_amdgcn_sched_barrier(0)
; #define WAIT_V(n) asm volatile("s_waitcnt vmcnt(" #n ")" ::: "memory")
; #define BAR do { __builtin_amdgcn_sched_barrier(0); __builtin_amdgcn_s_barrier(); asm volatile("" ::: "memory"); __builtin_amdgcn_sched_barrier(0); } while (0)
; template <bool SP2, bool ALIGN_EPI, bool DUAL, class Epi> DI void gemm_phase2(const bf16_t* A, const bf16_t* Bt, const bf16_t* A2, const bf16_t* Bt2, int M, int N, int K, const Epi& E, lds_t* lds) {
;     ...
;         WAIT_V(8); WAIT_L(0); BAR; MMA(1, 0, At, B0); MMA(1, 1, At, B1); BAR; SCHED;
;         LDB(B0, 1, 0); LDB(B1, 1, 1); SCHED; LDA(At, 1, 0); STAGE(SA(0, 1), a2 + hstep);
;         WAIT_V(8); WAIT_L(0); BAR; MMA(0, 0, At, B0); MMA(0, 1, At, B1); BAR; SCHED;
	s_setprio 1
	s_waitcnt lgkmcnt(0)
	v_mfma_f32_16x16x32_bf16 v[60:63], v[152:155], v[184:187], v[60:63]
	v_mfma_f32_16x16x32_bf16 v[56:59], v[160:163], v[184:187], v[56:59]
	v_mfma_f32_16x16x32_bf16 v[44:47], v[152:155], v[192:195], v[44:47]
	v_mfma_f32_16x16x32_bf16 v[40:43], v[160:163], v[192:195], v[40:43]
	v_mfma_f32_16x16x32_bf16 v[28:31], v[152:155], v[200:203], v[28:31]
	v_mfma_f32_16x16x32_bf16 v[24:27], v[160:163], v[200:203], v[24:27]
	v_mfma_f32_16x16x32_bf16 v[12:15], v[152:155], v[208:211], v[12:15]
	v_mfma_f32_16x16x32_bf16 v[8:11], v[160:163], v[208:211], v[8:11]
	v_mfma_f32_16x16x32_bf16 v[60:63], v[156:159], v[188:191], v[60:63]
	v_mfma_f32_16x16x32_bf16 v[56:59], v[164:167], v[188:191], v[56:59]
	v_mfma_f32_16x16x32_bf16 v[44:47], v[156:159], v[196:199], v[44:47]
	v_mfma_f32_16x16x32_bf16 v[40:43], v[164:167], v[196:199], v[40:43]
	v_mfma_f32_16x16x32_bf16 v[28:31], v[156:159], v[204:207], v[28:31]
	v_mfma_f32_16x16x32_bf16 v[24:27], v[164:167], v[204:207], v[24:27]
	v_mfma_f32_16x16x32_bf16 v[12:15], v[156:159], v[216:219], v[12:15]
	v_mfma_f32_16x16x32_bf16 v[8:11], v[164:167], v[216:219], v[8:11]
	s_setprio 0
	s_setprio 1
	v_mfma_f32_16x16x32_bf16 v[52:55], v[168:171], v[184:187], v[52:55]
	v_mfma_f32_16x16x32_bf16 v[48:51], v[176:179], v[184:187], v[48:51]
	v_mfma_f32_16x16x32_bf16 v[36:39], v[168:171], v[192:195], v[36:39]
	v_mfma_f32_16x16x32_bf16 v[32:35], v[176:179], v[192:195], v[32:35]
	v_mfma_f32_16x16x32_bf16 v[20:23], v[168:171], v[200:203], v[20:23]
	v_mfma_f32_16x16x32_bf16 v[16:19], v[176:179], v[200:203], v[16:19]
	v_mfma_f32_16x16x32_bf16 v[4:7], v[168:171], v[208:211], v[4:7]
	v_mfma_f32_16x16x32_bf16 v[0:3], v[176:179], v[208:211], v[0:3]
	v_mfma_f32_16x16x32_bf16 v[52:55], v[172:175], v[188:191], v[52:55]
	v_mfma_f32_16x16x32_bf16 v[48:51], v[180:183], v[188:191], v[48:51]
	v_mfma_f32_16x16x32_bf16 v[36:39], v[172:175], v[196:199], v[36:39]
	v_mfma_f32_16x16x32_bf16 v[32:35], v[180:183], v[196:199], v[32:35]
	v_mfma_f32_16x16x32_bf16 v[20:23], v[172:175], v[204:207], v[20:23]
	v_mfma_f32_16x16x32_bf16 v[16:19], v[180:183], v[204:207], v[16:19]
	v_mfma_f32_16x16x32_bf16 v[4:7], v[172:175], v[216:219], v[4:7]
	v_mfma_f32_16x16x32_bf16 v[0:3], v[180:183], v[216:219], v[0:3]
	s_setprio 0
	s_barrier
	s_add_i32 s45, 0, 0x18000
	s_add_i32 s52, 0, 0x1c000
	v_add_u32_e32 v164, s45, v143
	v_add_u32_e32 v180, s52, v143
	ds_read_b128 v[152:155], v164
	ds_read_b128 v[156:159], v164 offset:1024
	ds_read_b128 v[160:163], v164 offset:2048
	ds_read_b128 v[164:167], v164 offset:3072
	ds_read_b128 v[168:171], v180
	ds_read_b128 v[172:175], v180 offset:1024
	ds_read_b128 v[176:179], v180 offset:2048
	ds_read_b128 v[180:183], v180 offset:3072
	s_add_u32 s50, s50, 0x100000
	s_addc_u32 s51, s51, 0
	s_mov_b32 m0, s9
	v_lshl_add_u64 v[226:227], s[50:51], 0, v[128:129]
	ds_read_b128 v[184:187], v151 offset:32768
	ds_read_b128 v[188:191], v151 offset:33792
	ds_read_b128 v[192:195], v151 offset:34816
	ds_read_b128 v[196:199], v151 offset:35840
	ds_read_b128 v[200:203], v151 offset:36864
	ds_read_b128 v[204:207], v151 offset:37888
	ds_read_b128 v[208:211], v151 offset:38912
	ds_read_b128 v[216:219], v151 offset:39936
	global_load_lds_dwordx4 v[226:227], off
	v_lshl_add_u64 v[226:227], s[50:51], 0, v[132:133]
	s_mov_b32 m0, s10
	s_nop 0
	global_load_lds_dwordx4 v[226:227], off
	s_waitcnt vmcnt(8)
	s_waitcnt lgkmcnt(0)
	s_barrier
	s_setprio 1
	s_waitcnt lgkmcnt(0)
	v_mfma_f32_16x16x32_bf16 v[124:127], v[152:155], v[184:187], v[124:127]
	v_mfma_f32_16x16x32_bf16 v[120:123], v[160:163], v[184:187], v[120:123]
	v_mfma_f32_16x16x32_bf16 v[108:111], v[152:155], v[192:195], v[108:111]
	v_mfma_f32_16x16x32_bf16 v[104:107], v[160:163], v[192:195], v[104:107]
	v_mfma_f32_16x16x32_bf16 v[92:95], v[152:155], v[200:203], v[92:95]
	v_mfma_f32_16x16x32_bf16 v[88:91], v[160:163], v[200:203], v[88:91]
	v_mfma_f32_16x16x32_bf16 v[76:79], v[152:155], v[208:211], v[76:79]
	v_mfma_f32_16x16x32_bf16 v[72:75], v[160:163], v[208:211], v[72:75]
	v_mfma_f32_16x16x32_bf16 v[124:127], v[156:159], v[188:191], v[124:127]
	v_mfma_f32_16x16x32_bf16 v[120:123], v[164:167], v[188:191], v[120:123]
	v_mfma_f32_16x16x32_bf16 v[108:111], v[156:159], v[196:199], v[108:111]
	v_mfma_f32_16x16x32_bf16 v[104:107], v[164:167], v[196:199], v[104:107]
	v_mfma_f32_16x16x32_bf16 v[92:95], v[156:159], v[204:207], v[92:95]
	v_mfma_f32_16x16x32_bf16 v[88:91], v[164:167], v[204:207], v[88:91]
	v_mfma_f32_16x16x32_bf16 v[76:79], v[156:159], v[216:219], v[76:79]
	v_mfma_f32_16x16x32_bf16 v[72:75], v[164:167], v[216:219], v[72:75]
	s_setprio 0
	s_setprio 1
	v_mfma_f32_16x16x32_bf16 v[116:119], v[168:171], v[184:187], v[116:119]
	v_mfma_f32_16x16x32_bf16 v[112:115], v[176:179], v[184:187], v[112:115]
	v_mfma_f32_16x16x32_bf16 v[100:103], v[168:171], v[192:195], v[100:103]
	v_mfma_f32_16x16x32_bf16 v[96:99], v[176:179], v[192:195], v[96:99]
	v_mfma_f32_16x16x32_bf16 v[84:87], v[168:171], v[200:203], v[84:87]
	v_mfma_f32_16x16x32_bf16 v[80:83], v[176:179], v[200:203], v[80:83]
	v_mfma_f32_16x16x32_bf16 v[68:71], v[168:171], v[208:211], v[68:71]
	v_mfma_f32_16x16x32_bf16 v[64:67], v[176:179], v[208:211], v[64:67]
	v_mfma_f32_16x16x32_bf16 v[116:119], v[172:175], v[188:191], v[116:119]
	v_mfma_f32_16x16x32_bf16 v[112:115], v[180:183], v[188:191], v[112:115]
	v_mfma_f32_16x16x32_bf16 v[100:103], v[172:175], v[196:199], v[100:103]
	v_mfma_f32_16x16x32_bf16 v[96:99], v[180:183], v[196:199], v[96:99]
	v_mfma_f32_16x16x32_bf16 v[84:87], v[172:175], v[204:207], v[84:87]
	v_mfma_f32_16x16x32_bf16 v[80:83], v[180:183], v[204:207], v[80:83]
	v_mfma_f32_16x16x32_bf16 v[68:71], v[172:175], v[216:219], v[68:71]
	v_mfma_f32_16x16x32_bf16 v[64:67], v[180:183], v[216:219], v[64:67]
	s_setprio 0
	s_barrier
; #define STAGE(bufoff, gbase) STAGE_(bufoff, gbase, voffA)
; #define STAGEB(bufoff, gbase) STAGE_(bufoff, gbase, voffB)
; #define LDA(dst, b, h) do { _Pragma("unroll") for (int m = 0; m < 4; ++m) _Pragma("unroll") for (int k = 0; k < 2; ++k) dst[m][k] = *LDSP(const bf16x8, lds + SA(b, h) + aoff + m * 2048 + k * 1024); } while (0)
; #define MMA(ai, bj, AT, BT) do { __builtin_amdgcn_s_setprio(1); \
;     _Pragma("unroll") for (int m = 0; m < 4; ++m) _Pragma("unroll") for (int n = 0; n < 2; ++n) _Pragma("unroll") for (int k = 0; k < 2; ++k) \
;       acc[ai][bj][m][n] = __builtin_amdgcn_mfma_f32_16x16x32_bf16(BT[n][k], AT[m][k], acc[ai][bj][m][n], 0, 0, 0); \
;     __builtin_amdgcn_s_setprio(0); } while (0)
; #define WAIT_V(n) asm volatile("s_waitcnt vmcnt(" #n ")" ::: "memory")
; #define WAIT_L(n) asm volatile("s_waitcnt lgkmcnt(" #n ")" ::: "memory")
; #define BAR __builtin_amdgcn_s_barrier()
; #define SCHED __builtin_amdgcn_sched_barrier(0)
; #define WAIT_V(n) asm volatile("s_waitcnt vmcnt(" #n ")" ::: "memory")
; #define BAR do { __builtin_amdgcn_sched_barrier(0); __builtin_amdgcn_s_barrier(); asm volatile("" ::: "memory"); __builtin_amdgcn_sched_barrier(0); } while (0)
; template <bool SP2, bool ALIGN_EPI, bool DUAL, class Epi> DI void gemm_phase2(const bf16_t* A, const bf16_t* Bt, const bf16_t* A2, const bf16_t* Bt2, int M, int N, int K, const Epi& E, lds_t* lds) {
;     ...
;     for (int t = 0; t < nt; t += 2) {
;       const bool last = (t == nt - 2);
;       const char* a1 = cA + (size_t)(t + 1) * kstep;
;       const char* a2 = last ? nA : cA + (size_t)(t + 2) * kstep; const char* b2 = last ? nB : cB + (size_t)(t + 2) * kstep;
;       const char* a3 = a2 + kstep; const char* b3 = b2 + kstep;
;     ...
;         LDA(At, 1, 1); STAGEB(SB(1, 0), b3); STAGEB(SB(1, 1), b3 + bstep); STAGE(SA(1, 0), a3);
;         WAIT_V(8); WAIT_L(0); BAR; MMA(1, 0, At, B0); MMA(1, 1, At, B1); BAR; SCHED;
	s_add_i32 s45, s45, s2
	v_lshl_add_u64 v[140:141], v[140:141], 0, s[22:23]
	s_mov_b32 m0, s45
	ds_read_b128 v[184:187], v151 offset:49152
	ds_read_b128 v[188:191], v151 offset:50176
	ds_read_b128 v[192:195], v151 offset:51200
	ds_read_b128 v[196:199], v151 offset:52224
	ds_read_b128 v[200:203], v151 offset:53248
	ds_read_b128 v[204:207], v151 offset:54272
	ds_read_b128 v[208:211], v151 offset:55296
	ds_read_b128 v[216:219], v151 offset:56320
	global_load_lds_dwordx4 v[140:141], off
	s_add_i32 m0, s45, 0x2000
	s_add_u32 s48, s48, 0x40080
	v_lshl_add_u64 v[140:141], v[220:221], 0, s[22:23]
	s_addc_u32 s49, s49, 0
	s_add_i32 s45, s52, s2
	global_load_lds_dwordx4 v[140:141], off
	v_lshl_add_u64 v[140:141], s[48:49], 0, v[130:131]
	s_mov_b32 m0, s45
	s_nop 0
	global_load_lds_dwordx4 v[140:141], off
	v_lshl_add_u64 v[140:141], s[48:49], 0, v[134:135]
	s_add_i32 m0, s45, 0x2000
	s_nop 0
	global_load_lds_dwordx4 v[140:141], off
	v_lshl_add_u64 v[140:141], v[222:223], 0, s[22:23]
	s_mov_b32 m0, s14
	s_nop 0
	global_load_lds_dwordx4 v[140:141], off
	v_lshl_add_u64 v[140:141], v[224:225], 0, s[22:23]
	s_mov_b32 m0, s15
	s_nop 0
	global_load_lds_dwordx4 v[140:141], off
	s_waitcnt vmcnt(8)
	s_waitcnt lgkmcnt(0)
	s_barrier
	s_setprio 1
	s_waitcnt lgkmcnt(0)
	v_mfma_f32_16x16x32_bf16 v[60:63], v[152:155], v[184:187], v[60:63]
	v_mfma_f32_16x16x32_bf16 v[56:59], v[160:163], v[184:187], v[56:59]
	v_mfma_f32_16x16x32_bf16 v[44:47], v[152:155], v[192:195], v[44:47]
	v_mfma_f32_16x16x32_bf16 v[40:43], v[160:163], v[192:195], v[40:43]
	v_mfma_f32_16x16x32_bf16 v[28:31], v[152:155], v[200:203], v[28:31]
	v_mfma_f32_16x16x32_bf16 v[24:27], v[160:163], v[200:203], v[24:27]
	v_mfma_f32_16x16x32_bf16 v[12:15], v[152:155], v[208:211], v[12:15]
	v_mfma_f32_16x16x32_bf16 v[8:11], v[160:163], v[208:211], v[8:11]
	v_mfma_f32_16x16x32_bf16 v[60:63], v[156:159], v[188:191], v[60:63]
	v_mfma_f32_16x16x32_bf16 v[56:59], v[164:167], v[188:191], v[56:59]
	v_mfma_f32_16x16x32_bf16 v[44:47], v[156:159], v[196:199], v[44:47]
	v_mfma_f32_16x16x32_bf16 v[40:43], v[164:167], v[196:199], v[40:43]
	v_mfma_f32_16x16x32_bf16 v[28:31], v[156:159], v[204:207], v[28:31]
	v_mfma_f32_16x16x32_bf16 v[24:27], v[164:167], v[204:207], v[24:27]
	v_mfma_f32_16x16x32_bf16 v[12:15], v[156:159], v[216:219], v[12:15]
	v_mfma_f32_16x16x32_bf16 v[8:11], v[164:167], v[216:219], v[8:11]
	s_setprio 0
	s_setprio 1
	v_mfma_f32_16x16x32_bf16 v[52:55], v[168:171], v[184:187], v[52:55]
	v_mfma_f32_16x16x32_bf16 v[48:51], v[176:179], v[184:187], v[48:51]
	v_mfma_f32_16x16x32_bf16 v[36:39], v[168:171], v[192:195], v[36:39]
	v_mfma_f32_16x16x32_bf16 v[32:35], v[176:179], v[192:195], v[32:35]
	v_mfma_f32_16x16x32_bf16 v[20:23], v[168:171], v[200:203], v[20:23]
	v_mfma_f32_16x16x32_bf16 v[16:19], v[176:179], v[200:203], v[16:19]
	v_mfma_f32_16x16x32_bf16 v[4:7], v[168:171], v[208:211], v[4:7]
	v_mfma_f32_16x16x32_bf16 v[0:3], v[176:179], v[208:211], v[0:3]
	v_mfma_f32_16x16x32_bf16 v[52:55], v[172:175], v[188:191], v[52:55]
	v_mfma_f32_16x16x32_bf16 v[48:51], v[180:183], v[188:191], v[48:51]
	v_mfma_f32_16x16x32_bf16 v[36:39], v[172:175], v[196:199], v[36:39]
	v_mfma_f32_16x16x32_bf16 v[32:35], v[180:183], v[196:199], v[32:35]
	v_mfma_f32_16x16x32_bf16 v[20:23], v[172:175], v[204:207], v[20:23]
	v_mfma_f32_16x16x32_bf16 v[16:19], v[180:183], v[204:207], v[16:19]
	v_mfma_f32_16x16x32_bf16 v[4:7], v[172:175], v[216:219], v[4:7]
	v_mfma_f32_16x16x32_bf16 v[0:3], v[180:183], v[216:219], v[0:3]
	s_setprio 0
	s_add_i32 s39, s39, 2
	s_add_u32 s46, s46, 0x100
	s_addc_u32 s47, s47, 0
	s_add_u32 s34, s34, 0x100
	s_addc_u32 s35, s35, 0
	s_cmp_gt_u32 s39, 61
	s_barrier
	s_cbranch_scc0 .LBB0_824
	s_and_b64 vcc, exec, s[28:29]
	s_cbranch_vccz .LBB0_827
	s_barrier

; #define STAGE(bufoff, gbase) STAGE_(bufoff, gbase, voffA)
; #define STAGEB(bufoff, gbase) STAGE_(bufoff, gbase, voffB)
; #define LDA(dst, b, h) do { _Pragma("unroll") for (int m = 0; m < 4; ++m) _Pragma("unroll") for (int k = 0; k < 2; ++k) dst[m][k] = *LDSP(const bf16x8, lds + SA(b, h) + aoff + m * 2048 + k * 1024); } while (0)
; #define LDB(dst, b, h) do { _Pragma("unroll") for (int n = 0; n < 2; ++n) _Pragma("unroll") for (int k = 0; k < 2; ++k) dst[n][k] = *LDSP(const bf16x8, lds + SB(b, h) + boff + n * 2048 + k * 1024); } while (0)
; #define MMA(ai, bj, AT, BT) do { __builtin_amdgcn_s_setprio(1); \
;     _Pragma("unroll") for (int m = 0; m < 4; ++m) _Pragma("unroll") for (int n = 0; n < 2; ++n) _Pragma("unroll") for (int k = 0; k < 2; ++k) \
;       acc[ai][bj][m][n] = __builtin_amdgcn_mfma_f32_16x16x32_bf16(BT[n][k], AT[m][k], acc[ai][bj][m][n], 0, 0, 0); \
;     __builtin_amdgcn_s_setprio(0); } while (0)
; #define WAIT_V(n) asm volatile("s_waitcnt vmcnt(" #n ")" ::: "memory")
; #define WAIT_L(n) asm volatile("s_waitcnt lgkmcnt(" #n ")" ::: "memory")
; #define BAR __builtin_amdgcn_s_barrier()
; #define SCHED __builtin_amdgcn_sched_barrier(0)
; #define WAIT_V(n) asm volatile("s_waitcnt vmcnt(" #n ")" ::: "memory")
; #define BAR do { __builtin_amdgcn_sched_barrier(0); __builtin_amdgcn_s_barrier(); asm volatile("" ::: "memory"); __builtin_amdgcn_sched_barrier(0); } while (0)
; template <bool SP2, bool ALIGN_EPI, bool DUAL, class Epi> DI void gemm_phase2(const bf16_t* A, const bf16_t* Bt, const bf16_t* A2, const bf16_t* Bt2, int M, int N, int K, const Epi& E, lds_t* lds) {
;     ...
;     for (int t = 0; t < nt; t += 2) {
;       const bool last = (t == nt - 2);
;       const char* a1 = cA + (size_t)(t + 1) * kstep;
;       const char* a2 = last ? nA : cA + (size_t)(t + 2) * kstep; const char* b2 = last ? nB : cB + (size_t)(t + 2) * kstep;
;       const char* a3 = a2 + kstep; const char* b3 = b2 + kstep;
;       if constexpr (SP2) {
;         LDB(B0, 0, 0); LDB(B1, 0, 1); SCHED; LDA(At, 0, 0); STAGE(SA(1, 1), a1 + hstep);
;         WAIT_V(8); WAIT_L(0); BAR; MMA(0, 0, At, B0); MMA(0, 1, At, B1); BAR; SCHED;
;         LDA(At, 0, 1); STAGEB(SB(0, 0), b2); STAGEB(SB(0, 1), b2 + bstep); STAGE(SA(0, 0), a2);
;         WAIT_V(8); WAIT_L(0); BAR; MMA(1, 0, At, B0); MMA(1, 1, At, B1); BAR; SCHED;
.LBB0_900:
	ds_read_b128 v[140:143], v160
	ds_read_b128 v[144:147], v160 offset:1024
	ds_read_b128 v[148:151], v160 offset:2048
	ds_read_b128 v[152:155], v160 offset:3072
	ds_read_b128 v[164:167], v161
	ds_read_b128 v[168:171], v161 offset:1024
	ds_read_b128 v[172:175], v161 offset:2048
	ds_read_b128 v[176:179], v161 offset:3072
	s_add_u32 s27, s42, 0xfff00080
	s_addc_u32 s41, s43, -1
	s_cmp_eq_u32 s21, 60
	s_cselect_b32 s47, s0, s41
	s_cselect_b32 s46, s1, s27
	s_cselect_b32 s45, s2, s15
	s_cselect_b32 s44, s3, s14
	v_lshl_add_u64 v[216:217], s[42:43], 0, v[136:137]
	s_add_i32 m0, s11, 0xc000
	ds_read_b128 v[180:183], v162
	ds_read_b128 v[184:187], v162 offset:1024
	ds_read_b128 v[188:191], v162 offset:2048
	ds_read_b128 v[192:195], v162 offset:3072
	ds_read_b128 v[196:199], v162 offset:4096
	ds_read_b128 v[200:203], v162 offset:5120
	ds_read_b128 v[204:207], v162 offset:6144
	ds_read_b128 v[208:211], v162 offset:7168
	global_load_lds_dwordx4 v[216:217], off
	v_lshl_add_u64 v[216:217], s[42:43], 0, v[138:139]
	s_add_i32 m0, s11, 0xe000
	s_nop 0
	global_load_lds_dwordx4 v[216:217], off
	s_waitcnt vmcnt(8)
	s_waitcnt lgkmcnt(0)
	s_barrier
	s_setprio 1
	s_waitcnt lgkmcnt(0)
	v_mfma_f32_16x16x32_bf16 v[124:127], v[140:143], v[180:183], v[124:127]
	v_mfma_f32_16x16x32_bf16 v[120:123], v[148:151], v[180:183], v[120:123]
	v_mfma_f32_16x16x32_bf16 v[108:111], v[140:143], v[188:191], v[108:111]
	v_mfma_f32_16x16x32_bf16 v[104:107], v[148:151], v[188:191], v[104:107]
	v_mfma_f32_16x16x32_bf16 v[92:95], v[140:143], v[196:199], v[92:95]
	v_mfma_f32_16x16x32_bf16 v[88:91], v[148:151], v[196:199], v[88:91]
	v_mfma_f32_16x16x32_bf16 v[76:79], v[140:143], v[204:207], v[76:79]
	v_mfma_f32_16x16x32_bf16 v[72:75], v[148:151], v[204:207], v[72:75]
	v_mfma_f32_16x16x32_bf16 v[124:127], v[144:147], v[184:187], v[124:127]
	v_mfma_f32_16x16x32_bf16 v[120:123], v[152:155], v[184:187], v[120:123]
	v_mfma_f32_16x16x32_bf16 v[108:111], v[144:147], v[192:195], v[108:111]
	v_mfma_f32_16x16x32_bf16 v[104:107], v[152:155], v[192:195], v[104:107]
	v_mfma_f32_16x16x32_bf16 v[92:95], v[144:147], v[200:203], v[92:95]
	v_mfma_f32_16x16x32_bf16 v[88:91], v[152:155], v[200:203], v[88:91]
	v_mfma_f32_16x16x32_bf16 v[76:79], v[144:147], v[208:211], v[76:79]
	v_mfma_f32_16x16x32_bf16 v[72:75], v[152:155], v[208:211], v[72:75]
	s_setprio 0
	s_setprio 1
	v_mfma_f32_16x16x32_bf16 v[116:119], v[164:167], v[180:183], v[116:119]
	v_mfma_f32_16x16x32_bf16 v[112:115], v[172:175], v[180:183], v[112:115]
	v_mfma_f32_16x16x32_bf16 v[100:103], v[164:167], v[188:191], v[100:103]
	v_mfma_f32_16x16x32_bf16 v[96:99], v[172:175], v[188:191], v[96:99]
	v_mfma_f32_16x16x32_bf16 v[84:87], v[164:167], v[196:199], v[84:87]
	v_mfma_f32_16x16x32_bf16 v[80:83], v[172:175], v[196:199], v[80:83]
	v_mfma_f32_16x16x32_bf16 v[68:71], v[164:167], v[204:207], v[68:71]
	v_mfma_f32_16x16x32_bf16 v[64:67], v[172:175], v[204:207], v[64:67]
	v_mfma_f32_16x16x32_bf16 v[116:119], v[168:171], v[184:187], v[116:119]
	v_mfma_f32_16x16x32_bf16 v[112:115], v[176:179], v[184:187], v[112:115]
	v_mfma_f32_16x16x32_bf16 v[100:103], v[168:171], v[192:195], v[100:103]
	v_mfma_f32_16x16x32_bf16 v[96:99], v[176:179], v[192:195], v[96:99]
	v_mfma_f32_16x16x32_bf16 v[84:87], v[168:171], v[200:203], v[84:87]
	v_mfma_f32_16x16x32_bf16 v[80:83], v[176:179], v[200:203], v[80:83]
	v_mfma_f32_16x16x32_bf16 v[68:71], v[168:171], v[208:211], v[68:71]
	v_mfma_f32_16x16x32_bf16 v[64:67], v[176:179], v[208:211], v[64:67]
	s_setprio 0
	s_barrier
	s_add_i32 s27, s49, s10
	v_lshl_add_u64 v[216:217], s[44:45], 0, v[130:131]
	s_mov_b32 m0, s27
	ds_read_b128 v[180:183], v162 offset:16384
	ds_read_b128 v[184:187], v162 offset:17408
	ds_read_b128 v[188:191], v162 offset:18432
	ds_read_b128 v[192:195], v162 offset:19456
	ds_read_b128 v[196:199], v162 offset:20480
	ds_read_b128 v[200:203], v162 offset:21504
	ds_read_b128 v[204:207], v162 offset:22528
	ds_read_b128 v[208:211], v162 offset:23552
	global_load_lds_dwordx4 v[216:217], off
	s_add_i32 m0, s27, 0x2000
	s_add_u32 s54, s44, 0x40000
	v_lshl_add_u64 v[218:219], s[44:45], 0, v[134:135]
	s_addc_u32 s55, s45, 0
	s_add_i32 s27, s50, s10
	global_load_lds_dwordx4 v[218:219], off
	v_lshl_add_u64 v[220:221], s[54:55], 0, v[130:131]
	s_mov_b32 m0, s27
	v_lshl_add_u64 v[222:223], s[46:47], 0, v[132:133]
	global_load_lds_dwordx4 v[220:221], off
	v_lshl_add_u64 v[220:221], s[54:55], 0, v[134:135]
	s_add_i32 m0, s27, 0x2000
	s_nop 0
	global_load_lds_dwordx4 v[220:221], off
	v_lshl_add_u64 v[220:221], s[46:47], 0, v[128:129]
	s_mov_b32 m0, s11
	s_nop 0
	global_load_lds_dwordx4 v[220:221], off
	s_mov_b32 m0, s18
	s_nop 0
	global_load_lds_dwordx4 v[222:223], off
	s_waitcnt vmcnt(8)
	s_waitcnt lgkmcnt(0)
	s_barrier
; #define STAGE(bufoff, gbase) STAGE_(bufoff, gbase, voffA)
; #define LDA(dst, b, h) do { _Pragma("unroll") for (int m = 0; m < 4; ++m) _Pragma("unroll") for (int k = 0; k < 2; ++k) dst[m][k] = *LDSP(const bf16x8, lds + SA(b, h) + aoff + m * 2048 + k * 1024); } while (0)
; #define LDB(dst, b, h) do { _Pragma("unroll") for (int n = 0; n < 2; ++n) _Pragma("unroll") for (int k = 0; k < 2; ++k) dst[n][k] = *LDSP(const bf16x8, lds + SB(b, h) + boff + n * 2048 + k * 1024); } while (0)
; #define MMA(ai, bj, AT, BT) do { __builtin_amdgcn_s_setprio(1); \
;     _Pragma("unroll") for (int m = 0; m < 4; ++m) _Pragma("unroll") for (int n = 0; n < 2; ++n) _Pragma("unroll") for (int k = 0; k < 2; ++k) \
;       acc[ai][bj][m][n] = __builtin_amdgcn_mfma_f32_16x16x32_bf16(BT[n][k], AT[m][k], acc[ai][bj][m][n], 0, 0, 0); \
;     __builtin_amdgcn_s_setprio(0); } while (0)
; #define WAIT_V(n) asm volatile("s_waitcnt vmcnt(" #n ")" ::: "memory")
; #define WAIT_L(n) asm volatile("s_waitcnt lgkmcnt(" #n ")" ::: "memory")
; #define BAR __builtin_amdgcn_s_barrier()
; #define SCHED __builtin_amdgcn_sched_barrier(0)
; #define WAIT_V(n) asm volatile("s_waitcnt vmcnt(" #n ")" ::: "memory")
; #define BAR do { __builtin_amdgcn_sched_barrier(0); __builtin_amdgcn_s_barrier(); asm volatile("" ::: "memory"); __builtin_amdgcn_sched_barrier(0); } while (0)
; template <bool SP2, bool ALIGN_EPI, bool DUAL, class Epi> DI void gemm_phase2(const bf16_t* A, const bf16_t* Bt, const bf16_t* A2, const bf16_t* Bt2, int M, int N, int K, const Epi& E, lds_t* lds) {
;     ...
;         WAIT_V(8); WAIT_L(0); BAR; MMA(1, 0, At, B0); MMA(1, 1, At, B1); BAR; SCHED;
;         LDB(B0, 1, 0); LDB(B1, 1, 1); SCHED; LDA(At, 1, 0); STAGE(SA(0, 1), a2 + hstep);
;         WAIT_V(8); WAIT_L(0); BAR; MMA(0, 0, At, B0); MMA(0, 1, At, B1); BAR; SCHED;
	s_setprio 1
	s_waitcnt lgkmcnt(0)
	v_mfma_f32_16x16x32_bf16 v[60:63], v[140:143], v[180:183], v[60:63]
	v_mfma_f32_16x16x32_bf16 v[56:59], v[148:151], v[180:183], v[56:59]
	v_mfma_f32_16x16x32_bf16 v[44:47], v[140:143], v[188:191], v[44:47]
	v_mfma_f32_16x16x32_bf16 v[40:43], v[148:151], v[188:191], v[40:43]
	v_mfma_f32_16x16x32_bf16 v[28:31], v[140:143], v[196:199], v[28:31]
	v_mfma_f32_16x16x32_bf16 v[24:27], v[148:151], v[196:199], v[24:27]
	v_mfma_f32_16x16x32_bf16 v[12:15], v[140:143], v[204:207], v[12:15]
	v_mfma_f32_16x16x32_bf16 v[8:11], v[148:151], v[204:207], v[8:11]
	v_mfma_f32_16x16x32_bf16 v[60:63], v[144:147], v[184:187], v[60:63]
	v_mfma_f32_16x16x32_bf16 v[56:59], v[152:155], v[184:187], v[56:59]
	v_mfma_f32_16x16x32_bf16 v[44:47], v[144:147], v[192:195], v[44:47]
	v_mfma_f32_16x16x32_bf16 v[40:43], v[152:155], v[192:195], v[40:43]
	v_mfma_f32_16x16x32_bf16 v[28:31], v[144:147], v[200:203], v[28:31]
	v_mfma_f32_16x16x32_bf16 v[24:27], v[152:155], v[200:203], v[24:27]
	v_mfma_f32_16x16x32_bf16 v[12:15], v[144:147], v[208:211], v[12:15]
	v_mfma_f32_16x16x32_bf16 v[8:11], v[152:155], v[208:211], v[8:11]
	s_setprio 0
	s_setprio 1
	v_mfma_f32_16x16x32_bf16 v[52:55], v[164:167], v[180:183], v[52:55]
	v_mfma_f32_16x16x32_bf16 v[48:51], v[172:175], v[180:183], v[48:51]
	v_mfma_f32_16x16x32_bf16 v[36:39], v[164:167], v[188:191], v[36:39]
	v_mfma_f32_16x16x32_bf16 v[32:35], v[172:175], v[188:191], v[32:35]
	v_mfma_f32_16x16x32_bf16 v[20:23], v[164:167], v[196:199], v[20:23]
	v_mfma_f32_16x16x32_bf16 v[16:19], v[172:175], v[196:199], v[16:19]
	v_mfma_f32_16x16x32_bf16 v[4:7], v[164:167], v[204:207], v[4:7]
	v_mfma_f32_16x16x32_bf16 v[0:3], v[172:175], v[204:207], v[0:3]
	v_mfma_f32_16x16x32_bf16 v[52:55], v[168:171], v[184:187], v[52:55]
	v_mfma_f32_16x16x32_bf16 v[48:51], v[176:179], v[184:187], v[48:51]
	v_mfma_f32_16x16x32_bf16 v[36:39], v[168:171], v[192:195], v[36:39]
	v_mfma_f32_16x16x32_bf16 v[32:35], v[176:179], v[192:195], v[32:35]
	v_mfma_f32_16x16x32_bf16 v[20:23], v[168:171], v[200:203], v[20:23]
	v_mfma_f32_16x16x32_bf16 v[16:19], v[176:179], v[200:203], v[16:19]
	v_mfma_f32_16x16x32_bf16 v[4:7], v[168:171], v[208:211], v[4:7]
	v_mfma_f32_16x16x32_bf16 v[0:3], v[176:179], v[208:211], v[0:3]
	s_setprio 0
	s_barrier
	s_add_i32 s27, 0, 0x18000
	s_add_i32 s41, 0, 0x1c000
	v_add_u32_e32 v152, s27, v157
	v_add_u32_e32 v176, s41, v157
	ds_read_b128 v[140:143], v152
	ds_read_b128 v[144:147], v152 offset:1024
	ds_read_b128 v[148:151], v152 offset:2048
	ds_read_b128 v[152:155], v152 offset:3072
	ds_read_b128 v[164:167], v176
	ds_read_b128 v[168:171], v176 offset:1024
	ds_read_b128 v[172:175], v176 offset:2048
	ds_read_b128 v[176:179], v176 offset:3072
	s_add_u32 s46, s46, 0x100000
	s_addc_u32 s47, s47, 0
	s_mov_b32 m0, s19
	v_lshl_add_u64 v[224:225], s[46:47], 0, v[128:129]
	ds_read_b128 v[180:183], v162 offset:32768
	ds_read_b128 v[184:187], v162 offset:33792
	ds_read_b128 v[188:191], v162 offset:34816
	ds_read_b128 v[192:195], v162 offset:35840
	ds_read_b128 v[196:199], v162 offset:36864
	ds_read_b128 v[200:203], v162 offset:37888
	ds_read_b128 v[204:207], v162 offset:38912
	ds_read_b128 v[208:211], v162 offset:39936
	global_load_lds_dwordx4 v[224:225], off
	v_lshl_add_u64 v[224:225], s[46:47], 0, v[132:133]
	s_mov_b32 m0, s33
	s_nop 0
	global_load_lds_dwordx4 v[224:225], off
	s_waitcnt vmcnt(8)
	s_waitcnt lgkmcnt(0)
	s_barrier
	s_setprio 1
	s_waitcnt lgkmcnt(0)
	v_mfma_f32_16x16x32_bf16 v[124:127], v[140:143], v[180:183], v[124:127]
	v_mfma_f32_16x16x32_bf16 v[120:123], v[148:151], v[180:183], v[120:123]
	v_mfma_f32_16x16x32_bf16 v[108:111], v[140:143], v[188:191], v[108:111]
	v_mfma_f32_16x16x32_bf16 v[104:107], v[148:151], v[188:191], v[104:107]
	v_mfma_f32_16x16x32_bf16 v[92:95], v[140:143], v[196:199], v[92:95]
	v_mfma_f32_16x16x32_bf16 v[88:91], v[148:151], v[196:199], v[88:91]
	v_mfma_f32_16x16x32_bf16 v[76:79], v[140:143], v[204:207], v[76:79]
	v_mfma_f32_16x16x32_bf16 v[72:75], v[148:151], v[204:207], v[72:75]
	v_mfma_f32_16x16x32_bf16 v[124:127], v[144:147], v[184:187], v[124:127]
	v_mfma_f32_16x16x32_bf16 v[120:123], v[152:155], v[184:187], v[120:123]
	v_mfma_f32_16x16x32_bf16 v[108:111], v[144:147], v[192:195], v[108:111]
	v_mfma_f32_16x16x32_bf16 v[104:107], v[152:155], v[192:195], v[104:107]
	v_mfma_f32_16x16x32_bf16 v[92:95], v[144:147], v[200:203], v[92:95]
	v_mfma_f32_16x16x32_bf16 v[88:91], v[152:155], v[200:203], v[88:91]
	v_mfma_f32_16x16x32_bf16 v[76:79], v[144:147], v[208:211], v[76:79]
	v_mfma_f32_16x16x32_bf16 v[72:75], v[152:155], v[208:211], v[72:75]
	s_setprio 0
	s_setprio 1
	v_mfma_f32_16x16x32_bf16 v[116:119], v[164:167], v[180:183], v[116:119]
	v_mfma_f32_16x16x32_bf16 v[112:115], v[172:175], v[180:183], v[112:115]
	v_mfma_f32_16x16x32_bf16 v[100:103], v[164:167], v[188:191], v[100:103]
	v_mfma_f32_16x16x32_bf16 v[96:99], v[172:175], v[188:191], v[96:99]
	v_mfma_f32_16x16x32_bf16 v[84:87], v[164:167], v[196:199], v[84:87]
	v_mfma_f32_16x16x32_bf16 v[80:83], v[172:175], v[196:199], v[80:83]
	v_mfma_f32_16x16x32_bf16 v[68:71], v[164:167], v[204:207], v[68:71]
	v_mfma_f32_16x16x32_bf16 v[64:67], v[172:175], v[204:207], v[64:67]
	v_mfma_f32_16x16x32_bf16 v[116:119], v[168:171], v[184:187], v[116:119]
	v_mfma_f32_16x16x32_bf16 v[112:115], v[176:179], v[184:187], v[112:115]
	v_mfma_f32_16x16x32_bf16 v[100:103], v[168:171], v[192:195], v[100:103]
	v_mfma_f32_16x16x32_bf16 v[96:99], v[176:179], v[192:195], v[96:99]
	v_mfma_f32_16x16x32_bf16 v[84:87], v[168:171], v[200:203], v[84:87]
	v_mfma_f32_16x16x32_bf16 v[80:83], v[176:179], v[200:203], v[80:83]
	v_mfma_f32_16x16x32_bf16 v[68:71], v[168:171], v[208:211], v[68:71]
	v_mfma_f32_16x16x32_bf16 v[64:67], v[176:179], v[208:211], v[64:67]
	s_setprio 0
	s_barrier
; #define STAGE(bufoff, gbase) STAGE_(bufoff, gbase, voffA)
; #define STAGEB(bufoff, gbase) STAGE_(bufoff, gbase, voffB)
; #define LDA(dst, b, h) do { _Pragma("unroll") for (int m = 0; m < 4; ++m) _Pragma("unroll") for (int k = 0; k < 2; ++k) dst[m][k] = *LDSP(const bf16x8, lds + SA(b, h) + aoff + m * 2048 + k * 1024); } while (0)
; #define MMA(ai, bj, AT, BT) do { __builtin_amdgcn_s_setprio(1); \
;     _Pragma("unroll") for (int m = 0; m < 4; ++m) _Pragma("unroll") for (int n = 0; n < 2; ++n) _Pragma("unroll") for (int k = 0; k < 2; ++k) \
;       acc[ai][bj][m][n] = __builtin_amdgcn_mfma_f32_16x16x32_bf16(BT[n][k], AT[m][k], acc[ai][bj][m][n], 0, 0, 0); \
;     __builtin_amdgcn_s_setprio(0); } while (0)
; #define WAIT_V(n) asm volatile("s_waitcnt vmcnt(" #n ")" ::: "memory")
; #define WAIT_L(n) asm volatile("s_waitcnt lgkmcnt(" #n ")" ::: "memory")
; #define BAR __builtin_amdgcn_s_barrier()
; #define SCHED __builtin_amdgcn_sched_barrier(0)
; #define WAIT_V(n) asm volatile("s_waitcnt vmcnt(" #n ")" ::: "memory")
; #define BAR do { __builtin_amdgcn_sched_barrier(0); __builtin_amdgcn_s_barrier(); asm volatile("" ::: "memory"); __builtin_amdgcn_sched_barrier(0); } while (0)
; template <bool SP2, bool ALIGN_EPI, bool DUAL, class Epi> DI void gemm_phase2(const bf16_t* A, const bf16_t* Bt, const bf16_t* A2, const bf16_t* Bt2, int M, int N, int K, const Epi& E, lds_t* lds) {
;     ...
;     for (int t = 0; t < nt; t += 2) {
;       const bool last = (t == nt - 2);
;       const char* a1 = cA + (size_t)(t + 1) * kstep;
;       const char* a2 = last ? nA : cA + (size_t)(t + 2) * kstep; const char* b2 = last ? nB : cB + (size_t)(t + 2) * kstep;
;       const char* a3 = a2 + kstep; const char* b3 = b2 + kstep;
;     ...
;         LDA(At, 1, 1); STAGEB(SB(1, 0), b3); STAGEB(SB(1, 1), b3 + bstep); STAGE(SA(1, 0), a3);
;         WAIT_V(8); WAIT_L(0); BAR; MMA(1, 0, At, B0); MMA(1, 1, At, B1); BAR; SCHED;
	s_add_i32 s27, s27, s10
	v_lshl_add_u64 v[216:217], v[216:217], 0, s[8:9]
	s_mov_b32 m0, s27
	ds_read_b128 v[180:183], v162 offset:49152
	ds_read_b128 v[184:187], v162 offset:50176
	ds_read_b128 v[188:191], v162 offset:51200
	ds_read_b128 v[192:195], v162 offset:52224
	ds_read_b128 v[196:199], v162 offset:53248
	ds_read_b128 v[200:203], v162 offset:54272
	ds_read_b128 v[204:207], v162 offset:55296
	ds_read_b128 v[208:211], v162 offset:56320
	global_load_lds_dwordx4 v[216:217], off
	s_add_i32 m0, s27, 0x2000
	s_add_u32 s44, s44, 0x40080
	v_lshl_add_u64 v[216:217], v[218:219], 0, s[8:9]
	s_addc_u32 s45, s45, 0
	s_add_i32 s27, s41, s10
	global_load_lds_dwordx4 v[216:217], off
	v_lshl_add_u64 v[216:217], s[44:45], 0, v[130:131]
	s_mov_b32 m0, s27
	s_nop 0
	global_load_lds_dwordx4 v[216:217], off
	v_lshl_add_u64 v[216:217], s[44:45], 0, v[134:135]
	s_add_i32 m0, s27, 0x2000
	s_nop 0
	global_load_lds_dwordx4 v[216:217], off
	v_lshl_add_u64 v[216:217], v[220:221], 0, s[8:9]
	s_mov_b32 m0, s39
	s_nop 0
	global_load_lds_dwordx4 v[216:217], off
	v_lshl_add_u64 v[216:217], v[222:223], 0, s[8:9]
	s_mov_b32 m0, s48
	s_nop 0
	global_load_lds_dwordx4 v[216:217], off
	s_waitcnt vmcnt(8)
	s_waitcnt lgkmcnt(0)
	s_barrier
	s_setprio 1
	s_waitcnt lgkmcnt(0)
	v_mfma_f32_16x16x32_bf16 v[60:63], v[140:143], v[180:183], v[60:63]
	v_mfma_f32_16x16x32_bf16 v[56:59], v[148:151], v[180:183], v[56:59]
	v_mfma_f32_16x16x32_bf16 v[44:47], v[140:143], v[188:191], v[44:47]
	v_mfma_f32_16x16x32_bf16 v[40:43], v[148:151], v[188:191], v[40:43]
	v_mfma_f32_16x16x32_bf16 v[28:31], v[140:143], v[196:199], v[28:31]
	v_mfma_f32_16x16x32_bf16 v[24:27], v[148:151], v[196:199], v[24:27]
	v_mfma_f32_16x16x32_bf16 v[12:15], v[140:143], v[204:207], v[12:15]
	v_mfma_f32_16x16x32_bf16 v[8:11], v[148:151], v[204:207], v[8:11]
	v_mfma_f32_16x16x32_bf16 v[60:63], v[144:147], v[184:187], v[60:63]
	v_mfma_f32_16x16x32_bf16 v[56:59], v[152:155], v[184:187], v[56:59]
	v_mfma_f32_16x16x32_bf16 v[44:47], v[144:147], v[192:195], v[44:47]
	v_mfma_f32_16x16x32_bf16 v[40:43], v[152:155], v[192:195], v[40:43]
	v_mfma_f32_16x16x32_bf16 v[28:31], v[144:147], v[200:203], v[28:31]
	v_mfma_f32_16x16x32_bf16 v[24:27], v[152:155], v[200:203], v[24:27]
	v_mfma_f32_16x16x32_bf16 v[12:15], v[144:147], v[208:211], v[12:15]
	v_mfma_f32_16x16x32_bf16 v[8:11], v[152:155], v[208:211], v[8:11]
	s_setprio 0
	s_setprio 1
	v_mfma_f32_16x16x32_bf16 v[52:55], v[164:167], v[180:183], v[52:55]
	v_mfma_f32_16x16x32_bf16 v[48:51], v[172:175], v[180:183], v[48:51]
	v_mfma_f32_16x16x32_bf16 v[36:39], v[164:167], v[188:191], v[36:39]
	v_mfma_f32_16x16x32_bf16 v[32:35], v[172:175], v[188:191], v[32:35]
	v_mfma_f32_16x16x32_bf16 v[20:23], v[164:167], v[196:199], v[20:23]
	v_mfma_f32_16x16x32_bf16 v[16:19], v[172:175], v[196:199], v[16:19]
	v_mfma_f32_16x16x32_bf16 v[4:7], v[164:167], v[204:207], v[4:7]
	v_mfma_f32_16x16x32_bf16 v[0:3], v[172:175], v[204:207], v[0:3]
	v_mfma_f32_16x16x32_bf16 v[52:55], v[168:171], v[184:187], v[52:55]
	v_mfma_f32_16x16x32_bf16 v[48:51], v[176:179], v[184:187], v[48:51]
	v_mfma_f32_16x16x32_bf16 v[36:39], v[168:171], v[192:195], v[36:39]
	v_mfma_f32_16x16x32_bf16 v[32:35], v[176:179], v[192:195], v[32:35]
	v_mfma_f32_16x16x32_bf16 v[20:23], v[168:171], v[200:203], v[20:23]
	v_mfma_f32_16x16x32_bf16 v[16:19], v[176:179], v[200:203], v[16:19]
	v_mfma_f32_16x16x32_bf16 v[4:7], v[168:171], v[208:211], v[4:7]
	v_mfma_f32_16x16x32_bf16 v[0:3], v[176:179], v[208:211], v[0:3]
	s_setprio 0
	s_add_i32 s21, s21, 2
	s_add_u32 s42, s42, 0x100
	s_addc_u32 s43, s43, 0
	s_add_u32 s14, s14, 0x100
	s_addc_u32 s15, s15, 0
	s_cmp_gt_u32 s21, 61
	s_barrier
	s_cbranch_scc0 .LBB0_900
	s_and_b64 vcc, exec, s[22:23]
	s_cbranch_vccz .LBB0_903
	s_barrier
